# small-projection phase rewritten (K=256 tiles on the full-line DMA core, sigmoid-gated epilogue with early ys loads); tile-end vmcnt(0) drains removed in all hand-written GEMM phases
# speedup vs baseline: 1.2290x; 1.0077x over previous
; __device__ __forceinline__ float sigmoidf_(float v) { return 1.f / (1.f + __expf(-v)); }
; __device__ void phase_inproj(CParams& p, int l, int tm, int tn, char* smem) {
;     ...
;   } else {
;     int T = tn - 6;
;     const int lane = tid & 63, wid = tid >> 6, wr = wid >> 1, wc = wid & 1;
; #pragma unroll
;     for (int mi = 0; mi < 4; mi++)
; #pragma unroll
;       for (int a = 0; a < 2; a++)
; #pragma unroll
;         for (int j = 0; j < 4; j++) {
;           int rl = wr * 64 + mi * 16 + (lane >> 4) * 4 + j;
;           int ch = T * 64 + wc * 32 + a * 16 + (lane & 15);
;           float val = acc[mi][2 * a][j], gt = acc[mi][2 * a + 1][j];
;           p.zv[(size_t)(tbase + rl * tstr) * 256 + ch] = val * sigmoidf_(gt);
;         }
;   }
.Linpj_edone:
	s_nop 1
	v_mov_b32_e32 v0, 0
	v_mov_b32_e32 v1, 0
	v_mov_b32_e32 v2, 0
	v_mov_b32_e32 v3, 0
	v_mov_b32_e32 v4, 0
	v_mov_b32_e32 v5, 0
	v_mov_b32_e32 v6, 0
	v_mov_b32_e32 v7, 0
	v_mov_b32_e32 v8, 0
	v_mov_b32_e32 v9, 0
	v_mov_b32_e32 v10, 0
	v_mov_b32_e32 v11, 0
	v_mov_b32_e32 v12, 0
	v_mov_b32_e32 v13, 0
	v_mov_b32_e32 v14, 0
	v_mov_b32_e32 v15, 0
	v_mov_b32_e32 v16, 0
	v_mov_b32_e32 v17, 0
	v_mov_b32_e32 v18, 0
	v_mov_b32_e32 v19, 0
	v_mov_b32_e32 v20, 0
	v_mov_b32_e32 v21, 0
	v_mov_b32_e32 v22, 0
	v_mov_b32_e32 v23, 0
	v_mov_b32_e32 v24, 0
	v_mov_b32_e32 v25, 0
	v_mov_b32_e32 v26, 0
	v_mov_b32_e32 v27, 0
	v_mov_b32_e32 v28, 0
	v_mov_b32_e32 v29, 0
	v_mov_b32_e32 v30, 0
	v_mov_b32_e32 v31, 0
	v_mov_b32_e32 v32, 0
	v_mov_b32_e32 v33, 0
	v_mov_b32_e32 v34, 0
	v_mov_b32_e32 v35, 0
	v_mov_b32_e32 v36, 0
	v_mov_b32_e32 v37, 0
	v_mov_b32_e32 v38, 0
	v_mov_b32_e32 v39, 0
	v_mov_b32_e32 v40, 0
	v_mov_b32_e32 v41, 0
	v_mov_b32_e32 v42, 0
	v_mov_b32_e32 v43, 0
	v_mov_b32_e32 v44, 0
	v_mov_b32_e32 v45, 0
	v_mov_b32_e32 v46, 0
	v_mov_b32_e32 v47, 0
	v_mov_b32_e32 v48, 0
	v_mov_b32_e32 v49, 0
	v_mov_b32_e32 v50, 0
	v_mov_b32_e32 v51, 0
	v_mov_b32_e32 v52, 0
	v_mov_b32_e32 v53, 0
	v_mov_b32_e32 v54, 0
	v_mov_b32_e32 v55, 0
	v_mov_b32_e32 v56, 0
	v_mov_b32_e32 v57, 0
	v_mov_b32_e32 v58, 0
	v_mov_b32_e32 v59, 0
	v_mov_b32_e32 v60, 0
	v_mov_b32_e32 v61, 0
	v_mov_b32_e32 v62, 0
	v_mov_b32_e32 v63, 0
	s_add_u32 s41, s41, 1
	s_cmp_lt_u32 s41, s52
	s_cbranch_scc1 .Linpj_tile
	s_waitcnt vmcnt(0) lgkmcnt(0)
	s_barrier
	ds_write_b128 v145, v[252:255] offset:40960
	s_waitcnt lgkmcnt(0)
	s_barrier

; __device__ __forceinline__ int otid() { int t = threadIdx.x; asm volatile("" : "+v"(t)); return t; }
; template <int NI> ...
;     ...
;   const int lane = tid & 63, wid = tid >> 6, wr = wid >> 1, wc = wid & 1;
;   const int lrow = tid >> 2, lch = (tid & 3) * 8;
;   const int l15 = lane & 15, lq = lane >> 4;
;   const bf16_t* pa = A + (size_t)lrow * lda + lch;
;   const bf16_t* pb = B + (size_t)lrow * ldb + lch;
;   const size_t a64 = (size_t)64 * lda, b64 = (size_t)64 * ldb;
;   u32x4 a0[2], a1[2], b0[NB], b1[NB];
;   const int nk = K >> 5;
;   const int klast = K - 32;
;   const int wofs = lrow * GROW + lch;
;   const int raofs = (wr * 64 + l15) * GROW + lq * 8;
;   const int rbofs = 128 * GROW + (wc * (16 * NI) + l15) * GROW + lq * 8;
;     ...
;   G_LOAD(a0, b0, 0);
;   G_LOAD(a1, b1, 32);
;   __syncthreads();
;   G_WRITE(a0, b0, 0);
;   __syncthreads();
; __device__ void phase_small(CParams& p, int l, int item, char* smem) {
;   const int tid = otid();
;   bf16_t* sA = (bf16_t*)smem;
;   bf16_t* sB = sA + 128 * LDSS;
;   int which = item / 264, r = item % 264, tm = r >> 1, tn = r & 1;
;   int row0 = tm * 128, col0 = tn * 128;
;   const bf16_t* A = which == 0 ? p.ys : (which == 1 ? p.yfn : p.cv);
;   const bf16_t* B = (which == 0 ? p.WgluT : (which == 1 ? p.WfnT : p.WcvT)) + (size_t)l * 65536;
;   f32x4 acc[4][4];
;   zero_acc<4>(acc);
;   gemm_mainloop<4>(A + (size_t)row0 * 256, 256, B + (size_t)col0 * 256, 256, 256, sA, sB, acc, tid);
.LBB0_819:
	s_or_b64 exec, exec, s[20:21]
	v_readlane_b32 s34, v225, 5
	v_readlane_b32 s6, v225, 58
	v_readlane_b32 s35, v225, 6
	v_readlane_b32 s7, v225, 59
	s_mov_b64 s[20:21], s[34:35]
	s_andn2_b64 vcc, exec, s[6:7]
	s_waitcnt lgkmcnt(0)
	s_barrier
	s_cbranch_vccnz .LBB0_826
	s_mov_b64 exec, -1
	ds_read_b128 v[252:255], v145 offset:40960
	s_load_dwordx2 s[6:7], s[20:21], 0x1d0
	s_load_dwordx2 s[8:9], s[20:21], 0x1b8
	v_readlane_b32 s41, v225, 4
	v_readlane_b32 s40, v224, 26
	v_readfirstlane_b32 s53, v147
	v_and_b32_e32 v166, 63, v147
	s_nop 3
	s_cmp_lt_u32 s41, 280
	s_cselect_b32 s52, 2, 1
	s_lshr_b32 s53, s53, 6
	s_lshl_b32 s44, s53, 12
	v_lshrrev_b32_e32 v167, 3, v166
	s_lshl_b32 s57, s53, 5
	v_add_u32_e32 v167, s57, v167
	v_and_b32_e32 v226, 7, v166
	v_lshrrev_b32_e32 v227, 4, v166
	v_xor_b32_e32 v248, v226, v227
	v_xor_b32_e32 v249, 0, v248
	v_lshlrev_b32_e32 v249, 4, v249
	v_add_u32_e32 v250, 0, v167
	v_lshl_add_u32 v236, v250, 9, v249
	v_xor_b32_e32 v249, 4, v248
	v_lshlrev_b32_e32 v249, 4, v249
	v_add_u32_e32 v250, 8, v167
	v_lshl_add_u32 v237, v250, 9, v249
	v_xor_b32_e32 v249, 0, v248
	v_lshlrev_b32_e32 v249, 4, v249
	v_add_u32_e32 v250, 16, v167
	v_lshl_add_u32 v238, v250, 9, v249
	v_xor_b32_e32 v249, 4, v248
	v_lshlrev_b32_e32 v249, 4, v249
	v_add_u32_e32 v250, 24, v167
	v_lshl_add_u32 v239, v250, 9, v249
	s_and_b32 s58, s53, 1
	s_lshl_b32 s58, s58, 2
	v_and_b32_e32 v248, 1, v227
	v_or_b32_e32 v248, s58, v248
	v_xor_b32_e32 v248, v226, v248
	v_xor_b32_e32 v249, 0, v248
	v_lshlrev_b32_e32 v249, 4, v249
	v_add_u32_e32 v250, 0, v167
	v_lshl_add_u32 v240, v250, 9, v249
	v_xor_b32_e32 v249, 0, v248
	v_lshlrev_b32_e32 v249, 4, v249
	v_add_u32_e32 v250, 8, v167
	v_lshl_add_u32 v241, v250, 9, v249
	v_xor_b32_e32 v249, 2, v248
	v_lshlrev_b32_e32 v249, 4, v249
	v_add_u32_e32 v250, 16, v167
	v_lshl_add_u32 v242, v250, 9, v249
	v_xor_b32_e32 v249, 2, v248
	v_lshlrev_b32_e32 v249, 4, v249
	v_add_u32_e32 v250, 24, v167
	v_lshl_add_u32 v243, v250, 9, v249
	v_and_b32_e32 v167, 15, v166
	v_lshrrev_b32_e32 v227, 4, v166
	s_lshr_b32 s57, s53, 1
	s_and_b32 s58, s53, 1
	s_lshl_b32 s57, s57, 6
	s_lshl_b32 s58, s58, 6
	v_lshrrev_b32_e32 v226, 1, v167
	v_xor_b32_e32 v226, v227, v226
	v_lshlrev_b32_e32 v226, 4, v226
	v_add_u32_e32 v132, s57, v167
	v_lshl_add_u32 v248, v132, 7, v226
	v_xor_b32_e32 v249, 64, v248
	v_lshrrev_b32_e32 v226, 2, v167
	v_lshrrev_b32_e32 v250, 1, v167
	v_and_b32_e32 v250, 1, v250
	v_lshl_or_b32 v250, v226, 1, v250
	v_xor_b32_e32 v250, v227, v250
	v_lshlrev_b32_e32 v250, 4, v250
	v_and_b32_e32 v251, 3, v167
	v_lshl_add_u32 v251, v226, 4, v251
	v_add_u32_e32 v251, s58, v251
	v_lshl_add_u32 v250, v251, 7, v250
	v_xor_b32_e32 v251, 64, v250
	v_lshl_add_u32 v226, v227, 4, s58
	v_lshlrev_b32_e32 v226, 1, v226
	v_lshl_add_u32 v144, v132, 11, v226
	v_lshl_add_u32 v132, v132, 9, v226
	s_mov_b32 s59, 0x0
	s_mov_b32 s62, 0x4000
	s_mov_b32 s63, 0x8000
	s_mov_b32 s92, 0xc000
	s_mov_b32 s93, 0x10000
	s_mov_b32 s45, 0
	s_mov_b32 s99, s41
	s_cmp_ge_u32 s99, 264
	s_cselect_b32 s55, 1, 0
	s_cmp_ge_u32 s99, 528
	s_cselect_b32 s56, 1, 0
	s_add_u32 s55, s55, s56
	s_mul_i32 s56, s55, 264
	s_sub_u32 s56, s99, s56
	s_lshl_b32 s57, s55, 3
	s_add_u32 s58, s57, 0x1b8
	s_load_dwordx2 s[12:13], s[20:21], s58
	s_add_u32 s58, s57, 0x130
	s_load_dwordx2 s[18:19], s[20:21], s58
	s_lshr_b32 s57, s56, 1
	s_lshl_b32 s57, s57, 16
	s_and_b32 s56, s56, 1
	s_lshl_b32 s56, s56, 16
	s_lshl_b32 s58, s40, 17
	s_add_u32 s56, s56, s58
	s_waitcnt lgkmcnt(0)
	s_add_u32 s12, s12, s57
	s_addc_u32 s13, s13, 0
	s_add_u32 s18, s18, s56
	s_addc_u32 s19, s19, 0
	s_barrier
	s_add_u32 s54, s44, s59
	s_add_u32 m0, s54, 0x0
	s_nop 0
	global_load_lds_dwordx4 v236, s[12:13]
	s_add_u32 m0, s54, 0x400
	s_nop 0
	global_load_lds_dwordx4 v237, s[12:13]
	s_add_u32 m0, s54, 0x800
	s_nop 0
	global_load_lds_dwordx4 v238, s[12:13]
	s_add_u32 m0, s54, 0xc00
	s_nop 0
	global_load_lds_dwordx4 v239, s[12:13]
	s_add_u32 s12, s12, 128
	s_addc_u32 s13, s13, 0
	s_add_u32 s54, s44, s62
	s_add_u32 m0, s54, 0x0
	s_nop 0
	global_load_lds_dwordx4 v240, s[18:19]
	s_add_u32 m0, s54, 0x400
	s_nop 0
	global_load_lds_dwordx4 v241, s[18:19]
	s_add_u32 m0, s54, 0x800
	s_nop 0
	global_load_lds_dwordx4 v242, s[18:19]
	s_add_u32 m0, s54, 0xc00
	s_nop 0
	global_load_lds_dwordx4 v243, s[18:19]
	s_add_u32 s18, s18, 128
	s_addc_u32 s19, s19, 0
	s_add_u32 s54, s44, s63
	s_add_u32 m0, s54, 0x0
	s_nop 0
	global_load_lds_dwordx4 v236, s[12:13]
	s_add_u32 m0, s54, 0x400
	s_nop 0
	global_load_lds_dwordx4 v237, s[12:13]
	s_add_u32 m0, s54, 0x800
	s_nop 0
	global_load_lds_dwordx4 v238, s[12:13]
	s_add_u32 m0, s54, 0xc00
	s_nop 0
	global_load_lds_dwordx4 v239, s[12:13]
	s_add_u32 s12, s12, 128
	s_addc_u32 s13, s13, 0
	s_add_u32 s54, s44, s92
	s_add_u32 m0, s54, 0x0
	s_nop 0
	global_load_lds_dwordx4 v240, s[18:19]
	s_add_u32 m0, s54, 0x400
	s_nop 0
	global_load_lds_dwordx4 v241, s[18:19]
	s_add_u32 m0, s54, 0x800
	s_nop 0
	global_load_lds_dwordx4 v242, s[18:19]
	s_add_u32 m0, s54, 0xc00
	s_nop 0
	global_load_lds_dwordx4 v243, s[18:19]
	s_add_u32 s18, s18, 128
	s_addc_u32 s19, s19, 0
	v_mov_b32_e32 v0, 0
	v_mov_b32_e32 v1, 0
	v_mov_b32_e32 v2, 0
	v_mov_b32_e32 v3, 0
	v_mov_b32_e32 v4, 0
	v_mov_b32_e32 v5, 0
	v_mov_b32_e32 v6, 0
	v_mov_b32_e32 v7, 0
	v_mov_b32_e32 v8, 0
	v_mov_b32_e32 v9, 0
	v_mov_b32_e32 v10, 0
	v_mov_b32_e32 v11, 0
	v_mov_b32_e32 v12, 0
	v_mov_b32_e32 v13, 0
	v_mov_b32_e32 v14, 0
	v_mov_b32_e32 v15, 0
	v_mov_b32_e32 v16, 0
	v_mov_b32_e32 v17, 0
	v_mov_b32_e32 v18, 0
	v_mov_b32_e32 v19, 0
	v_mov_b32_e32 v20, 0
	v_mov_b32_e32 v21, 0
	v_mov_b32_e32 v22, 0
	v_mov_b32_e32 v23, 0
	v_mov_b32_e32 v24, 0
	v_mov_b32_e32 v25, 0
	v_mov_b32_e32 v26, 0
	v_mov_b32_e32 v27, 0
	v_mov_b32_e32 v28, 0
	v_mov_b32_e32 v29, 0
	v_mov_b32_e32 v30, 0
	v_mov_b32_e32 v31, 0
	v_mov_b32_e32 v32, 0
	v_mov_b32_e32 v33, 0
	v_mov_b32_e32 v34, 0
	v_mov_b32_e32 v35, 0
	v_mov_b32_e32 v36, 0
	v_mov_b32_e32 v37, 0
	v_mov_b32_e32 v38, 0
	v_mov_b32_e32 v39, 0
	v_mov_b32_e32 v40, 0
	v_mov_b32_e32 v41, 0
	v_mov_b32_e32 v42, 0
	v_mov_b32_e32 v43, 0
	v_mov_b32_e32 v44, 0
	v_mov_b32_e32 v45, 0
	v_mov_b32_e32 v46, 0
	v_mov_b32_e32 v47, 0
	v_mov_b32_e32 v48, 0
	v_mov_b32_e32 v49, 0
	v_mov_b32_e32 v50, 0
	v_mov_b32_e32 v51, 0
	v_mov_b32_e32 v52, 0
	v_mov_b32_e32 v53, 0
	v_mov_b32_e32 v54, 0
	v_mov_b32_e32 v55, 0
	v_mov_b32_e32 v56, 0
	v_mov_b32_e32 v57, 0
	v_mov_b32_e32 v58, 0
	v_mov_b32_e32 v59, 0
	v_mov_b32_e32 v60, 0
	v_mov_b32_e32 v61, 0
	v_mov_b32_e32 v62, 0
	v_mov_b32_e32 v63, 0
	s_waitcnt vmcnt(8)
	s_barrier
	v_add_u32_e32 v128, s59, v248
	v_add_u32_e32 v130, s62, v250
	ds_read_b128 v[168:171], v128 offset:0
	ds_read_b128 v[184:187], v130 offset:0
	ds_read_b128 v[172:175], v128 offset:2048
	ds_read_b128 v[188:191], v130 offset:512
	ds_read_b128 v[176:179], v128 offset:4096
	ds_read_b128 v[192:195], v130 offset:1024
	ds_read_b128 v[180:183], v128 offset:6144
	ds_read_b128 v[196:199], v130 offset:1536
; template <int NI> ...
;     ...
;   for (int kt = 0; kt < nk; kt += 2) {
;     G_LOAD(a0, b0, min((kt + 2) * 32, klast));
;     G_COMPUTE(0);
;     G_WRITE(a1, b1, 1);
;     __syncthreads();
;     G_LOAD(a1, b1, min((kt + 3) * 32, klast));
;     G_COMPUTE(1);
;     G_WRITE(a0, b0, 0);
;     __syncthreads();
;   }
; __device__ void phase_small(CParams& p, int l, int item, char* smem) {
;     ...
;   int which = item / 264, r = item % 264, tm = r >> 1, tn = r & 1;
;   int row0 = tm * 128, col0 = tn * 128;
;   const bf16_t* A = which == 0 ? p.ys : (which == 1 ? p.yfn : p.cv);
;   const bf16_t* B = (which == 0 ? p.WgluT : (which == 1 ? p.WfnT : p.WcvT)) + (size_t)l * 65536;
;   f32x4 acc[4][4];
;   zero_acc<4>(acc);
;   gemm_mainloop<4>(A + (size_t)row0 * 256, 256, B + (size_t)col0 * 256, 256, 256, sA, sB, acc, tid);
.Lsml_tile:
	s_mov_b32 s98, s99
	s_cmp_ge_u32 s98, 264
	s_cselect_b32 s55, 1, 0
	s_cmp_ge_u32 s98, 528
	s_cselect_b32 s56, 1, 0
	s_add_u32 s1, s55, s56
	s_mul_i32 s55, s1, 264
	s_sub_u32 s55, s98, s55
	s_lshr_b32 s57, s55, 1
	s_and_b32 s55, s55, 1
	s_lshl_b32 s55, s55, 8
	s_lshl_b32 s58, s57, 16
	s_add_u32 s58, s58, s55
	s_add_u32 s28, s8, s58
	s_addc_u32 s29, s9, 0
	s_lshl_b32 s58, s57, 18
	s_add_u32 s58, s58, s55
	s_lshl_b32 s55, s1, 9
	s_add_u32 s58, s58, s55
	s_cmp_eq_u32 s1, 2
	s_cselect_b32 s55, 0x200, 0
	s_add_u32 s58, s58, s55
	s_add_u32 s26, s6, s58
	s_addc_u32 s27, s7, 0
	s_cmp_lg_u32 s1, 0
	s_cbranch_scc1 .Lsml_noys
	global_load_dwordx4 v[64:67], v132, s[28:29] offset:0
	global_load_dwordx4 v[68:71], v132, s[28:29] offset:16
	s_add_u32 s28, s28, 0x2000
	s_addc_u32 s29, s29, 0
	global_load_dwordx4 v[72:75], v132, s[28:29] offset:0
	global_load_dwordx4 v[76:79], v132, s[28:29] offset:16
	s_add_u32 s28, s28, 0x2000
	s_addc_u32 s29, s29, 0
	global_load_dwordx4 v[80:83], v132, s[28:29] offset:0
	global_load_dwordx4 v[84:87], v132, s[28:29] offset:16
	s_add_u32 s28, s28, 0x2000
	s_addc_u32 s29, s29, 0
	global_load_dwordx4 v[88:91], v132, s[28:29] offset:0
	global_load_dwordx4 v[92:95], v132, s[28:29] offset:16
.Lsml_noys:
	s_add_u32 s58, s45, 1
	s_sub_u32 s57, s52, 1
	s_min_u32 s58, s58, s57
	s_lshl_b32 s58, s58, 9
	s_add_u32 s99, s41, s58
	s_cmp_ge_u32 s99, 264
	s_cselect_b32 s55, 1, 0
	s_cmp_ge_u32 s99, 528
	s_cselect_b32 s56, 1, 0
	s_add_u32 s55, s55, s56
	s_mul_i32 s56, s55, 264
	s_sub_u32 s56, s99, s56
	s_lshl_b32 s57, s55, 3
	s_add_u32 s58, s57, 0x1b8
	s_load_dwordx2 s[22:23], s[20:21], s58
	s_add_u32 s58, s57, 0x130
	s_load_dwordx2 s[24:25], s[20:21], s58
	s_lshr_b32 s57, s56, 1
	s_lshl_b32 s57, s57, 16
	s_and_b32 s56, s56, 1
	s_lshl_b32 s56, s56, 16
	s_lshl_b32 s58, s40, 17
	s_add_u32 s56, s56, s58
	s_waitcnt lgkmcnt(0)
	s_add_u32 s22, s22, s57
	s_addc_u32 s23, s23, 0
	s_add_u32 s24, s24, s56
	s_addc_u32 s25, s25, 0
	s_mov_b32 s53, 0
.Lsml_pair:
	s_waitcnt lgkmcnt(0)
	s_cmp_eq_u32 s53, 2
	s_cselect_b64 s[12:13], s[22:23], s[12:13]
	s_add_u32 s54, s44, s93
	s_add_u32 m0, s54, 0x0
	s_nop 0
	global_load_lds_dwordx4 v236, s[12:13]
	s_add_u32 m0, s54, 0x400
	s_nop 0
	global_load_lds_dwordx4 v237, s[12:13]
	s_add_u32 m0, s54, 0x800
	s_nop 0
	global_load_lds_dwordx4 v238, s[12:13]
	s_add_u32 m0, s54, 0xc00
	s_nop 0
	global_load_lds_dwordx4 v239, s[12:13]
	s_add_u32 s12, s12, 128
	s_addc_u32 s13, s13, 0
	v_add_u32_e32 v129, s59, v249
	v_add_u32_e32 v131, s62, v251
	v_mfma_f32_16x16x32_bf16 v[0:3], v[184:187], v[168:171], v[0:3]
	ds_read_b128 v[200:203], v129 offset:0
	v_mfma_f32_16x16x32_bf16 v[4:7], v[188:191], v[168:171], v[4:7]
	ds_read_b128 v[216:219], v131 offset:0
	v_mfma_f32_16x16x32_bf16 v[8:11], v[192:195], v[168:171], v[8:11]
	ds_read_b128 v[204:207], v129 offset:2048
	v_mfma_f32_16x16x32_bf16 v[12:15], v[196:199], v[168:171], v[12:15]
	ds_read_b128 v[220:223], v131 offset:512
	v_mfma_f32_16x16x32_bf16 v[16:19], v[184:187], v[172:175], v[16:19]
	ds_read_b128 v[208:211], v129 offset:4096
	v_mfma_f32_16x16x32_bf16 v[20:23], v[188:191], v[172:175], v[20:23]
	ds_read_b128 v[228:231], v131 offset:1024
	v_mfma_f32_16x16x32_bf16 v[24:27], v[192:195], v[172:175], v[24:27]
	ds_read_b128 v[212:215], v129 offset:6144
	v_mfma_f32_16x16x32_bf16 v[28:31], v[196:199], v[172:175], v[28:31]
	ds_read_b128 v[232:235], v131 offset:1536
	v_mfma_f32_16x16x32_bf16 v[32:35], v[184:187], v[176:179], v[32:35]
	v_mfma_f32_16x16x32_bf16 v[36:39], v[188:191], v[176:179], v[36:39]
	v_mfma_f32_16x16x32_bf16 v[40:43], v[192:195], v[176:179], v[40:43]
	v_mfma_f32_16x16x32_bf16 v[44:47], v[196:199], v[176:179], v[44:47]
	v_mfma_f32_16x16x32_bf16 v[48:51], v[184:187], v[180:183], v[48:51]
	v_mfma_f32_16x16x32_bf16 v[52:55], v[188:191], v[180:183], v[52:55]
	v_mfma_f32_16x16x32_bf16 v[56:59], v[192:195], v[180:183], v[56:59]
	v_mfma_f32_16x16x32_bf16 v[60:63], v[196:199], v[180:183], v[60:63]
	s_waitcnt vmcnt(4) lgkmcnt(0)
	s_barrier
	s_cmp_eq_u32 s53, 2
	s_cselect_b64 s[18:19], s[24:25], s[18:19]
	s_add_u32 s54, s44, s59
	s_add_u32 m0, s54, 0x0
	s_nop 0
	global_load_lds_dwordx4 v240, s[18:19]
	s_add_u32 m0, s54, 0x400
	s_nop 0
	global_load_lds_dwordx4 v241, s[18:19]
	s_add_u32 m0, s54, 0x800
	s_nop 0
	global_load_lds_dwordx4 v242, s[18:19]
	s_add_u32 m0, s54, 0xc00
	s_nop 0
	global_load_lds_dwordx4 v243, s[18:19]
	s_add_u32 s18, s18, 128
	s_addc_u32 s19, s19, 0
	v_add_u32_e32 v128, s63, v248
	v_add_u32_e32 v130, s92, v250
	v_mfma_f32_16x16x32_bf16 v[0:3], v[216:219], v[200:203], v[0:3]
	ds_read_b128 v[168:171], v128 offset:0
	v_mfma_f32_16x16x32_bf16 v[4:7], v[220:223], v[200:203], v[4:7]
	ds_read_b128 v[184:187], v130 offset:0
	v_mfma_f32_16x16x32_bf16 v[8:11], v[228:231], v[200:203], v[8:11]
	ds_read_b128 v[172:175], v128 offset:2048
	v_mfma_f32_16x16x32_bf16 v[12:15], v[232:235], v[200:203], v[12:15]
	ds_read_b128 v[188:191], v130 offset:512
	v_mfma_f32_16x16x32_bf16 v[16:19], v[216:219], v[204:207], v[16:19]
	ds_read_b128 v[176:179], v128 offset:4096
	v_mfma_f32_16x16x32_bf16 v[20:23], v[220:223], v[204:207], v[20:23]
	ds_read_b128 v[192:195], v130 offset:1024
	v_mfma_f32_16x16x32_bf16 v[24:27], v[228:231], v[204:207], v[24:27]
	ds_read_b128 v[180:183], v128 offset:6144
	v_mfma_f32_16x16x32_bf16 v[28:31], v[232:235], v[204:207], v[28:31]
	ds_read_b128 v[196:199], v130 offset:1536
	v_mfma_f32_16x16x32_bf16 v[32:35], v[216:219], v[208:211], v[32:35]
	v_mfma_f32_16x16x32_bf16 v[36:39], v[220:223], v[208:211], v[36:39]
	v_mfma_f32_16x16x32_bf16 v[40:43], v[228:231], v[208:211], v[40:43]
	v_mfma_f32_16x16x32_bf16 v[44:47], v[232:235], v[208:211], v[44:47]
	v_mfma_f32_16x16x32_bf16 v[48:51], v[216:219], v[212:215], v[48:51]
	v_mfma_f32_16x16x32_bf16 v[52:55], v[220:223], v[212:215], v[52:55]
	v_mfma_f32_16x16x32_bf16 v[56:59], v[228:231], v[212:215], v[56:59]
	v_mfma_f32_16x16x32_bf16 v[60:63], v[232:235], v[212:215], v[60:63]
	s_mov_b32 s55, s59
	s_mov_b32 s56, s62
	s_mov_b32 s59, s63
	s_mov_b32 s62, s92
	s_mov_b32 s63, s93
	s_mov_b32 s92, s55
	s_mov_b32 s93, s56
	s_add_u32 s53, s53, 1
	s_cmp_lt_u32 s53, 4
	s_cbranch_scc1 .Lsml_pair
; __device__ __forceinline__ float bf2f(bf16_t b) { return __uint_as_float(((unsigned)b) << 16); }
; __device__ __forceinline__ float sigmoidf_(float v) { return 1.f / (1.f + __expf(-v)); }
; __device__ void phase_small(CParams& p, int l, int item, char* smem) {
;     ...
;   if (which == 0) {
;     EPI_LOOP({
;       float y = bf2f(p.ys[(size_t)(row0 + rl) * 256 + col0 + cl]);
;       p.br[(size_t)(row0 + rl) * 1024 + col0 + cl] = f2bf(y * sigmoidf_(acc[mi][ni][j]));
;     })
	s_cmp_lg_u32 s1, 0
	s_cbranch_scc1 .Lsml_eplain
	s_nop 7
	v_mul_f32_e32 v96, 0xbfb8aa3b, v0
	v_mul_f32_e32 v97, 0xbfb8aa3b, v1
	v_mul_f32_e32 v98, 0xbfb8aa3b, v2
	v_mul_f32_e32 v99, 0xbfb8aa3b, v3
	v_mul_f32_e32 v100, 0xbfb8aa3b, v4
	v_mul_f32_e32 v101, 0xbfb8aa3b, v5
	v_mul_f32_e32 v102, 0xbfb8aa3b, v6
	v_mul_f32_e32 v103, 0xbfb8aa3b, v7
	v_mul_f32_e32 v104, 0xbfb8aa3b, v8
	v_mul_f32_e32 v105, 0xbfb8aa3b, v9
	v_mul_f32_e32 v106, 0xbfb8aa3b, v10
	v_mul_f32_e32 v107, 0xbfb8aa3b, v11
	v_mul_f32_e32 v108, 0xbfb8aa3b, v12
	v_mul_f32_e32 v109, 0xbfb8aa3b, v13
	v_mul_f32_e32 v110, 0xbfb8aa3b, v14
	v_mul_f32_e32 v111, 0xbfb8aa3b, v15
	v_exp_f32_e32 v96, v96
	v_exp_f32_e32 v97, v97
	v_exp_f32_e32 v98, v98
	v_exp_f32_e32 v99, v99
	v_exp_f32_e32 v100, v100
	v_exp_f32_e32 v101, v101
	v_exp_f32_e32 v102, v102
	v_exp_f32_e32 v103, v103
	v_exp_f32_e32 v104, v104
	v_exp_f32_e32 v105, v105
	v_exp_f32_e32 v106, v106
	v_exp_f32_e32 v107, v107
	v_exp_f32_e32 v108, v108
	v_exp_f32_e32 v109, v109
	v_exp_f32_e32 v110, v110
	v_exp_f32_e32 v111, v111
	v_add_f32_e32 v96, 1.0, v96
	v_add_f32_e32 v97, 1.0, v97
	v_add_f32_e32 v98, 1.0, v98
	v_add_f32_e32 v99, 1.0, v99
	v_add_f32_e32 v100, 1.0, v100
	v_add_f32_e32 v101, 1.0, v101
	v_add_f32_e32 v102, 1.0, v102
	v_add_f32_e32 v103, 1.0, v103
	v_add_f32_e32 v104, 1.0, v104
	v_add_f32_e32 v105, 1.0, v105
	v_add_f32_e32 v106, 1.0, v106
	v_add_f32_e32 v107, 1.0, v107
	v_add_f32_e32 v108, 1.0, v108
	v_add_f32_e32 v109, 1.0, v109
	v_add_f32_e32 v110, 1.0, v110
	v_add_f32_e32 v111, 1.0, v111
	v_rcp_f32_e32 v96, v96
	v_rcp_f32_e32 v97, v97
	v_rcp_f32_e32 v98, v98
	v_rcp_f32_e32 v99, v99
	v_rcp_f32_e32 v100, v100
	v_rcp_f32_e32 v101, v101
	v_rcp_f32_e32 v102, v102
	v_rcp_f32_e32 v103, v103
	v_rcp_f32_e32 v104, v104
	v_rcp_f32_e32 v105, v105
	v_rcp_f32_e32 v106, v106
	v_rcp_f32_e32 v107, v107
	v_rcp_f32_e32 v108, v108
	v_rcp_f32_e32 v109, v109
	v_rcp_f32_e32 v110, v110
	v_rcp_f32_e32 v111, v111
	s_waitcnt vmcnt(8)
	v_lshlrev_b32_e32 v112, 16, v64
	v_and_b32_e32 v113, 0xffff0000, v64
	v_lshlrev_b32_e32 v114, 16, v65
	v_and_b32_e32 v115, 0xffff0000, v65
	v_lshlrev_b32_e32 v116, 16, v66
	v_and_b32_e32 v117, 0xffff0000, v66
	v_lshlrev_b32_e32 v118, 16, v67
	v_and_b32_e32 v119, 0xffff0000, v67
	v_lshlrev_b32_e32 v120, 16, v68
	v_and_b32_e32 v121, 0xffff0000, v68
	v_lshlrev_b32_e32 v122, 16, v69
	v_and_b32_e32 v123, 0xffff0000, v69
	v_lshlrev_b32_e32 v124, 16, v70
	v_and_b32_e32 v125, 0xffff0000, v70
	v_lshlrev_b32_e32 v126, 16, v71
	v_and_b32_e32 v127, 0xffff0000, v71
	v_mul_f32_e32 v96, v96, v112
	v_mul_f32_e32 v97, v97, v113
	v_mul_f32_e32 v98, v98, v114
	v_mul_f32_e32 v99, v99, v115
	v_mul_f32_e32 v100, v100, v116
	v_mul_f32_e32 v101, v101, v117
	v_mul_f32_e32 v102, v102, v118
	v_mul_f32_e32 v103, v103, v119
	v_mul_f32_e32 v104, v104, v120
	v_mul_f32_e32 v105, v105, v121
	v_mul_f32_e32 v106, v106, v122
	v_mul_f32_e32 v107, v107, v123
	v_mul_f32_e32 v108, v108, v124
	v_mul_f32_e32 v109, v109, v125
	v_mul_f32_e32 v110, v110, v126
	v_mul_f32_e32 v111, v111, v127
	v_cvt_pk_bf16_f32 v200, v96, v97
	v_cvt_pk_bf16_f32 v201, v98, v99
	v_cvt_pk_bf16_f32 v202, v100, v101
	v_cvt_pk_bf16_f32 v203, v102, v103
	v_cvt_pk_bf16_f32 v204, v104, v105
	v_cvt_pk_bf16_f32 v205, v106, v107
	v_cvt_pk_bf16_f32 v206, v108, v109
	v_cvt_pk_bf16_f32 v207, v110, v111
	v_mul_f32_e32 v96, 0xbfb8aa3b, v16
	v_mul_f32_e32 v97, 0xbfb8aa3b, v17
	v_mul_f32_e32 v98, 0xbfb8aa3b, v18
	v_mul_f32_e32 v99, 0xbfb8aa3b, v19
	v_mul_f32_e32 v100, 0xbfb8aa3b, v20
	v_mul_f32_e32 v101, 0xbfb8aa3b, v21
	v_mul_f32_e32 v102, 0xbfb8aa3b, v22
	v_mul_f32_e32 v103, 0xbfb8aa3b, v23
	v_mul_f32_e32 v104, 0xbfb8aa3b, v24
	v_mul_f32_e32 v105, 0xbfb8aa3b, v25
	v_mul_f32_e32 v106, 0xbfb8aa3b, v26
	v_mul_f32_e32 v107, 0xbfb8aa3b, v27
	v_mul_f32_e32 v108, 0xbfb8aa3b, v28
	v_mul_f32_e32 v109, 0xbfb8aa3b, v29
	v_mul_f32_e32 v110, 0xbfb8aa3b, v30
	v_mul_f32_e32 v111, 0xbfb8aa3b, v31
	v_exp_f32_e32 v96, v96
	v_exp_f32_e32 v97, v97
	v_exp_f32_e32 v98, v98
	v_exp_f32_e32 v99, v99
	v_exp_f32_e32 v100, v100
	v_exp_f32_e32 v101, v101
	v_exp_f32_e32 v102, v102
	v_exp_f32_e32 v103, v103
	v_exp_f32_e32 v104, v104
	v_exp_f32_e32 v105, v105
	v_exp_f32_e32 v106, v106
	v_exp_f32_e32 v107, v107
	v_exp_f32_e32 v108, v108
	v_exp_f32_e32 v109, v109
	v_exp_f32_e32 v110, v110
	v_exp_f32_e32 v111, v111
	v_add_f32_e32 v96, 1.0, v96
	v_add_f32_e32 v97, 1.0, v97
	v_add_f32_e32 v98, 1.0, v98
	v_add_f32_e32 v99, 1.0, v99
	v_add_f32_e32 v100, 1.0, v100
	v_add_f32_e32 v101, 1.0, v101
	v_add_f32_e32 v102, 1.0, v102
	v_add_f32_e32 v103, 1.0, v103
	v_add_f32_e32 v104, 1.0, v104
	v_add_f32_e32 v105, 1.0, v105
	v_add_f32_e32 v106, 1.0, v106
	v_add_f32_e32 v107, 1.0, v107
	v_add_f32_e32 v108, 1.0, v108
	v_add_f32_e32 v109, 1.0, v109
	v_add_f32_e32 v110, 1.0, v110
	v_add_f32_e32 v111, 1.0, v111
	v_rcp_f32_e32 v96, v96
	v_rcp_f32_e32 v97, v97
	v_rcp_f32_e32 v98, v98
	v_rcp_f32_e32 v99, v99
	v_rcp_f32_e32 v100, v100
	v_rcp_f32_e32 v101, v101
	v_rcp_f32_e32 v102, v102
	v_rcp_f32_e32 v103, v103
	v_rcp_f32_e32 v104, v104
	v_rcp_f32_e32 v105, v105
	v_rcp_f32_e32 v106, v106
	v_rcp_f32_e32 v107, v107
	v_rcp_f32_e32 v108, v108
	v_rcp_f32_e32 v109, v109
	v_rcp_f32_e32 v110, v110
	v_rcp_f32_e32 v111, v111
	v_lshlrev_b32_e32 v112, 16, v72
	v_and_b32_e32 v113, 0xffff0000, v72
	v_lshlrev_b32_e32 v114, 16, v73
	v_and_b32_e32 v115, 0xffff0000, v73
	v_lshlrev_b32_e32 v116, 16, v74
	v_and_b32_e32 v117, 0xffff0000, v74
	v_lshlrev_b32_e32 v118, 16, v75
	v_and_b32_e32 v119, 0xffff0000, v75
	v_lshlrev_b32_e32 v120, 16, v76
	v_and_b32_e32 v121, 0xffff0000, v76
	v_lshlrev_b32_e32 v122, 16, v77
	v_and_b32_e32 v123, 0xffff0000, v77
	v_lshlrev_b32_e32 v124, 16, v78
; __device__ __forceinline__ float bf2f(bf16_t b) { return __uint_as_float(((unsigned)b) << 16); }
; __device__ __forceinline__ float sigmoidf_(float v) { return 1.f / (1.f + __expf(-v)); }
; __device__ void phase_small(CParams& p, int l, int item, char* smem) {
;     ...
;   if (which == 0) {
;     EPI_LOOP({
;       float y = bf2f(p.ys[(size_t)(row0 + rl) * 256 + col0 + cl]);
;       p.br[(size_t)(row0 + rl) * 1024 + col0 + cl] = f2bf(y * sigmoidf_(acc[mi][ni][j]));
;     })
	v_and_b32_e32 v125, 0xffff0000, v78
	v_lshlrev_b32_e32 v126, 16, v79
	v_and_b32_e32 v127, 0xffff0000, v79
	v_mul_f32_e32 v96, v96, v112
	v_mul_f32_e32 v97, v97, v113
	v_mul_f32_e32 v98, v98, v114
	v_mul_f32_e32 v99, v99, v115
	v_mul_f32_e32 v100, v100, v116
	v_mul_f32_e32 v101, v101, v117
	v_mul_f32_e32 v102, v102, v118
	v_mul_f32_e32 v103, v103, v119
	v_mul_f32_e32 v104, v104, v120
	v_mul_f32_e32 v105, v105, v121
	v_mul_f32_e32 v106, v106, v122
	v_mul_f32_e32 v107, v107, v123
	v_mul_f32_e32 v108, v108, v124
	v_mul_f32_e32 v109, v109, v125
	v_mul_f32_e32 v110, v110, v126
	v_mul_f32_e32 v111, v111, v127
	v_cvt_pk_bf16_f32 v208, v96, v97
	v_cvt_pk_bf16_f32 v209, v98, v99
	v_cvt_pk_bf16_f32 v210, v100, v101
	v_cvt_pk_bf16_f32 v211, v102, v103
	v_cvt_pk_bf16_f32 v212, v104, v105
	v_cvt_pk_bf16_f32 v213, v106, v107
	v_cvt_pk_bf16_f32 v214, v108, v109
	v_cvt_pk_bf16_f32 v215, v110, v111
	v_mul_f32_e32 v96, 0xbfb8aa3b, v32
	v_mul_f32_e32 v97, 0xbfb8aa3b, v33
	v_mul_f32_e32 v98, 0xbfb8aa3b, v34
	v_mul_f32_e32 v99, 0xbfb8aa3b, v35
	v_mul_f32_e32 v100, 0xbfb8aa3b, v36
	v_mul_f32_e32 v101, 0xbfb8aa3b, v37
	v_mul_f32_e32 v102, 0xbfb8aa3b, v38
	v_mul_f32_e32 v103, 0xbfb8aa3b, v39
	v_mul_f32_e32 v104, 0xbfb8aa3b, v40
	v_mul_f32_e32 v105, 0xbfb8aa3b, v41
	v_mul_f32_e32 v106, 0xbfb8aa3b, v42
	v_mul_f32_e32 v107, 0xbfb8aa3b, v43
	v_mul_f32_e32 v108, 0xbfb8aa3b, v44
	v_mul_f32_e32 v109, 0xbfb8aa3b, v45
	v_mul_f32_e32 v110, 0xbfb8aa3b, v46
	v_mul_f32_e32 v111, 0xbfb8aa3b, v47
	v_exp_f32_e32 v96, v96
	v_exp_f32_e32 v97, v97
	v_exp_f32_e32 v98, v98
	v_exp_f32_e32 v99, v99
	v_exp_f32_e32 v100, v100
	v_exp_f32_e32 v101, v101
	v_exp_f32_e32 v102, v102
	v_exp_f32_e32 v103, v103
	v_exp_f32_e32 v104, v104
	v_exp_f32_e32 v105, v105
	v_exp_f32_e32 v106, v106
	v_exp_f32_e32 v107, v107
	v_exp_f32_e32 v108, v108
	v_exp_f32_e32 v109, v109
	v_exp_f32_e32 v110, v110
	v_exp_f32_e32 v111, v111
	v_add_f32_e32 v96, 1.0, v96
	v_add_f32_e32 v97, 1.0, v97
	v_add_f32_e32 v98, 1.0, v98
	v_add_f32_e32 v99, 1.0, v99
	v_add_f32_e32 v100, 1.0, v100
	v_add_f32_e32 v101, 1.0, v101
	v_add_f32_e32 v102, 1.0, v102
	v_add_f32_e32 v103, 1.0, v103
	v_add_f32_e32 v104, 1.0, v104
	v_add_f32_e32 v105, 1.0, v105
	v_add_f32_e32 v106, 1.0, v106
	v_add_f32_e32 v107, 1.0, v107
	v_add_f32_e32 v108, 1.0, v108
	v_add_f32_e32 v109, 1.0, v109
	v_add_f32_e32 v110, 1.0, v110
	v_add_f32_e32 v111, 1.0, v111
	v_rcp_f32_e32 v96, v96
	v_rcp_f32_e32 v97, v97
	v_rcp_f32_e32 v98, v98
	v_rcp_f32_e32 v99, v99
	v_rcp_f32_e32 v100, v100
	v_rcp_f32_e32 v101, v101
	v_rcp_f32_e32 v102, v102
	v_rcp_f32_e32 v103, v103
	v_rcp_f32_e32 v104, v104
	v_rcp_f32_e32 v105, v105
	v_rcp_f32_e32 v106, v106
	v_rcp_f32_e32 v107, v107
	v_rcp_f32_e32 v108, v108
	v_rcp_f32_e32 v109, v109
	v_rcp_f32_e32 v110, v110
	v_rcp_f32_e32 v111, v111
	v_lshlrev_b32_e32 v112, 16, v80
	v_and_b32_e32 v113, 0xffff0000, v80
	v_lshlrev_b32_e32 v114, 16, v81
	v_and_b32_e32 v115, 0xffff0000, v81
	v_lshlrev_b32_e32 v116, 16, v82
	v_and_b32_e32 v117, 0xffff0000, v82
	v_lshlrev_b32_e32 v118, 16, v83
	v_and_b32_e32 v119, 0xffff0000, v83
	v_lshlrev_b32_e32 v120, 16, v84
	v_and_b32_e32 v121, 0xffff0000, v84
	v_lshlrev_b32_e32 v122, 16, v85
	v_and_b32_e32 v123, 0xffff0000, v85
	v_lshlrev_b32_e32 v124, 16, v86
	v_and_b32_e32 v125, 0xffff0000, v86
	v_lshlrev_b32_e32 v126, 16, v87
	v_and_b32_e32 v127, 0xffff0000, v87
	v_mul_f32_e32 v96, v96, v112
	v_mul_f32_e32 v97, v97, v113
	v_mul_f32_e32 v98, v98, v114
	v_mul_f32_e32 v99, v99, v115
	v_mul_f32_e32 v100, v100, v116
	v_mul_f32_e32 v101, v101, v117
	v_mul_f32_e32 v102, v102, v118
	v_mul_f32_e32 v103, v103, v119
	v_mul_f32_e32 v104, v104, v120
	v_mul_f32_e32 v105, v105, v121
	v_mul_f32_e32 v106, v106, v122
	v_mul_f32_e32 v107, v107, v123
	v_mul_f32_e32 v108, v108, v124
	v_mul_f32_e32 v109, v109, v125
	v_mul_f32_e32 v110, v110, v126
	v_mul_f32_e32 v111, v111, v127
	v_cvt_pk_bf16_f32 v216, v96, v97
	v_cvt_pk_bf16_f32 v217, v98, v99
	v_cvt_pk_bf16_f32 v218, v100, v101
	v_cvt_pk_bf16_f32 v219, v102, v103
	v_cvt_pk_bf16_f32 v220, v104, v105
	v_cvt_pk_bf16_f32 v221, v106, v107
	v_cvt_pk_bf16_f32 v222, v108, v109
	v_cvt_pk_bf16_f32 v223, v110, v111
	v_mul_f32_e32 v96, 0xbfb8aa3b, v48
	v_mul_f32_e32 v97, 0xbfb8aa3b, v49
	v_mul_f32_e32 v98, 0xbfb8aa3b, v50
	v_mul_f32_e32 v99, 0xbfb8aa3b, v51
	v_mul_f32_e32 v100, 0xbfb8aa3b, v52
	v_mul_f32_e32 v101, 0xbfb8aa3b, v53
	v_mul_f32_e32 v102, 0xbfb8aa3b, v54
	v_mul_f32_e32 v103, 0xbfb8aa3b, v55
	v_mul_f32_e32 v104, 0xbfb8aa3b, v56
	v_mul_f32_e32 v105, 0xbfb8aa3b, v57
	v_mul_f32_e32 v106, 0xbfb8aa3b, v58
	v_mul_f32_e32 v107, 0xbfb8aa3b, v59
	v_mul_f32_e32 v108, 0xbfb8aa3b, v60
	v_mul_f32_e32 v109, 0xbfb8aa3b, v61
	v_mul_f32_e32 v110, 0xbfb8aa3b, v62
	v_mul_f32_e32 v111, 0xbfb8aa3b, v63
	v_exp_f32_e32 v96, v96
	v_exp_f32_e32 v97, v97
	v_exp_f32_e32 v98, v98
	v_exp_f32_e32 v99, v99
	v_exp_f32_e32 v100, v100
	v_exp_f32_e32 v101, v101
	v_exp_f32_e32 v102, v102
	v_exp_f32_e32 v103, v103
	v_exp_f32_e32 v104, v104
	v_exp_f32_e32 v105, v105
	v_exp_f32_e32 v106, v106
	v_exp_f32_e32 v107, v107
	v_exp_f32_e32 v108, v108
	v_exp_f32_e32 v109, v109
	v_exp_f32_e32 v110, v110
	v_exp_f32_e32 v111, v111
	v_add_f32_e32 v96, 1.0, v96
	v_add_f32_e32 v97, 1.0, v97
	v_add_f32_e32 v98, 1.0, v98
	v_add_f32_e32 v99, 1.0, v99
	v_add_f32_e32 v100, 1.0, v100
	v_add_f32_e32 v101, 1.0, v101
	v_add_f32_e32 v102, 1.0, v102
	v_add_f32_e32 v103, 1.0, v103
	v_add_f32_e32 v104, 1.0, v104
	v_add_f32_e32 v105, 1.0, v105
	v_add_f32_e32 v106, 1.0, v106
	v_add_f32_e32 v107, 1.0, v107
	v_add_f32_e32 v108, 1.0, v108
	v_add_f32_e32 v109, 1.0, v109
	v_add_f32_e32 v110, 1.0, v110
	v_add_f32_e32 v111, 1.0, v111
	v_rcp_f32_e32 v96, v96
; __device__ __forceinline__ float bf2f(bf16_t b) { return __uint_as_float(((unsigned)b) << 16); }
; __device__ __forceinline__ float sigmoidf_(float v) { return 1.f / (1.f + __expf(-v)); }
; __device__ void phase_small(CParams& p, int l, int item, char* smem) {
;     ...
;   if (which == 0) {
;     EPI_LOOP({
;       float y = bf2f(p.ys[(size_t)(row0 + rl) * 256 + col0 + cl]);
;       p.br[(size_t)(row0 + rl) * 1024 + col0 + cl] = f2bf(y * sigmoidf_(acc[mi][ni][j]));
;     })
;   } else {
;     int cb = which == 1 ? 256 : 768;
;     EPI_LOOP({ p.br[(size_t)(row0 + rl) * 1024 + cb + col0 + cl] = f2bf(acc[mi][ni][j]); })
;   }
	v_rcp_f32_e32 v97, v97
	v_rcp_f32_e32 v98, v98
	v_rcp_f32_e32 v99, v99
	v_rcp_f32_e32 v100, v100
	v_rcp_f32_e32 v101, v101
	v_rcp_f32_e32 v102, v102
	v_rcp_f32_e32 v103, v103
	v_rcp_f32_e32 v104, v104
	v_rcp_f32_e32 v105, v105
	v_rcp_f32_e32 v106, v106
	v_rcp_f32_e32 v107, v107
	v_rcp_f32_e32 v108, v108
	v_rcp_f32_e32 v109, v109
	v_rcp_f32_e32 v110, v110
	v_rcp_f32_e32 v111, v111
	v_lshlrev_b32_e32 v112, 16, v88
	v_and_b32_e32 v113, 0xffff0000, v88
	v_lshlrev_b32_e32 v114, 16, v89
	v_and_b32_e32 v115, 0xffff0000, v89
	v_lshlrev_b32_e32 v116, 16, v90
	v_and_b32_e32 v117, 0xffff0000, v90
	v_lshlrev_b32_e32 v118, 16, v91
	v_and_b32_e32 v119, 0xffff0000, v91
	v_lshlrev_b32_e32 v120, 16, v92
	v_and_b32_e32 v121, 0xffff0000, v92
	v_lshlrev_b32_e32 v122, 16, v93
	v_and_b32_e32 v123, 0xffff0000, v93
	v_lshlrev_b32_e32 v124, 16, v94
	v_and_b32_e32 v125, 0xffff0000, v94
	v_lshlrev_b32_e32 v126, 16, v95
	v_and_b32_e32 v127, 0xffff0000, v95
	v_mul_f32_e32 v96, v96, v112
	v_mul_f32_e32 v97, v97, v113
	v_mul_f32_e32 v98, v98, v114
	v_mul_f32_e32 v99, v99, v115
	v_mul_f32_e32 v100, v100, v116
	v_mul_f32_e32 v101, v101, v117
	v_mul_f32_e32 v102, v102, v118
	v_mul_f32_e32 v103, v103, v119
	v_mul_f32_e32 v104, v104, v120
	v_mul_f32_e32 v105, v105, v121
	v_mul_f32_e32 v106, v106, v122
	v_mul_f32_e32 v107, v107, v123
	v_mul_f32_e32 v108, v108, v124
	v_mul_f32_e32 v109, v109, v125
	v_mul_f32_e32 v110, v110, v126
	v_mul_f32_e32 v111, v111, v127
	v_cvt_pk_bf16_f32 v228, v96, v97
	v_cvt_pk_bf16_f32 v229, v98, v99
	v_cvt_pk_bf16_f32 v230, v100, v101
	v_cvt_pk_bf16_f32 v231, v102, v103
	v_cvt_pk_bf16_f32 v232, v104, v105
	v_cvt_pk_bf16_f32 v233, v106, v107
	v_cvt_pk_bf16_f32 v234, v108, v109
	v_cvt_pk_bf16_f32 v235, v110, v111
	global_store_dwordx4 v144, v[200:203], s[26:27] offset:0
	global_store_dwordx4 v144, v[204:207], s[26:27] offset:16
	s_add_u32 s26, s26, 0x8000
	s_addc_u32 s27, s27, 0
	global_store_dwordx4 v144, v[208:211], s[26:27] offset:0
	global_store_dwordx4 v144, v[212:215], s[26:27] offset:16
	s_add_u32 s26, s26, 0x8000
	s_addc_u32 s27, s27, 0
	global_store_dwordx4 v144, v[216:219], s[26:27] offset:0
	global_store_dwordx4 v144, v[220:223], s[26:27] offset:16
	s_add_u32 s26, s26, 0x8000
	s_addc_u32 s27, s27, 0
	global_store_dwordx4 v144, v[228:231], s[26:27] offset:0
	global_store_dwordx4 v144, v[232:235], s[26:27] offset:16
	s_branch .Lsml_edone
.Lsml_eplain:
	s_nop 7
	v_cvt_pk_bf16_f32 v200, v0, v1
	v_cvt_pk_bf16_f32 v201, v2, v3
	v_cvt_pk_bf16_f32 v202, v4, v5
	v_cvt_pk_bf16_f32 v203, v6, v7
	global_store_dwordx4 v144, v[200:203], s[26:27] offset:0
	v_cvt_pk_bf16_f32 v204, v8, v9
	v_cvt_pk_bf16_f32 v205, v10, v11
	v_cvt_pk_bf16_f32 v206, v12, v13
	v_cvt_pk_bf16_f32 v207, v14, v15
	global_store_dwordx4 v144, v[204:207], s[26:27] offset:16
	s_add_u32 s26, s26, 0x8000
	s_addc_u32 s27, s27, 0
	v_cvt_pk_bf16_f32 v208, v16, v17
	v_cvt_pk_bf16_f32 v209, v18, v19
	v_cvt_pk_bf16_f32 v210, v20, v21
	v_cvt_pk_bf16_f32 v211, v22, v23
	global_store_dwordx4 v144, v[208:211], s[26:27] offset:0
	v_cvt_pk_bf16_f32 v212, v24, v25
	v_cvt_pk_bf16_f32 v213, v26, v27
	v_cvt_pk_bf16_f32 v214, v28, v29
	v_cvt_pk_bf16_f32 v215, v30, v31
	global_store_dwordx4 v144, v[212:215], s[26:27] offset:16
	s_add_u32 s26, s26, 0x8000
	s_addc_u32 s27, s27, 0
	v_cvt_pk_bf16_f32 v216, v32, v33
	v_cvt_pk_bf16_f32 v217, v34, v35
	v_cvt_pk_bf16_f32 v218, v36, v37
	v_cvt_pk_bf16_f32 v219, v38, v39
	global_store_dwordx4 v144, v[216:219], s[26:27] offset:0
	v_cvt_pk_bf16_f32 v220, v40, v41
	v_cvt_pk_bf16_f32 v221, v42, v43
	v_cvt_pk_bf16_f32 v222, v44, v45
	v_cvt_pk_bf16_f32 v223, v46, v47
	global_store_dwordx4 v144, v[220:223], s[26:27] offset:16
	s_add_u32 s26, s26, 0x8000
	s_addc_u32 s27, s27, 0
	v_cvt_pk_bf16_f32 v228, v48, v49
	v_cvt_pk_bf16_f32 v229, v50, v51
	v_cvt_pk_bf16_f32 v230, v52, v53
	v_cvt_pk_bf16_f32 v231, v54, v55
	global_store_dwordx4 v144, v[228:231], s[26:27] offset:0
	v_cvt_pk_bf16_f32 v232, v56, v57
	v_cvt_pk_bf16_f32 v233, v58, v59
	v_cvt_pk_bf16_f32 v234, v60, v61
	v_cvt_pk_bf16_f32 v235, v62, v63
	global_store_dwordx4 v144, v[232:235], s[26:27] offset:16
.Lsml_edone:
	s_nop 1
	v_mov_b32_e32 v0, 0
	v_mov_b32_e32 v1, 0
	v_mov_b32_e32 v2, 0
	v_mov_b32_e32 v3, 0
	v_mov_b32_e32 v4, 0
	v_mov_b32_e32 v5, 0
	v_mov_b32_e32 v6, 0
	v_mov_b32_e32 v7, 0
	v_mov_b32_e32 v8, 0
	v_mov_b32_e32 v9, 0
	v_mov_b32_e32 v10, 0
	v_mov_b32_e32 v11, 0
	v_mov_b32_e32 v12, 0
	v_mov_b32_e32 v13, 0
	v_mov_b32_e32 v14, 0
	v_mov_b32_e32 v15, 0
	v_mov_b32_e32 v16, 0
	v_mov_b32_e32 v17, 0
	v_mov_b32_e32 v18, 0
	v_mov_b32_e32 v19, 0
	v_mov_b32_e32 v20, 0
	v_mov_b32_e32 v21, 0
	v_mov_b32_e32 v22, 0
	v_mov_b32_e32 v23, 0
	v_mov_b32_e32 v24, 0
	v_mov_b32_e32 v25, 0
	v_mov_b32_e32 v26, 0
	v_mov_b32_e32 v27, 0
	v_mov_b32_e32 v28, 0
	v_mov_b32_e32 v29, 0
	v_mov_b32_e32 v30, 0
	v_mov_b32_e32 v31, 0
	v_mov_b32_e32 v32, 0
	v_mov_b32_e32 v33, 0
	v_mov_b32_e32 v34, 0
	v_mov_b32_e32 v35, 0
	v_mov_b32_e32 v36, 0
	v_mov_b32_e32 v37, 0
	v_mov_b32_e32 v38, 0
	v_mov_b32_e32 v39, 0
	v_mov_b32_e32 v40, 0
	v_mov_b32_e32 v41, 0
	v_mov_b32_e32 v42, 0
	v_mov_b32_e32 v43, 0
	v_mov_b32_e32 v44, 0
	v_mov_b32_e32 v45, 0
	v_mov_b32_e32 v46, 0
	v_mov_b32_e32 v47, 0
	v_mov_b32_e32 v48, 0
	v_mov_b32_e32 v49, 0
	v_mov_b32_e32 v50, 0
	v_mov_b32_e32 v51, 0
	v_mov_b32_e32 v52, 0
	v_mov_b32_e32 v53, 0
	v_mov_b32_e32 v54, 0
	v_mov_b32_e32 v55, 0
	v_mov_b32_e32 v56, 0
	v_mov_b32_e32 v57, 0
	v_mov_b32_e32 v58, 0
	v_mov_b32_e32 v59, 0
	v_mov_b32_e32 v60, 0
	v_mov_b32_e32 v61, 0
	v_mov_b32_e32 v62, 0
	v_mov_b32_e32 v63, 0
	s_add_u32 s45, s45, 1
	s_cmp_lt_u32 s45, s52
	s_cbranch_scc1 .Lsml_tile
	s_waitcnt vmcnt(0) lgkmcnt(0)
	s_barrier
	ds_write_b128 v145, v[252:255] offset:40960
	s_waitcnt lgkmcnt(0)
	s_barrier
	s_mov_b32 s0, 0x8000

; template <int NI> ...
;     ...
;   for (int kt = 0; kt < nk; kt += 2) {
;     G_LOAD(a0, b0, min((kt + 2) * 32, klast));
;     G_COMPUTE(0);
;     G_WRITE(a1, b1, 1);
;     __syncthreads();
;     G_LOAD(a1, b1, min((kt + 3) * 32, klast));
;     G_COMPUTE(1);
;     G_WRITE(a0, b0, 0);
;     __syncthreads();
;   }
; __device__ void phase_merge4(CParams& p, int l, int tm, int tn, char* smem) {
;     ...
;       gemm_mainloop<4>(p.br + (size_t)row0 * 1024 + kb * 256, 1024,
;                        p.WbT + (((size_t)l * 4 + kb) * 1024 + col0) * 256, 256, 256, sA, sB, acc, tid2);
; #pragma unroll
;       for (int mi = 0; mi < 4; mi++)
; #pragma unroll
;         for (int ni = 0; ni < 4; ni++) {
;           pk[mi][ni][0] = (unsigned)f2bf(acc[mi][ni][0]) | ((unsigned)f2bf(acc[mi][ni][1]) << 16);
;           pk[mi][ni][1] = (unsigned)f2bf(acc[mi][ni][2]) | ((unsigned)f2bf(acc[mi][ni][3]) << 16);
;         }
;     }
;     f32x4 acc[4][4];
;     zero_acc<4>(acc);
;     asm volatile("" : "+v"(tid2));
;     gemm_mainloop<4>(p.hbuf + (size_t)row0 * DM, DM,
;                      p.WgT + (((size_t)l * 4 + kb) * 1024 + col0) * 1024, 1024, 1024, sA, sB, acc, tid2);
.Lmg4_nozero:
	s_waitcnt lgkmcnt(0)
	s_add_u32 m0, s56, 0x10000
	s_nop 0
	global_load_lds_dwordx4 v236, s[24:25]
	s_add_u32 m0, s56, 0x10400
	s_nop 0
	global_load_lds_dwordx4 v237, s[24:25]
	s_add_u32 m0, s56, 0x10800
	s_nop 0
	global_load_lds_dwordx4 v238, s[24:25]
	s_add_u32 m0, s56, 0x10c00
	s_nop 0
	global_load_lds_dwordx4 v239, s[24:25]
	s_add_u32 s24, s24, 128
	s_addc_u32 s25, s25, 0
	v_mfma_f32_16x16x32_bf16 v[0:3], v[184:187], v[168:171], 0
	ds_read_b128 v[200:203], v249 offset:0
	v_mfma_f32_16x16x32_bf16 v[4:7], v[188:191], v[168:171], 0
	ds_read_b128 v[216:219], v251 offset:16384
	v_mfma_f32_16x16x32_bf16 v[8:11], v[192:195], v[168:171], 0
	ds_read_b128 v[204:207], v249 offset:2048
	v_mfma_f32_16x16x32_bf16 v[12:15], v[196:199], v[168:171], 0
	ds_read_b128 v[220:223], v251 offset:16896
	v_mfma_f32_16x16x32_bf16 v[16:19], v[184:187], v[172:175], 0
	ds_read_b128 v[208:211], v249 offset:4096
	v_mfma_f32_16x16x32_bf16 v[20:23], v[188:191], v[172:175], 0
	ds_read_b128 v[228:231], v251 offset:17408
	v_mfma_f32_16x16x32_bf16 v[24:27], v[192:195], v[172:175], 0
	ds_read_b128 v[212:215], v249 offset:6144
	v_mfma_f32_16x16x32_bf16 v[28:31], v[196:199], v[172:175], 0
	ds_read_b128 v[232:235], v251 offset:17920
	v_mfma_f32_16x16x32_bf16 v[32:35], v[184:187], v[176:179], 0
	v_mfma_f32_16x16x32_bf16 v[36:39], v[188:191], v[176:179], 0
	v_mfma_f32_16x16x32_bf16 v[40:43], v[192:195], v[176:179], 0
	v_mfma_f32_16x16x32_bf16 v[44:47], v[196:199], v[176:179], 0
	v_mfma_f32_16x16x32_bf16 v[48:51], v[184:187], v[180:183], 0
	v_mfma_f32_16x16x32_bf16 v[52:55], v[188:191], v[180:183], 0
	v_mfma_f32_16x16x32_bf16 v[56:59], v[192:195], v[180:183], 0
	v_mfma_f32_16x16x32_bf16 v[60:63], v[196:199], v[180:183], 0
	s_waitcnt vmcnt(4) lgkmcnt(0)
	s_barrier
	s_add_u32 m0, s56, 0x0
	s_nop 0
	global_load_lds_dwordx4 v240, s[26:27]
	s_add_u32 m0, s56, 0x400
	s_nop 0
	global_load_lds_dwordx4 v241, s[26:27]
	s_add_u32 m0, s56, 0x800
	s_nop 0
	global_load_lds_dwordx4 v242, s[26:27]
	s_add_u32 m0, s56, 0xc00
	s_nop 0
	global_load_lds_dwordx4 v243, s[26:27]
	s_add_u32 s26, s26, 128
	s_addc_u32 s27, s27, 0
	v_mfma_f32_16x16x32_bf16 v[0:3], v[216:219], v[200:203], v[0:3]
	ds_read_b128 v[168:171], v248 offset:32768
	v_mfma_f32_16x16x32_bf16 v[4:7], v[220:223], v[200:203], v[4:7]
	ds_read_b128 v[184:187], v250 offset:49152
	v_mfma_f32_16x16x32_bf16 v[8:11], v[228:231], v[200:203], v[8:11]
	ds_read_b128 v[172:175], v248 offset:34816
	v_mfma_f32_16x16x32_bf16 v[12:15], v[232:235], v[200:203], v[12:15]
	ds_read_b128 v[188:191], v250 offset:49664
	v_mfma_f32_16x16x32_bf16 v[16:19], v[216:219], v[204:207], v[16:19]
	ds_read_b128 v[176:179], v248 offset:36864
	v_mfma_f32_16x16x32_bf16 v[20:23], v[220:223], v[204:207], v[20:23]
	ds_read_b128 v[192:195], v250 offset:50176
	v_mfma_f32_16x16x32_bf16 v[24:27], v[228:231], v[204:207], v[24:27]
	ds_read_b128 v[180:183], v248 offset:38912
	v_mfma_f32_16x16x32_bf16 v[28:31], v[232:235], v[204:207], v[28:31]
	ds_read_b128 v[196:199], v250 offset:50688
	v_mfma_f32_16x16x32_bf16 v[32:35], v[216:219], v[208:211], v[32:35]
	v_mfma_f32_16x16x32_bf16 v[36:39], v[220:223], v[208:211], v[36:39]
	v_mfma_f32_16x16x32_bf16 v[40:43], v[228:231], v[208:211], v[40:43]
	v_mfma_f32_16x16x32_bf16 v[44:47], v[232:235], v[208:211], v[44:47]
	v_mfma_f32_16x16x32_bf16 v[48:51], v[216:219], v[212:215], v[48:51]
	v_mfma_f32_16x16x32_bf16 v[52:55], v[220:223], v[212:215], v[52:55]
	v_mfma_f32_16x16x32_bf16 v[56:59], v[228:231], v[212:215], v[56:59]
	v_mfma_f32_16x16x32_bf16 v[60:63], v[232:235], v[212:215], v[60:63]
	s_waitcnt lgkmcnt(0)
	s_add_u32 m0, s56, 0x4000
	s_nop 0
	global_load_lds_dwordx4 v236, s[24:25]
	s_add_u32 m0, s56, 0x4400
	s_nop 0
	global_load_lds_dwordx4 v237, s[24:25]
	s_add_u32 m0, s56, 0x4800
	s_nop 0
	global_load_lds_dwordx4 v238, s[24:25]
	s_add_u32 m0, s56, 0x4c00
	s_nop 0
	global_load_lds_dwordx4 v239, s[24:25]
	s_add_u32 s24, s24, 128
	s_addc_u32 s25, s25, 0
	v_mfma_f32_16x16x32_bf16 v[0:3], v[184:187], v[168:171], v[0:3]
	ds_read_b128 v[200:203], v249 offset:32768
	v_mfma_f32_16x16x32_bf16 v[4:7], v[188:191], v[168:171], v[4:7]
	ds_read_b128 v[216:219], v251 offset:49152
	v_mfma_f32_16x16x32_bf16 v[8:11], v[192:195], v[168:171], v[8:11]
	ds_read_b128 v[204:207], v249 offset:34816
	v_mfma_f32_16x16x32_bf16 v[12:15], v[196:199], v[168:171], v[12:15]
	ds_read_b128 v[220:223], v251 offset:49664
	v_mfma_f32_16x16x32_bf16 v[16:19], v[184:187], v[172:175], v[16:19]
	ds_read_b128 v[208:211], v249 offset:36864
	v_mfma_f32_16x16x32_bf16 v[20:23], v[188:191], v[172:175], v[20:23]
	ds_read_b128 v[228:231], v251 offset:50176
	v_mfma_f32_16x16x32_bf16 v[24:27], v[192:195], v[172:175], v[24:27]
	ds_read_b128 v[212:215], v249 offset:38912
	v_mfma_f32_16x16x32_bf16 v[28:31], v[196:199], v[172:175], v[28:31]
	ds_read_b128 v[232:235], v251 offset:50688
	v_mfma_f32_16x16x32_bf16 v[32:35], v[184:187], v[176:179], v[32:35]
	v_mfma_f32_16x16x32_bf16 v[36:39], v[188:191], v[176:179], v[36:39]
	v_mfma_f32_16x16x32_bf16 v[40:43], v[192:195], v[176:179], v[40:43]
	v_mfma_f32_16x16x32_bf16 v[44:47], v[196:199], v[176:179], v[44:47]
	v_mfma_f32_16x16x32_bf16 v[48:51], v[184:187], v[180:183], v[48:51]
	v_mfma_f32_16x16x32_bf16 v[52:55], v[188:191], v[180:183], v[52:55]
	v_mfma_f32_16x16x32_bf16 v[56:59], v[192:195], v[180:183], v[56:59]
	v_mfma_f32_16x16x32_bf16 v[60:63], v[196:199], v[180:183], v[60:63]
	s_waitcnt vmcnt(4) lgkmcnt(0)
	s_barrier
; template <int NI> ...
;     ...
;   for (int kt = 0; kt < nk; kt += 2) {
;     G_LOAD(a0, b0, min((kt + 2) * 32, klast));
;     G_COMPUTE(0);
;     G_WRITE(a1, b1, 1);
;     __syncthreads();
;     G_LOAD(a1, b1, min((kt + 3) * 32, klast));
;     G_COMPUTE(1);
;     G_WRITE(a0, b0, 0);
;     __syncthreads();
;   }
; __device__ void phase_merge4(CParams& p, int l, int tm, int tn, char* smem) {
;     ...
;       gemm_mainloop<4>(p.br + (size_t)row0 * 1024 + kb * 256, 1024,
;                        p.WbT + (((size_t)l * 4 + kb) * 1024 + col0) * 256, 256, 256, sA, sB, acc, tid2);
; #pragma unroll
;       for (int mi = 0; mi < 4; mi++)
; #pragma unroll
;         for (int ni = 0; ni < 4; ni++) {
;           pk[mi][ni][0] = (unsigned)f2bf(acc[mi][ni][0]) | ((unsigned)f2bf(acc[mi][ni][1]) << 16);
;           pk[mi][ni][1] = (unsigned)f2bf(acc[mi][ni][2]) | ((unsigned)f2bf(acc[mi][ni][3]) << 16);
;         }
;     }
;     f32x4 acc[4][4];
;     zero_acc<4>(acc);
;     asm volatile("" : "+v"(tid2));
;     gemm_mainloop<4>(p.hbuf + (size_t)row0 * DM, DM,
;                      p.WgT + (((size_t)l * 4 + kb) * 1024 + col0) * 1024, 1024, 1024, sA, sB, acc, tid2);
	s_add_u32 m0, s56, 0x8000
	s_nop 0
	global_load_lds_dwordx4 v240, s[26:27]
	s_add_u32 m0, s56, 0x8400
	s_nop 0
	global_load_lds_dwordx4 v241, s[26:27]
	s_add_u32 m0, s56, 0x8800
	s_nop 0
	global_load_lds_dwordx4 v242, s[26:27]
	s_add_u32 m0, s56, 0x8c00
	s_nop 0
	global_load_lds_dwordx4 v243, s[26:27]
	s_add_u32 s26, s26, 128
	s_addc_u32 s27, s27, 0
	v_mfma_f32_16x16x32_bf16 v[0:3], v[216:219], v[200:203], v[0:3]
	ds_read_b128 v[168:171], v166 offset:49152
	v_mfma_f32_16x16x32_bf16 v[4:7], v[220:223], v[200:203], v[4:7]
	ds_read_b128 v[184:187], v250 offset:0
	v_mfma_f32_16x16x32_bf16 v[8:11], v[228:231], v[200:203], v[8:11]
	ds_read_b128 v[172:175], v166 offset:51200
	v_mfma_f32_16x16x32_bf16 v[12:15], v[232:235], v[200:203], v[12:15]
	ds_read_b128 v[188:191], v250 offset:512
	v_mfma_f32_16x16x32_bf16 v[16:19], v[216:219], v[204:207], v[16:19]
	ds_read_b128 v[176:179], v166 offset:53248
	v_mfma_f32_16x16x32_bf16 v[20:23], v[220:223], v[204:207], v[20:23]
	ds_read_b128 v[192:195], v250 offset:1024
	v_mfma_f32_16x16x32_bf16 v[24:27], v[228:231], v[204:207], v[24:27]
	ds_read_b128 v[180:183], v166 offset:55296
	v_mfma_f32_16x16x32_bf16 v[28:31], v[232:235], v[204:207], v[28:31]
	ds_read_b128 v[196:199], v250 offset:1536
	v_mfma_f32_16x16x32_bf16 v[32:35], v[216:219], v[208:211], v[32:35]
	v_mfma_f32_16x16x32_bf16 v[36:39], v[220:223], v[208:211], v[36:39]
	v_mfma_f32_16x16x32_bf16 v[40:43], v[228:231], v[208:211], v[40:43]
	v_mfma_f32_16x16x32_bf16 v[44:47], v[232:235], v[208:211], v[44:47]
	v_mfma_f32_16x16x32_bf16 v[48:51], v[216:219], v[212:215], v[48:51]
	v_mfma_f32_16x16x32_bf16 v[52:55], v[220:223], v[212:215], v[52:55]
	v_mfma_f32_16x16x32_bf16 v[56:59], v[228:231], v[212:215], v[56:59]
	v_mfma_f32_16x16x32_bf16 v[60:63], v[232:235], v[212:215], v[60:63]
	s_waitcnt lgkmcnt(0)
	s_mov_b64 s[24:25], s[50:51]
	s_add_u32 m0, s56, 0xc000
	s_nop 0
	global_load_lds_dwordx4 v236, s[24:25]
	s_add_u32 m0, s56, 0xc400
	s_nop 0
	global_load_lds_dwordx4 v237, s[24:25]
	s_add_u32 m0, s56, 0xc800
	s_nop 0
	global_load_lds_dwordx4 v238, s[24:25]
	s_add_u32 m0, s56, 0xcc00
	s_nop 0
	global_load_lds_dwordx4 v239, s[24:25]
	s_add_u32 s24, s24, 128
	s_addc_u32 s25, s25, 0
	v_mfma_f32_16x16x32_bf16 v[0:3], v[184:187], v[168:171], v[0:3]
	ds_read_b128 v[200:203], v167 offset:49152
	v_mfma_f32_16x16x32_bf16 v[4:7], v[188:191], v[168:171], v[4:7]
	ds_read_b128 v[216:219], v251 offset:0
	v_mfma_f32_16x16x32_bf16 v[8:11], v[192:195], v[168:171], v[8:11]
	ds_read_b128 v[204:207], v167 offset:51200
	v_mfma_f32_16x16x32_bf16 v[12:15], v[196:199], v[168:171], v[12:15]
	ds_read_b128 v[220:223], v251 offset:512
	v_mfma_f32_16x16x32_bf16 v[16:19], v[184:187], v[172:175], v[16:19]
	ds_read_b128 v[208:211], v167 offset:53248
	v_mfma_f32_16x16x32_bf16 v[20:23], v[188:191], v[172:175], v[20:23]
	ds_read_b128 v[228:231], v251 offset:1024
	v_mfma_f32_16x16x32_bf16 v[24:27], v[192:195], v[172:175], v[24:27]
	ds_read_b128 v[212:215], v167 offset:55296
	v_mfma_f32_16x16x32_bf16 v[28:31], v[196:199], v[172:175], v[28:31]
	ds_read_b128 v[232:235], v251 offset:1536
	v_mfma_f32_16x16x32_bf16 v[32:35], v[184:187], v[176:179], v[32:35]
	v_mfma_f32_16x16x32_bf16 v[36:39], v[188:191], v[176:179], v[36:39]
	v_mfma_f32_16x16x32_bf16 v[40:43], v[192:195], v[176:179], v[40:43]
	v_mfma_f32_16x16x32_bf16 v[44:47], v[196:199], v[176:179], v[44:47]
	v_mfma_f32_16x16x32_bf16 v[48:51], v[184:187], v[180:183], v[48:51]
	v_mfma_f32_16x16x32_bf16 v[52:55], v[188:191], v[180:183], v[52:55]
	v_mfma_f32_16x16x32_bf16 v[56:59], v[192:195], v[180:183], v[56:59]
	v_mfma_f32_16x16x32_bf16 v[60:63], v[196:199], v[180:183], v[60:63]
	s_waitcnt vmcnt(4) lgkmcnt(0)
	s_barrier
	s_mov_b64 s[26:27], s[54:55]
	s_add_u32 m0, s56, 0x10000
	s_nop 0
	global_load_lds_dwordx4 v244, s[26:27]
	s_add_u32 m0, s56, 0x10400
	s_nop 0
	global_load_lds_dwordx4 v245, s[26:27]
	s_add_u32 m0, s56, 0x10800
	s_nop 0
	global_load_lds_dwordx4 v246, s[26:27]
	s_add_u32 m0, s56, 0x10c00
	s_nop 0
	global_load_lds_dwordx4 v247, s[26:27]
	s_add_u32 s26, s26, 128
	s_addc_u32 s27, s27, 0
	v_mfma_f32_16x16x32_bf16 v[0:3], v[216:219], v[200:203], v[0:3]
	ds_read_b128 v[168:171], v248 offset:16384
	v_mfma_f32_16x16x32_bf16 v[4:7], v[220:223], v[200:203], v[4:7]
	ds_read_b128 v[184:187], v250 offset:32768
	v_mfma_f32_16x16x32_bf16 v[8:11], v[228:231], v[200:203], v[8:11]
	ds_read_b128 v[172:175], v248 offset:18432
	v_mfma_f32_16x16x32_bf16 v[12:15], v[232:235], v[200:203], v[12:15]
	ds_read_b128 v[188:191], v250 offset:33280
	v_mfma_f32_16x16x32_bf16 v[16:19], v[216:219], v[204:207], v[16:19]
	ds_read_b128 v[176:179], v248 offset:20480
	v_mfma_f32_16x16x32_bf16 v[20:23], v[220:223], v[204:207], v[20:23]
	ds_read_b128 v[192:195], v250 offset:33792
	v_mfma_f32_16x16x32_bf16 v[24:27], v[228:231], v[204:207], v[24:27]
	ds_read_b128 v[180:183], v248 offset:22528
	v_mfma_f32_16x16x32_bf16 v[28:31], v[232:235], v[204:207], v[28:31]
	ds_read_b128 v[196:199], v250 offset:34304
	v_mfma_f32_16x16x32_bf16 v[32:35], v[216:219], v[208:211], v[32:35]
	v_mfma_f32_16x16x32_bf16 v[36:39], v[220:223], v[208:211], v[36:39]
	v_mfma_f32_16x16x32_bf16 v[40:43], v[228:231], v[208:211], v[40:43]
	v_mfma_f32_16x16x32_bf16 v[44:47], v[232:235], v[208:211], v[44:47]
	v_mfma_f32_16x16x32_bf16 v[48:51], v[216:219], v[212:215], v[48:51]
	v_mfma_f32_16x16x32_bf16 v[52:55], v[220:223], v[212:215], v[52:55]
	v_mfma_f32_16x16x32_bf16 v[56:59], v[228:231], v[212:215], v[56:59]
	v_mfma_f32_16x16x32_bf16 v[60:63], v[232:235], v[212:215], v[60:63]
	s_waitcnt lgkmcnt(0)
; __device__ void phase_merge4(CParams& p, int l, int tm, int tn, char* smem) {
;     ...
; #pragma unroll
;       for (int mi = 0; mi < 4; mi++)
; #pragma unroll
;         for (int ni = 0; ni < 4; ni++) {
;           pk[mi][ni][0] = (unsigned)f2bf(acc[mi][ni][0]) | ((unsigned)f2bf(acc[mi][ni][1]) << 16);
;           pk[mi][ni][1] = (unsigned)f2bf(acc[mi][ni][2]) | ((unsigned)f2bf(acc[mi][ni][3]) << 16);
;         }
;     }
;     f32x4 acc[4][4];
;     zero_acc<4>(acc);
;     asm volatile("" : "+v"(tid2));
;     gemm_mainloop<4>(p.hbuf + (size_t)row0 * DM, DM,
;                      p.WgT + (((size_t)l * 4 + kb) * 1024 + col0) * 1024, 1024, 1024, sA, sB, acc, tid2);
	s_add_u32 m0, s56, 0x0
	s_nop 0
	global_load_lds_dwordx4 v236, s[24:25]
	s_add_u32 m0, s56, 0x400
	s_nop 0
	global_load_lds_dwordx4 v237, s[24:25]
	s_add_u32 m0, s56, 0x800
	s_nop 0
	global_load_lds_dwordx4 v238, s[24:25]
	s_add_u32 m0, s56, 0xc00
	s_nop 0
	global_load_lds_dwordx4 v239, s[24:25]
	s_add_u32 s24, s24, 128
	s_addc_u32 s25, s25, 0
	v_mfma_f32_16x16x32_bf16 v[0:3], v[184:187], v[168:171], v[0:3]
	ds_read_b128 v[200:203], v249 offset:16384
	v_mfma_f32_16x16x32_bf16 v[4:7], v[188:191], v[168:171], v[4:7]
	ds_read_b128 v[216:219], v251 offset:32768
	v_mfma_f32_16x16x32_bf16 v[8:11], v[192:195], v[168:171], v[8:11]
	ds_read_b128 v[204:207], v249 offset:18432
	v_mfma_f32_16x16x32_bf16 v[12:15], v[196:199], v[168:171], v[12:15]
	ds_read_b128 v[220:223], v251 offset:33280
	v_mfma_f32_16x16x32_bf16 v[16:19], v[184:187], v[172:175], v[16:19]
	ds_read_b128 v[208:211], v249 offset:20480
	v_mfma_f32_16x16x32_bf16 v[20:23], v[188:191], v[172:175], v[20:23]
	ds_read_b128 v[228:231], v251 offset:33792
	v_mfma_f32_16x16x32_bf16 v[24:27], v[192:195], v[172:175], v[24:27]
	ds_read_b128 v[212:215], v249 offset:22528
	v_mfma_f32_16x16x32_bf16 v[28:31], v[196:199], v[172:175], v[28:31]
	ds_read_b128 v[232:235], v251 offset:34304
	v_mfma_f32_16x16x32_bf16 v[32:35], v[184:187], v[176:179], v[32:35]
	v_mfma_f32_16x16x32_bf16 v[36:39], v[188:191], v[176:179], v[36:39]
	v_mfma_f32_16x16x32_bf16 v[40:43], v[192:195], v[176:179], v[40:43]
	v_mfma_f32_16x16x32_bf16 v[44:47], v[196:199], v[176:179], v[44:47]
	v_mfma_f32_16x16x32_bf16 v[48:51], v[184:187], v[180:183], v[48:51]
	v_mfma_f32_16x16x32_bf16 v[52:55], v[188:191], v[180:183], v[52:55]
	v_mfma_f32_16x16x32_bf16 v[56:59], v[192:195], v[180:183], v[56:59]
	v_mfma_f32_16x16x32_bf16 v[60:63], v[196:199], v[180:183], v[60:63]
	s_waitcnt vmcnt(4) lgkmcnt(0)
	s_barrier
	s_add_u32 m0, s56, 0x4000
	s_nop 0
	global_load_lds_dwordx4 v244, s[26:27]
	s_add_u32 m0, s56, 0x4400
	s_nop 0
	global_load_lds_dwordx4 v245, s[26:27]
	s_add_u32 m0, s56, 0x4800
	s_nop 0
	global_load_lds_dwordx4 v246, s[26:27]
	s_add_u32 m0, s56, 0x4c00
	s_nop 0
	global_load_lds_dwordx4 v247, s[26:27]
	s_add_u32 s26, s26, 128
	s_addc_u32 s27, s27, 0
	v_mfma_f32_16x16x32_bf16 v[0:3], v[216:219], v[200:203], v[0:3]
	ds_read_b128 v[168:171], v248 offset:49152
	v_mfma_f32_16x16x32_bf16 v[4:7], v[220:223], v[200:203], v[4:7]
	ds_read_b128 v[184:187], v226 offset:49152
	v_mfma_f32_16x16x32_bf16 v[8:11], v[228:231], v[200:203], v[8:11]
	ds_read_b128 v[172:175], v248 offset:51200
	v_mfma_f32_16x16x32_bf16 v[12:15], v[232:235], v[200:203], v[12:15]
	ds_read_b128 v[188:191], v226 offset:49664
	v_mfma_f32_16x16x32_bf16 v[16:19], v[216:219], v[204:207], v[16:19]
	ds_read_b128 v[176:179], v248 offset:53248
	v_mfma_f32_16x16x32_bf16 v[20:23], v[220:223], v[204:207], v[20:23]
	ds_read_b128 v[192:195], v226 offset:50176
	v_mfma_f32_16x16x32_bf16 v[24:27], v[228:231], v[204:207], v[24:27]
	ds_read_b128 v[180:183], v248 offset:55296
	v_mfma_f32_16x16x32_bf16 v[28:31], v[232:235], v[204:207], v[28:31]
	ds_read_b128 v[196:199], v226 offset:50688
	v_mfma_f32_16x16x32_bf16 v[32:35], v[216:219], v[208:211], v[32:35]
	v_mfma_f32_16x16x32_bf16 v[36:39], v[220:223], v[208:211], v[36:39]
	v_mfma_f32_16x16x32_bf16 v[40:43], v[228:231], v[208:211], v[40:43]
	v_mfma_f32_16x16x32_bf16 v[44:47], v[232:235], v[208:211], v[44:47]
	v_mfma_f32_16x16x32_bf16 v[48:51], v[216:219], v[212:215], v[48:51]
	v_mfma_f32_16x16x32_bf16 v[52:55], v[220:223], v[212:215], v[52:55]
	v_mfma_f32_16x16x32_bf16 v[56:59], v[228:231], v[212:215], v[56:59]
	v_mfma_f32_16x16x32_bf16 v[60:63], v[232:235], v[212:215], v[60:63]
	s_nop 15
	s_nop 7
	v_cvt_pk_bf16_f32 v128, v0, v1
	v_cvt_pk_bf16_f32 v129, v2, v3
	v_cvt_pk_bf16_f32 v130, v4, v5
	v_cvt_pk_bf16_f32 v131, v6, v7
	v_cvt_pk_bf16_f32 v132, v8, v9
	v_cvt_pk_bf16_f32 v133, v10, v11
	v_cvt_pk_bf16_f32 v134, v12, v13
	v_cvt_pk_bf16_f32 v135, v14, v15
	v_cvt_pk_bf16_f32 v136, v16, v17
	v_cvt_pk_bf16_f32 v137, v18, v19
	v_cvt_pk_bf16_f32 v138, v20, v21
	v_cvt_pk_bf16_f32 v139, v22, v23
	v_cvt_pk_bf16_f32 v140, v24, v25
	v_cvt_pk_bf16_f32 v141, v26, v27
	v_cvt_pk_bf16_f32 v142, v28, v29
	v_cvt_pk_bf16_f32 v143, v30, v31
	v_cvt_pk_bf16_f32 v148, v32, v33
	v_cvt_pk_bf16_f32 v149, v34, v35
	v_cvt_pk_bf16_f32 v150, v36, v37
	v_cvt_pk_bf16_f32 v151, v38, v39
	v_cvt_pk_bf16_f32 v152, v40, v41
	v_cvt_pk_bf16_f32 v153, v42, v43
	v_cvt_pk_bf16_f32 v154, v44, v45
	v_cvt_pk_bf16_f32 v155, v46, v47
	v_cvt_pk_bf16_f32 v156, v48, v49
	v_cvt_pk_bf16_f32 v157, v50, v51
	v_cvt_pk_bf16_f32 v158, v52, v53
	v_cvt_pk_bf16_f32 v159, v54, v55
	v_cvt_pk_bf16_f32 v160, v56, v57
	v_cvt_pk_bf16_f32 v161, v58, v59
	v_cvt_pk_bf16_f32 v162, v60, v61
	v_cvt_pk_bf16_f32 v163, v62, v63
	s_waitcnt lgkmcnt(0)
	s_add_u32 m0, s56, 0x8000
	s_nop 0
	global_load_lds_dwordx4 v236, s[24:25]
	s_add_u32 m0, s56, 0x8400
	s_nop 0
	global_load_lds_dwordx4 v237, s[24:25]
	s_add_u32 m0, s56, 0x8800
	s_nop 0
	global_load_lds_dwordx4 v238, s[24:25]
	s_add_u32 m0, s56, 0x8c00
	s_nop 0
	global_load_lds_dwordx4 v239, s[24:25]
	s_add_u32 s24, s24, 128
	s_addc_u32 s25, s25, 0
	v_mfma_f32_16x16x32_bf16 v[0:3], v[184:187], v[168:171], 0
	ds_read_b128 v[200:203], v249 offset:49152
	v_mfma_f32_16x16x32_bf16 v[4:7], v[188:191], v[168:171], 0
	ds_read_b128 v[216:219], v227 offset:49152
	v_mfma_f32_16x16x32_bf16 v[8:11], v[192:195], v[168:171], 0
	ds_read_b128 v[204:207], v249 offset:51200
	v_mfma_f32_16x16x32_bf16 v[12:15], v[196:199], v[168:171], 0
	ds_read_b128 v[220:223], v227 offset:49664
	v_mfma_f32_16x16x32_bf16 v[16:19], v[184:187], v[172:175], 0
	ds_read_b128 v[208:211], v249 offset:53248
	v_mfma_f32_16x16x32_bf16 v[20:23], v[188:191], v[172:175], 0
	ds_read_b128 v[228:231], v227 offset:50176
	v_mfma_f32_16x16x32_bf16 v[24:27], v[192:195], v[172:175], 0
	ds_read_b128 v[212:215], v249 offset:55296
	v_mfma_f32_16x16x32_bf16 v[28:31], v[196:199], v[172:175], 0
	ds_read_b128 v[232:235], v227 offset:50688
	v_mfma_f32_16x16x32_bf16 v[32:35], v[184:187], v[176:179], 0
	v_mfma_f32_16x16x32_bf16 v[36:39], v[188:191], v[176:179], 0
	v_mfma_f32_16x16x32_bf16 v[40:43], v[192:195], v[176:179], 0
	v_mfma_f32_16x16x32_bf16 v[44:47], v[196:199], v[176:179], 0
	v_mfma_f32_16x16x32_bf16 v[48:51], v[184:187], v[180:183], 0
	v_mfma_f32_16x16x32_bf16 v[52:55], v[188:191], v[180:183], 0
	v_mfma_f32_16x16x32_bf16 v[56:59], v[192:195], v[180:183], 0
	v_mfma_f32_16x16x32_bf16 v[60:63], v[196:199], v[180:183], 0
	s_waitcnt vmcnt(4) lgkmcnt(0)
	s_barrier
; template <int NI> ...
;     ...
;   for (int kt = 0; kt < nk; kt += 2) {
;     G_LOAD(a0, b0, min((kt + 2) * 32, klast));
;     G_COMPUTE(0);
;     G_WRITE(a1, b1, 1);
;     __syncthreads();
;     G_LOAD(a1, b1, min((kt + 3) * 32, klast));
;     G_COMPUTE(1);
;     G_WRITE(a0, b0, 0);
;     __syncthreads();
;   }
; __device__ void phase_merge4(CParams& p, int l, int tm, int tn, char* smem) {
;     ...
;     gemm_mainloop<4>(p.hbuf + (size_t)row0 * DM, DM,
;                      p.WgT + (((size_t)l * 4 + kb) * 1024 + col0) * 1024, 1024, 1024, sA, sB, acc, tid2);
	s_add_u32 m0, s56, 0xc000
	s_nop 0
	global_load_lds_dwordx4 v244, s[26:27]
	s_add_u32 m0, s56, 0xc400
	s_nop 0
	global_load_lds_dwordx4 v245, s[26:27]
	s_add_u32 m0, s56, 0xc800
	s_nop 0
	global_load_lds_dwordx4 v246, s[26:27]
	s_add_u32 m0, s56, 0xcc00
	s_nop 0
	global_load_lds_dwordx4 v247, s[26:27]
	s_add_u32 s26, s26, 128
	s_addc_u32 s27, s27, 0
	v_mfma_f32_16x16x32_bf16 v[0:3], v[216:219], v[200:203], v[0:3]
	ds_read_b128 v[168:171], v248 offset:0
	v_mfma_f32_16x16x32_bf16 v[4:7], v[220:223], v[200:203], v[4:7]
	ds_read_b128 v[184:187], v250 offset:16384
	v_mfma_f32_16x16x32_bf16 v[8:11], v[228:231], v[200:203], v[8:11]
	ds_read_b128 v[172:175], v248 offset:2048
	v_mfma_f32_16x16x32_bf16 v[12:15], v[232:235], v[200:203], v[12:15]
	ds_read_b128 v[188:191], v250 offset:16896
	v_mfma_f32_16x16x32_bf16 v[16:19], v[216:219], v[204:207], v[16:19]
	ds_read_b128 v[176:179], v248 offset:4096
	v_mfma_f32_16x16x32_bf16 v[20:23], v[220:223], v[204:207], v[20:23]
	ds_read_b128 v[192:195], v250 offset:17408
	v_mfma_f32_16x16x32_bf16 v[24:27], v[228:231], v[204:207], v[24:27]
	ds_read_b128 v[180:183], v248 offset:6144
	v_mfma_f32_16x16x32_bf16 v[28:31], v[232:235], v[204:207], v[28:31]
	ds_read_b128 v[196:199], v250 offset:17920
	v_mfma_f32_16x16x32_bf16 v[32:35], v[216:219], v[208:211], v[32:35]
	v_mfma_f32_16x16x32_bf16 v[36:39], v[220:223], v[208:211], v[36:39]
	v_mfma_f32_16x16x32_bf16 v[40:43], v[228:231], v[208:211], v[40:43]
	v_mfma_f32_16x16x32_bf16 v[44:47], v[232:235], v[208:211], v[44:47]
	v_mfma_f32_16x16x32_bf16 v[48:51], v[216:219], v[212:215], v[48:51]
	v_mfma_f32_16x16x32_bf16 v[52:55], v[220:223], v[212:215], v[52:55]
	v_mfma_f32_16x16x32_bf16 v[56:59], v[228:231], v[212:215], v[56:59]
	v_mfma_f32_16x16x32_bf16 v[60:63], v[232:235], v[212:215], v[60:63]
	s_waitcnt lgkmcnt(0)
	s_add_u32 m0, s56, 0x10000
	s_nop 0
	global_load_lds_dwordx4 v236, s[24:25]
	s_add_u32 m0, s56, 0x10400
	s_nop 0
	global_load_lds_dwordx4 v237, s[24:25]
	s_add_u32 m0, s56, 0x10800
	s_nop 0
	global_load_lds_dwordx4 v238, s[24:25]
	s_add_u32 m0, s56, 0x10c00
	s_nop 0
	global_load_lds_dwordx4 v239, s[24:25]
	s_add_u32 s24, s24, 128
	s_addc_u32 s25, s25, 0
	v_mfma_f32_16x16x32_bf16 v[0:3], v[184:187], v[168:171], v[0:3]
	ds_read_b128 v[200:203], v249 offset:0
	v_mfma_f32_16x16x32_bf16 v[4:7], v[188:191], v[168:171], v[4:7]
	ds_read_b128 v[216:219], v251 offset:16384
	v_mfma_f32_16x16x32_bf16 v[8:11], v[192:195], v[168:171], v[8:11]
	ds_read_b128 v[204:207], v249 offset:2048
	v_mfma_f32_16x16x32_bf16 v[12:15], v[196:199], v[168:171], v[12:15]
	ds_read_b128 v[220:223], v251 offset:16896
	v_mfma_f32_16x16x32_bf16 v[16:19], v[184:187], v[172:175], v[16:19]
	ds_read_b128 v[208:211], v249 offset:4096
	v_mfma_f32_16x16x32_bf16 v[20:23], v[188:191], v[172:175], v[20:23]
	ds_read_b128 v[228:231], v251 offset:17408
	v_mfma_f32_16x16x32_bf16 v[24:27], v[192:195], v[172:175], v[24:27]
	ds_read_b128 v[212:215], v249 offset:6144
	v_mfma_f32_16x16x32_bf16 v[28:31], v[196:199], v[172:175], v[28:31]
	ds_read_b128 v[232:235], v251 offset:17920
	v_mfma_f32_16x16x32_bf16 v[32:35], v[184:187], v[176:179], v[32:35]
	v_mfma_f32_16x16x32_bf16 v[36:39], v[188:191], v[176:179], v[36:39]
	v_mfma_f32_16x16x32_bf16 v[40:43], v[192:195], v[176:179], v[40:43]
	v_mfma_f32_16x16x32_bf16 v[44:47], v[196:199], v[176:179], v[44:47]
	v_mfma_f32_16x16x32_bf16 v[48:51], v[184:187], v[180:183], v[48:51]
	v_mfma_f32_16x16x32_bf16 v[52:55], v[188:191], v[180:183], v[52:55]
	v_mfma_f32_16x16x32_bf16 v[56:59], v[192:195], v[180:183], v[56:59]
	v_mfma_f32_16x16x32_bf16 v[60:63], v[196:199], v[180:183], v[60:63]
	s_waitcnt vmcnt(4) lgkmcnt(0)
	s_barrier
	s_add_u32 m0, s56, 0x0
	s_nop 0
	global_load_lds_dwordx4 v244, s[26:27]
	s_add_u32 m0, s56, 0x400
	s_nop 0
	global_load_lds_dwordx4 v245, s[26:27]
	s_add_u32 m0, s56, 0x800
	s_nop 0
	global_load_lds_dwordx4 v246, s[26:27]
	s_add_u32 m0, s56, 0xc00
	s_nop 0
	global_load_lds_dwordx4 v247, s[26:27]
	s_add_u32 s26, s26, 128
	s_addc_u32 s27, s27, 0
	v_mfma_f32_16x16x32_bf16 v[0:3], v[216:219], v[200:203], v[0:3]
	ds_read_b128 v[168:171], v248 offset:32768
	v_mfma_f32_16x16x32_bf16 v[4:7], v[220:223], v[200:203], v[4:7]
	ds_read_b128 v[184:187], v250 offset:49152
	v_mfma_f32_16x16x32_bf16 v[8:11], v[228:231], v[200:203], v[8:11]
	ds_read_b128 v[172:175], v248 offset:34816
	v_mfma_f32_16x16x32_bf16 v[12:15], v[232:235], v[200:203], v[12:15]
	ds_read_b128 v[188:191], v250 offset:49664
	v_mfma_f32_16x16x32_bf16 v[16:19], v[216:219], v[204:207], v[16:19]
	ds_read_b128 v[176:179], v248 offset:36864
	v_mfma_f32_16x16x32_bf16 v[20:23], v[220:223], v[204:207], v[20:23]
	ds_read_b128 v[192:195], v250 offset:50176
	v_mfma_f32_16x16x32_bf16 v[24:27], v[228:231], v[204:207], v[24:27]
	ds_read_b128 v[180:183], v248 offset:38912
	v_mfma_f32_16x16x32_bf16 v[28:31], v[232:235], v[204:207], v[28:31]
	ds_read_b128 v[196:199], v250 offset:50688
	v_mfma_f32_16x16x32_bf16 v[32:35], v[216:219], v[208:211], v[32:35]
	v_mfma_f32_16x16x32_bf16 v[36:39], v[220:223], v[208:211], v[36:39]
	v_mfma_f32_16x16x32_bf16 v[40:43], v[228:231], v[208:211], v[40:43]
	v_mfma_f32_16x16x32_bf16 v[44:47], v[232:235], v[208:211], v[44:47]
	v_mfma_f32_16x16x32_bf16 v[48:51], v[216:219], v[212:215], v[48:51]
	v_mfma_f32_16x16x32_bf16 v[52:55], v[220:223], v[212:215], v[52:55]
	v_mfma_f32_16x16x32_bf16 v[56:59], v[228:231], v[212:215], v[56:59]
	v_mfma_f32_16x16x32_bf16 v[60:63], v[232:235], v[212:215], v[60:63]
	s_waitcnt lgkmcnt(0)
; template <int NI> ...
;     ...
;   for (int kt = 0; kt < nk; kt += 2) {
;     G_LOAD(a0, b0, min((kt + 2) * 32, klast));
;     G_COMPUTE(0);
;     G_WRITE(a1, b1, 1);
;     __syncthreads();
;     G_LOAD(a1, b1, min((kt + 3) * 32, klast));
;     G_COMPUTE(1);
;     G_WRITE(a0, b0, 0);
;     __syncthreads();
;   }
; __device__ void phase_merge4(CParams& p, int l, int tm, int tn, char* smem) {
;     ...
;     gemm_mainloop<4>(p.hbuf + (size_t)row0 * DM, DM,
;                      p.WgT + (((size_t)l * 4 + kb) * 1024 + col0) * 1024, 1024, 1024, sA, sB, acc, tid2);
	s_add_u32 m0, s56, 0x4000
	s_nop 0
	global_load_lds_dwordx4 v236, s[24:25]
	s_add_u32 m0, s56, 0x4400
	s_nop 0
	global_load_lds_dwordx4 v237, s[24:25]
	s_add_u32 m0, s56, 0x4800
	s_nop 0
	global_load_lds_dwordx4 v238, s[24:25]
	s_add_u32 m0, s56, 0x4c00
	s_nop 0
	global_load_lds_dwordx4 v239, s[24:25]
	s_add_u32 s24, s24, 128
	s_addc_u32 s25, s25, 0
	v_mfma_f32_16x16x32_bf16 v[0:3], v[184:187], v[168:171], v[0:3]
	ds_read_b128 v[200:203], v249 offset:32768
	v_mfma_f32_16x16x32_bf16 v[4:7], v[188:191], v[168:171], v[4:7]
	ds_read_b128 v[216:219], v251 offset:49152
	v_mfma_f32_16x16x32_bf16 v[8:11], v[192:195], v[168:171], v[8:11]
	ds_read_b128 v[204:207], v249 offset:34816
	v_mfma_f32_16x16x32_bf16 v[12:15], v[196:199], v[168:171], v[12:15]
	ds_read_b128 v[220:223], v251 offset:49664
	v_mfma_f32_16x16x32_bf16 v[16:19], v[184:187], v[172:175], v[16:19]
	ds_read_b128 v[208:211], v249 offset:36864
	v_mfma_f32_16x16x32_bf16 v[20:23], v[188:191], v[172:175], v[20:23]
	ds_read_b128 v[228:231], v251 offset:50176
	v_mfma_f32_16x16x32_bf16 v[24:27], v[192:195], v[172:175], v[24:27]
	ds_read_b128 v[212:215], v249 offset:38912
	v_mfma_f32_16x16x32_bf16 v[28:31], v[196:199], v[172:175], v[28:31]
	ds_read_b128 v[232:235], v251 offset:50688
	v_mfma_f32_16x16x32_bf16 v[32:35], v[184:187], v[176:179], v[32:35]
	v_mfma_f32_16x16x32_bf16 v[36:39], v[188:191], v[176:179], v[36:39]
	v_mfma_f32_16x16x32_bf16 v[40:43], v[192:195], v[176:179], v[40:43]
	v_mfma_f32_16x16x32_bf16 v[44:47], v[196:199], v[176:179], v[44:47]
	v_mfma_f32_16x16x32_bf16 v[48:51], v[184:187], v[180:183], v[48:51]
	v_mfma_f32_16x16x32_bf16 v[52:55], v[188:191], v[180:183], v[52:55]
	v_mfma_f32_16x16x32_bf16 v[56:59], v[192:195], v[180:183], v[56:59]
	v_mfma_f32_16x16x32_bf16 v[60:63], v[196:199], v[180:183], v[60:63]
	s_waitcnt vmcnt(4) lgkmcnt(0)
	s_barrier
	s_add_u32 m0, s56, 0x8000
	s_nop 0
	global_load_lds_dwordx4 v244, s[26:27]
	s_add_u32 m0, s56, 0x8400
	s_nop 0
	global_load_lds_dwordx4 v245, s[26:27]
	s_add_u32 m0, s56, 0x8800
	s_nop 0
	global_load_lds_dwordx4 v246, s[26:27]
	s_add_u32 m0, s56, 0x8c00
	s_nop 0
	global_load_lds_dwordx4 v247, s[26:27]
	s_add_u32 s26, s26, 128
	s_addc_u32 s27, s27, 0
	v_mfma_f32_16x16x32_bf16 v[0:3], v[216:219], v[200:203], v[0:3]
	ds_read_b128 v[168:171], v166 offset:49152
	v_mfma_f32_16x16x32_bf16 v[4:7], v[220:223], v[200:203], v[4:7]
	ds_read_b128 v[184:187], v250 offset:0
	v_mfma_f32_16x16x32_bf16 v[8:11], v[228:231], v[200:203], v[8:11]
	ds_read_b128 v[172:175], v166 offset:51200
	v_mfma_f32_16x16x32_bf16 v[12:15], v[232:235], v[200:203], v[12:15]
	ds_read_b128 v[188:191], v250 offset:512
	v_mfma_f32_16x16x32_bf16 v[16:19], v[216:219], v[204:207], v[16:19]
	ds_read_b128 v[176:179], v166 offset:53248
	v_mfma_f32_16x16x32_bf16 v[20:23], v[220:223], v[204:207], v[20:23]
	ds_read_b128 v[192:195], v250 offset:1024
	v_mfma_f32_16x16x32_bf16 v[24:27], v[228:231], v[204:207], v[24:27]
	ds_read_b128 v[180:183], v166 offset:55296
	v_mfma_f32_16x16x32_bf16 v[28:31], v[232:235], v[204:207], v[28:31]
	ds_read_b128 v[196:199], v250 offset:1536
	v_mfma_f32_16x16x32_bf16 v[32:35], v[216:219], v[208:211], v[32:35]
	v_mfma_f32_16x16x32_bf16 v[36:39], v[220:223], v[208:211], v[36:39]
	v_mfma_f32_16x16x32_bf16 v[40:43], v[228:231], v[208:211], v[40:43]
	v_mfma_f32_16x16x32_bf16 v[44:47], v[232:235], v[208:211], v[44:47]
	v_mfma_f32_16x16x32_bf16 v[48:51], v[216:219], v[212:215], v[48:51]
	v_mfma_f32_16x16x32_bf16 v[52:55], v[220:223], v[212:215], v[52:55]
	v_mfma_f32_16x16x32_bf16 v[56:59], v[228:231], v[212:215], v[56:59]
	v_mfma_f32_16x16x32_bf16 v[60:63], v[232:235], v[212:215], v[60:63]
	s_waitcnt lgkmcnt(0)
	s_add_u32 m0, s56, 0xc000
	s_nop 0
	global_load_lds_dwordx4 v236, s[24:25]
	s_add_u32 m0, s56, 0xc400
	s_nop 0
	global_load_lds_dwordx4 v237, s[24:25]
	s_add_u32 m0, s56, 0xc800
	s_nop 0
	global_load_lds_dwordx4 v238, s[24:25]
	s_add_u32 m0, s56, 0xcc00
	s_nop 0
	global_load_lds_dwordx4 v239, s[24:25]
	s_add_u32 s24, s24, 128
	s_addc_u32 s25, s25, 0
	v_mfma_f32_16x16x32_bf16 v[0:3], v[184:187], v[168:171], v[0:3]
	ds_read_b128 v[200:203], v167 offset:49152
	v_mfma_f32_16x16x32_bf16 v[4:7], v[188:191], v[168:171], v[4:7]
	ds_read_b128 v[216:219], v251 offset:0
	v_mfma_f32_16x16x32_bf16 v[8:11], v[192:195], v[168:171], v[8:11]
	ds_read_b128 v[204:207], v167 offset:51200
	v_mfma_f32_16x16x32_bf16 v[12:15], v[196:199], v[168:171], v[12:15]
	ds_read_b128 v[220:223], v251 offset:512
	v_mfma_f32_16x16x32_bf16 v[16:19], v[184:187], v[172:175], v[16:19]
	ds_read_b128 v[208:211], v167 offset:53248
	v_mfma_f32_16x16x32_bf16 v[20:23], v[188:191], v[172:175], v[20:23]
	ds_read_b128 v[228:231], v251 offset:1024
	v_mfma_f32_16x16x32_bf16 v[24:27], v[192:195], v[172:175], v[24:27]
	ds_read_b128 v[212:215], v167 offset:55296
	v_mfma_f32_16x16x32_bf16 v[28:31], v[196:199], v[172:175], v[28:31]
	ds_read_b128 v[232:235], v251 offset:1536
	v_mfma_f32_16x16x32_bf16 v[32:35], v[184:187], v[176:179], v[32:35]
	v_mfma_f32_16x16x32_bf16 v[36:39], v[188:191], v[176:179], v[36:39]
	v_mfma_f32_16x16x32_bf16 v[40:43], v[192:195], v[176:179], v[40:43]
	v_mfma_f32_16x16x32_bf16 v[44:47], v[196:199], v[176:179], v[44:47]
	v_mfma_f32_16x16x32_bf16 v[48:51], v[184:187], v[180:183], v[48:51]
	v_mfma_f32_16x16x32_bf16 v[52:55], v[188:191], v[180:183], v[52:55]
	v_mfma_f32_16x16x32_bf16 v[56:59], v[192:195], v[180:183], v[56:59]
	v_mfma_f32_16x16x32_bf16 v[60:63], v[196:199], v[180:183], v[60:63]
	s_waitcnt vmcnt(4) lgkmcnt(0)
	s_barrier
; template <int NI> ...
;     ...
;   for (int kt = 0; kt < nk; kt += 2) {
;     G_LOAD(a0, b0, min((kt + 2) * 32, klast));
;     G_COMPUTE(0);
;     G_WRITE(a1, b1, 1);
;     __syncthreads();
;     G_LOAD(a1, b1, min((kt + 3) * 32, klast));
;     G_COMPUTE(1);
;     G_WRITE(a0, b0, 0);
;     __syncthreads();
;   }
; __device__ void phase_merge4(CParams& p, int l, int tm, int tn, char* smem) {
;     ...
;     gemm_mainloop<4>(p.hbuf + (size_t)row0 * DM, DM,
;                      p.WgT + (((size_t)l * 4 + kb) * 1024 + col0) * 1024, 1024, 1024, sA, sB, acc, tid2);
	s_add_u32 m0, s56, 0x10000
	s_nop 0
	global_load_lds_dwordx4 v244, s[26:27]
	s_add_u32 m0, s56, 0x10400
	s_nop 0
	global_load_lds_dwordx4 v245, s[26:27]
	s_add_u32 m0, s56, 0x10800
	s_nop 0
	global_load_lds_dwordx4 v246, s[26:27]
	s_add_u32 m0, s56, 0x10c00
	s_nop 0
	global_load_lds_dwordx4 v247, s[26:27]
	s_add_u32 s26, s26, 128
	s_addc_u32 s27, s27, 0
	v_mfma_f32_16x16x32_bf16 v[0:3], v[216:219], v[200:203], v[0:3]
	ds_read_b128 v[168:171], v248 offset:16384
	v_mfma_f32_16x16x32_bf16 v[4:7], v[220:223], v[200:203], v[4:7]
	ds_read_b128 v[184:187], v250 offset:32768
	v_mfma_f32_16x16x32_bf16 v[8:11], v[228:231], v[200:203], v[8:11]
	ds_read_b128 v[172:175], v248 offset:18432
	v_mfma_f32_16x16x32_bf16 v[12:15], v[232:235], v[200:203], v[12:15]
	ds_read_b128 v[188:191], v250 offset:33280
	v_mfma_f32_16x16x32_bf16 v[16:19], v[216:219], v[204:207], v[16:19]
	ds_read_b128 v[176:179], v248 offset:20480
	v_mfma_f32_16x16x32_bf16 v[20:23], v[220:223], v[204:207], v[20:23]
	ds_read_b128 v[192:195], v250 offset:33792
	v_mfma_f32_16x16x32_bf16 v[24:27], v[228:231], v[204:207], v[24:27]
	ds_read_b128 v[180:183], v248 offset:22528
	v_mfma_f32_16x16x32_bf16 v[28:31], v[232:235], v[204:207], v[28:31]
	ds_read_b128 v[196:199], v250 offset:34304
	v_mfma_f32_16x16x32_bf16 v[32:35], v[216:219], v[208:211], v[32:35]
	v_mfma_f32_16x16x32_bf16 v[36:39], v[220:223], v[208:211], v[36:39]
	v_mfma_f32_16x16x32_bf16 v[40:43], v[228:231], v[208:211], v[40:43]
	v_mfma_f32_16x16x32_bf16 v[44:47], v[232:235], v[208:211], v[44:47]
	v_mfma_f32_16x16x32_bf16 v[48:51], v[216:219], v[212:215], v[48:51]
	v_mfma_f32_16x16x32_bf16 v[52:55], v[220:223], v[212:215], v[52:55]
	v_mfma_f32_16x16x32_bf16 v[56:59], v[228:231], v[212:215], v[56:59]
	v_mfma_f32_16x16x32_bf16 v[60:63], v[232:235], v[212:215], v[60:63]
	s_waitcnt lgkmcnt(0)
	s_add_u32 m0, s56, 0x0
	s_nop 0
	global_load_lds_dwordx4 v236, s[24:25]
	s_add_u32 m0, s56, 0x400
	s_nop 0
	global_load_lds_dwordx4 v237, s[24:25]
	s_add_u32 m0, s56, 0x800
	s_nop 0
	global_load_lds_dwordx4 v238, s[24:25]
	s_add_u32 m0, s56, 0xc00
	s_nop 0
	global_load_lds_dwordx4 v239, s[24:25]
	s_add_u32 s24, s24, 128
	s_addc_u32 s25, s25, 0
	v_mfma_f32_16x16x32_bf16 v[0:3], v[184:187], v[168:171], v[0:3]
	ds_read_b128 v[200:203], v249 offset:16384
	v_mfma_f32_16x16x32_bf16 v[4:7], v[188:191], v[168:171], v[4:7]
	ds_read_b128 v[216:219], v251 offset:32768
	v_mfma_f32_16x16x32_bf16 v[8:11], v[192:195], v[168:171], v[8:11]
	ds_read_b128 v[204:207], v249 offset:18432
	v_mfma_f32_16x16x32_bf16 v[12:15], v[196:199], v[168:171], v[12:15]
	ds_read_b128 v[220:223], v251 offset:33280
	v_mfma_f32_16x16x32_bf16 v[16:19], v[184:187], v[172:175], v[16:19]
	ds_read_b128 v[208:211], v249 offset:20480
	v_mfma_f32_16x16x32_bf16 v[20:23], v[188:191], v[172:175], v[20:23]
	ds_read_b128 v[228:231], v251 offset:33792
	v_mfma_f32_16x16x32_bf16 v[24:27], v[192:195], v[172:175], v[24:27]
	ds_read_b128 v[212:215], v249 offset:22528
	v_mfma_f32_16x16x32_bf16 v[28:31], v[196:199], v[172:175], v[28:31]
	ds_read_b128 v[232:235], v251 offset:34304
	v_mfma_f32_16x16x32_bf16 v[32:35], v[184:187], v[176:179], v[32:35]
	v_mfma_f32_16x16x32_bf16 v[36:39], v[188:191], v[176:179], v[36:39]
	v_mfma_f32_16x16x32_bf16 v[40:43], v[192:195], v[176:179], v[40:43]
	v_mfma_f32_16x16x32_bf16 v[44:47], v[196:199], v[176:179], v[44:47]
	v_mfma_f32_16x16x32_bf16 v[48:51], v[184:187], v[180:183], v[48:51]
	v_mfma_f32_16x16x32_bf16 v[52:55], v[188:191], v[180:183], v[52:55]
	v_mfma_f32_16x16x32_bf16 v[56:59], v[192:195], v[180:183], v[56:59]
	v_mfma_f32_16x16x32_bf16 v[60:63], v[196:199], v[180:183], v[60:63]
	s_waitcnt vmcnt(4) lgkmcnt(0)
	s_barrier
	s_add_u32 m0, s56, 0x4000
	s_nop 0
	global_load_lds_dwordx4 v244, s[26:27]
	s_add_u32 m0, s56, 0x4400
	s_nop 0
	global_load_lds_dwordx4 v245, s[26:27]
	s_add_u32 m0, s56, 0x4800
	s_nop 0
	global_load_lds_dwordx4 v246, s[26:27]
	s_add_u32 m0, s56, 0x4c00
	s_nop 0
	global_load_lds_dwordx4 v247, s[26:27]
	s_add_u32 s26, s26, 128
	s_addc_u32 s27, s27, 0
	v_mfma_f32_16x16x32_bf16 v[0:3], v[216:219], v[200:203], v[0:3]
	ds_read_b128 v[168:171], v248 offset:49152
	v_mfma_f32_16x16x32_bf16 v[4:7], v[220:223], v[200:203], v[4:7]
	ds_read_b128 v[184:187], v226 offset:49152
	v_mfma_f32_16x16x32_bf16 v[8:11], v[228:231], v[200:203], v[8:11]
	ds_read_b128 v[172:175], v248 offset:51200
	v_mfma_f32_16x16x32_bf16 v[12:15], v[232:235], v[200:203], v[12:15]
	ds_read_b128 v[188:191], v226 offset:49664
	v_mfma_f32_16x16x32_bf16 v[16:19], v[216:219], v[204:207], v[16:19]
	ds_read_b128 v[176:179], v248 offset:53248
	v_mfma_f32_16x16x32_bf16 v[20:23], v[220:223], v[204:207], v[20:23]
	ds_read_b128 v[192:195], v226 offset:50176
	v_mfma_f32_16x16x32_bf16 v[24:27], v[228:231], v[204:207], v[24:27]
	ds_read_b128 v[180:183], v248 offset:55296
	v_mfma_f32_16x16x32_bf16 v[28:31], v[232:235], v[204:207], v[28:31]
	ds_read_b128 v[196:199], v226 offset:50688
	v_mfma_f32_16x16x32_bf16 v[32:35], v[216:219], v[208:211], v[32:35]
	v_mfma_f32_16x16x32_bf16 v[36:39], v[220:223], v[208:211], v[36:39]
	v_mfma_f32_16x16x32_bf16 v[40:43], v[228:231], v[208:211], v[40:43]
	v_mfma_f32_16x16x32_bf16 v[44:47], v[232:235], v[208:211], v[44:47]
	v_mfma_f32_16x16x32_bf16 v[48:51], v[216:219], v[212:215], v[48:51]
	v_mfma_f32_16x16x32_bf16 v[52:55], v[220:223], v[212:215], v[52:55]
	v_mfma_f32_16x16x32_bf16 v[56:59], v[228:231], v[212:215], v[56:59]
	v_mfma_f32_16x16x32_bf16 v[60:63], v[232:235], v[212:215], v[60:63]
	s_waitcnt lgkmcnt(0)
; template <int NI> ...
;     ...
;   for (int kt = 0; kt < nk; kt += 2) {
;     G_LOAD(a0, b0, min((kt + 2) * 32, klast));
;     G_COMPUTE(0);
;     G_WRITE(a1, b1, 1);
;     __syncthreads();
;     G_LOAD(a1, b1, min((kt + 3) * 32, klast));
;     G_COMPUTE(1);
;     G_WRITE(a0, b0, 0);
;     __syncthreads();
;   }
; __device__ void phase_merge4(CParams& p, int l, int tm, int tn, char* smem) {
;     ...
;     gemm_mainloop<4>(p.hbuf + (size_t)row0 * DM, DM,
;                      p.WgT + (((size_t)l * 4 + kb) * 1024 + col0) * 1024, 1024, 1024, sA, sB, acc, tid2);
	s_add_u32 m0, s56, 0x8000
	s_nop 0
	global_load_lds_dwordx4 v236, s[24:25]
	s_add_u32 m0, s56, 0x8400
	s_nop 0
	global_load_lds_dwordx4 v237, s[24:25]
	s_add_u32 m0, s56, 0x8800
	s_nop 0
	global_load_lds_dwordx4 v238, s[24:25]
	s_add_u32 m0, s56, 0x8c00
	s_nop 0
	global_load_lds_dwordx4 v239, s[24:25]
	s_add_u32 s24, s24, 128
	s_addc_u32 s25, s25, 0
	v_mfma_f32_16x16x32_bf16 v[0:3], v[184:187], v[168:171], v[0:3]
	ds_read_b128 v[200:203], v249 offset:49152
	v_mfma_f32_16x16x32_bf16 v[4:7], v[188:191], v[168:171], v[4:7]
	ds_read_b128 v[216:219], v227 offset:49152
	v_mfma_f32_16x16x32_bf16 v[8:11], v[192:195], v[168:171], v[8:11]
	ds_read_b128 v[204:207], v249 offset:51200
	v_mfma_f32_16x16x32_bf16 v[12:15], v[196:199], v[168:171], v[12:15]
	ds_read_b128 v[220:223], v227 offset:49664
	v_mfma_f32_16x16x32_bf16 v[16:19], v[184:187], v[172:175], v[16:19]
	ds_read_b128 v[208:211], v249 offset:53248
	v_mfma_f32_16x16x32_bf16 v[20:23], v[188:191], v[172:175], v[20:23]
	ds_read_b128 v[228:231], v227 offset:50176
	v_mfma_f32_16x16x32_bf16 v[24:27], v[192:195], v[172:175], v[24:27]
	ds_read_b128 v[212:215], v249 offset:55296
	v_mfma_f32_16x16x32_bf16 v[28:31], v[196:199], v[172:175], v[28:31]
	ds_read_b128 v[232:235], v227 offset:50688
	v_mfma_f32_16x16x32_bf16 v[32:35], v[184:187], v[176:179], v[32:35]
	v_mfma_f32_16x16x32_bf16 v[36:39], v[188:191], v[176:179], v[36:39]
	v_mfma_f32_16x16x32_bf16 v[40:43], v[192:195], v[176:179], v[40:43]
	v_mfma_f32_16x16x32_bf16 v[44:47], v[196:199], v[176:179], v[44:47]
	v_mfma_f32_16x16x32_bf16 v[48:51], v[184:187], v[180:183], v[48:51]
	v_mfma_f32_16x16x32_bf16 v[52:55], v[188:191], v[180:183], v[52:55]
	v_mfma_f32_16x16x32_bf16 v[56:59], v[192:195], v[180:183], v[56:59]
	v_mfma_f32_16x16x32_bf16 v[60:63], v[196:199], v[180:183], v[60:63]
	s_waitcnt vmcnt(4) lgkmcnt(0)
	s_barrier
	s_add_u32 m0, s56, 0xc000
	s_nop 0
	global_load_lds_dwordx4 v244, s[26:27]
	s_add_u32 m0, s56, 0xc400
	s_nop 0
	global_load_lds_dwordx4 v245, s[26:27]
	s_add_u32 m0, s56, 0xc800
	s_nop 0
	global_load_lds_dwordx4 v246, s[26:27]
	s_add_u32 m0, s56, 0xcc00
	s_nop 0
	global_load_lds_dwordx4 v247, s[26:27]
	s_add_u32 s26, s26, 128
	s_addc_u32 s27, s27, 0
	v_mfma_f32_16x16x32_bf16 v[0:3], v[216:219], v[200:203], v[0:3]
	ds_read_b128 v[168:171], v248 offset:0
	v_mfma_f32_16x16x32_bf16 v[4:7], v[220:223], v[200:203], v[4:7]
	ds_read_b128 v[184:187], v250 offset:16384
	v_mfma_f32_16x16x32_bf16 v[8:11], v[228:231], v[200:203], v[8:11]
	ds_read_b128 v[172:175], v248 offset:2048
	v_mfma_f32_16x16x32_bf16 v[12:15], v[232:235], v[200:203], v[12:15]
	ds_read_b128 v[188:191], v250 offset:16896
	v_mfma_f32_16x16x32_bf16 v[16:19], v[216:219], v[204:207], v[16:19]
	ds_read_b128 v[176:179], v248 offset:4096
	v_mfma_f32_16x16x32_bf16 v[20:23], v[220:223], v[204:207], v[20:23]
	ds_read_b128 v[192:195], v250 offset:17408
	v_mfma_f32_16x16x32_bf16 v[24:27], v[228:231], v[204:207], v[24:27]
	ds_read_b128 v[180:183], v248 offset:6144
	v_mfma_f32_16x16x32_bf16 v[28:31], v[232:235], v[204:207], v[28:31]
	ds_read_b128 v[196:199], v250 offset:17920
	v_mfma_f32_16x16x32_bf16 v[32:35], v[216:219], v[208:211], v[32:35]
	v_mfma_f32_16x16x32_bf16 v[36:39], v[220:223], v[208:211], v[36:39]
	v_mfma_f32_16x16x32_bf16 v[40:43], v[228:231], v[208:211], v[40:43]
	v_mfma_f32_16x16x32_bf16 v[44:47], v[232:235], v[208:211], v[44:47]
	v_mfma_f32_16x16x32_bf16 v[48:51], v[216:219], v[212:215], v[48:51]
	v_mfma_f32_16x16x32_bf16 v[52:55], v[220:223], v[212:215], v[52:55]
	v_mfma_f32_16x16x32_bf16 v[56:59], v[228:231], v[212:215], v[56:59]
	v_mfma_f32_16x16x32_bf16 v[60:63], v[232:235], v[212:215], v[60:63]
	s_waitcnt lgkmcnt(0)
	s_add_u32 m0, s56, 0x10000
	s_nop 0
	global_load_lds_dwordx4 v236, s[24:25]
	s_add_u32 m0, s56, 0x10400
	s_nop 0
	global_load_lds_dwordx4 v237, s[24:25]
	s_add_u32 m0, s56, 0x10800
	s_nop 0
	global_load_lds_dwordx4 v238, s[24:25]
	s_add_u32 m0, s56, 0x10c00
	s_nop 0
	global_load_lds_dwordx4 v239, s[24:25]
	s_add_u32 s24, s24, 128
	s_addc_u32 s25, s25, 0
	v_mfma_f32_16x16x32_bf16 v[0:3], v[184:187], v[168:171], v[0:3]
	ds_read_b128 v[200:203], v249 offset:0
	v_mfma_f32_16x16x32_bf16 v[4:7], v[188:191], v[168:171], v[4:7]
	ds_read_b128 v[216:219], v251 offset:16384
	v_mfma_f32_16x16x32_bf16 v[8:11], v[192:195], v[168:171], v[8:11]
	ds_read_b128 v[204:207], v249 offset:2048
	v_mfma_f32_16x16x32_bf16 v[12:15], v[196:199], v[168:171], v[12:15]
	ds_read_b128 v[220:223], v251 offset:16896
	v_mfma_f32_16x16x32_bf16 v[16:19], v[184:187], v[172:175], v[16:19]
	ds_read_b128 v[208:211], v249 offset:4096
	v_mfma_f32_16x16x32_bf16 v[20:23], v[188:191], v[172:175], v[20:23]
	ds_read_b128 v[228:231], v251 offset:17408
	v_mfma_f32_16x16x32_bf16 v[24:27], v[192:195], v[172:175], v[24:27]
	ds_read_b128 v[212:215], v249 offset:6144
	v_mfma_f32_16x16x32_bf16 v[28:31], v[196:199], v[172:175], v[28:31]
	ds_read_b128 v[232:235], v251 offset:17920
	v_mfma_f32_16x16x32_bf16 v[32:35], v[184:187], v[176:179], v[32:35]
	v_mfma_f32_16x16x32_bf16 v[36:39], v[188:191], v[176:179], v[36:39]
	v_mfma_f32_16x16x32_bf16 v[40:43], v[192:195], v[176:179], v[40:43]
	v_mfma_f32_16x16x32_bf16 v[44:47], v[196:199], v[176:179], v[44:47]
	v_mfma_f32_16x16x32_bf16 v[48:51], v[184:187], v[180:183], v[48:51]
	v_mfma_f32_16x16x32_bf16 v[52:55], v[188:191], v[180:183], v[52:55]
	v_mfma_f32_16x16x32_bf16 v[56:59], v[192:195], v[180:183], v[56:59]
	v_mfma_f32_16x16x32_bf16 v[60:63], v[196:199], v[180:183], v[60:63]
	s_waitcnt vmcnt(4) lgkmcnt(0)
	s_barrier
; template <int NI> ...
;     ...
;   for (int kt = 0; kt < nk; kt += 2) {
;     G_LOAD(a0, b0, min((kt + 2) * 32, klast));
;     G_COMPUTE(0);
;     G_WRITE(a1, b1, 1);
;     __syncthreads();
;     G_LOAD(a1, b1, min((kt + 3) * 32, klast));
;     G_COMPUTE(1);
;     G_WRITE(a0, b0, 0);
;     __syncthreads();
;   }
; __device__ void phase_merge4(CParams& p, int l, int tm, int tn, char* smem) {
;     ...
;     gemm_mainloop<4>(p.hbuf + (size_t)row0 * DM, DM,
;                      p.WgT + (((size_t)l * 4 + kb) * 1024 + col0) * 1024, 1024, 1024, sA, sB, acc, tid2);
	s_add_u32 m0, s56, 0x0
	s_nop 0
	global_load_lds_dwordx4 v244, s[26:27]
	s_add_u32 m0, s56, 0x400
	s_nop 0
	global_load_lds_dwordx4 v245, s[26:27]
	s_add_u32 m0, s56, 0x800
	s_nop 0
	global_load_lds_dwordx4 v246, s[26:27]
	s_add_u32 m0, s56, 0xc00
	s_nop 0
	global_load_lds_dwordx4 v247, s[26:27]
	s_add_u32 s26, s26, 128
	s_addc_u32 s27, s27, 0
	v_mfma_f32_16x16x32_bf16 v[0:3], v[216:219], v[200:203], v[0:3]
	ds_read_b128 v[168:171], v248 offset:32768
	v_mfma_f32_16x16x32_bf16 v[4:7], v[220:223], v[200:203], v[4:7]
	ds_read_b128 v[184:187], v250 offset:49152
	v_mfma_f32_16x16x32_bf16 v[8:11], v[228:231], v[200:203], v[8:11]
	ds_read_b128 v[172:175], v248 offset:34816
	v_mfma_f32_16x16x32_bf16 v[12:15], v[232:235], v[200:203], v[12:15]
	ds_read_b128 v[188:191], v250 offset:49664
	v_mfma_f32_16x16x32_bf16 v[16:19], v[216:219], v[204:207], v[16:19]
	ds_read_b128 v[176:179], v248 offset:36864
	v_mfma_f32_16x16x32_bf16 v[20:23], v[220:223], v[204:207], v[20:23]
	ds_read_b128 v[192:195], v250 offset:50176
	v_mfma_f32_16x16x32_bf16 v[24:27], v[228:231], v[204:207], v[24:27]
	ds_read_b128 v[180:183], v248 offset:38912
	v_mfma_f32_16x16x32_bf16 v[28:31], v[232:235], v[204:207], v[28:31]
	ds_read_b128 v[196:199], v250 offset:50688
	v_mfma_f32_16x16x32_bf16 v[32:35], v[216:219], v[208:211], v[32:35]
	v_mfma_f32_16x16x32_bf16 v[36:39], v[220:223], v[208:211], v[36:39]
	v_mfma_f32_16x16x32_bf16 v[40:43], v[228:231], v[208:211], v[40:43]
	v_mfma_f32_16x16x32_bf16 v[44:47], v[232:235], v[208:211], v[44:47]
	v_mfma_f32_16x16x32_bf16 v[48:51], v[216:219], v[212:215], v[48:51]
	v_mfma_f32_16x16x32_bf16 v[52:55], v[220:223], v[212:215], v[52:55]
	v_mfma_f32_16x16x32_bf16 v[56:59], v[228:231], v[212:215], v[56:59]
	v_mfma_f32_16x16x32_bf16 v[60:63], v[232:235], v[212:215], v[60:63]
	s_waitcnt lgkmcnt(0)
	s_add_u32 m0, s56, 0x4000
	s_nop 0
	global_load_lds_dwordx4 v236, s[24:25]
	s_add_u32 m0, s56, 0x4400
	s_nop 0
	global_load_lds_dwordx4 v237, s[24:25]
	s_add_u32 m0, s56, 0x4800
	s_nop 0
	global_load_lds_dwordx4 v238, s[24:25]
	s_add_u32 m0, s56, 0x4c00
	s_nop 0
	global_load_lds_dwordx4 v239, s[24:25]
	s_add_u32 s24, s24, 128
	s_addc_u32 s25, s25, 0
	v_mfma_f32_16x16x32_bf16 v[0:3], v[184:187], v[168:171], v[0:3]
	ds_read_b128 v[200:203], v249 offset:32768
	v_mfma_f32_16x16x32_bf16 v[4:7], v[188:191], v[168:171], v[4:7]
	ds_read_b128 v[216:219], v251 offset:49152
	v_mfma_f32_16x16x32_bf16 v[8:11], v[192:195], v[168:171], v[8:11]
	ds_read_b128 v[204:207], v249 offset:34816
	v_mfma_f32_16x16x32_bf16 v[12:15], v[196:199], v[168:171], v[12:15]
	ds_read_b128 v[220:223], v251 offset:49664
	v_mfma_f32_16x16x32_bf16 v[16:19], v[184:187], v[172:175], v[16:19]
	ds_read_b128 v[208:211], v249 offset:36864
	v_mfma_f32_16x16x32_bf16 v[20:23], v[188:191], v[172:175], v[20:23]
	ds_read_b128 v[228:231], v251 offset:50176
	v_mfma_f32_16x16x32_bf16 v[24:27], v[192:195], v[172:175], v[24:27]
	ds_read_b128 v[212:215], v249 offset:38912
	v_mfma_f32_16x16x32_bf16 v[28:31], v[196:199], v[172:175], v[28:31]
	ds_read_b128 v[232:235], v251 offset:50688
	v_mfma_f32_16x16x32_bf16 v[32:35], v[184:187], v[176:179], v[32:35]
	v_mfma_f32_16x16x32_bf16 v[36:39], v[188:191], v[176:179], v[36:39]
	v_mfma_f32_16x16x32_bf16 v[40:43], v[192:195], v[176:179], v[40:43]
	v_mfma_f32_16x16x32_bf16 v[44:47], v[196:199], v[176:179], v[44:47]
	v_mfma_f32_16x16x32_bf16 v[48:51], v[184:187], v[180:183], v[48:51]
	v_mfma_f32_16x16x32_bf16 v[52:55], v[188:191], v[180:183], v[52:55]
	v_mfma_f32_16x16x32_bf16 v[56:59], v[192:195], v[180:183], v[56:59]
	v_mfma_f32_16x16x32_bf16 v[60:63], v[196:199], v[180:183], v[60:63]
	s_waitcnt vmcnt(4) lgkmcnt(0)
	s_barrier
	s_add_u32 m0, s56, 0x8000
	s_nop 0
	global_load_lds_dwordx4 v244, s[26:27]
	s_add_u32 m0, s56, 0x8400
	s_nop 0
	global_load_lds_dwordx4 v245, s[26:27]
	s_add_u32 m0, s56, 0x8800
	s_nop 0
	global_load_lds_dwordx4 v246, s[26:27]
	s_add_u32 m0, s56, 0x8c00
	s_nop 0
	global_load_lds_dwordx4 v247, s[26:27]
	s_add_u32 s26, s26, 128
	s_addc_u32 s27, s27, 0
	v_mfma_f32_16x16x32_bf16 v[0:3], v[216:219], v[200:203], v[0:3]
	ds_read_b128 v[168:171], v166 offset:49152
	v_mfma_f32_16x16x32_bf16 v[4:7], v[220:223], v[200:203], v[4:7]
	ds_read_b128 v[184:187], v250 offset:0
	v_mfma_f32_16x16x32_bf16 v[8:11], v[228:231], v[200:203], v[8:11]
	ds_read_b128 v[172:175], v166 offset:51200
	v_mfma_f32_16x16x32_bf16 v[12:15], v[232:235], v[200:203], v[12:15]
	ds_read_b128 v[188:191], v250 offset:512
	v_mfma_f32_16x16x32_bf16 v[16:19], v[216:219], v[204:207], v[16:19]
	ds_read_b128 v[176:179], v166 offset:53248
	v_mfma_f32_16x16x32_bf16 v[20:23], v[220:223], v[204:207], v[20:23]
	ds_read_b128 v[192:195], v250 offset:1024
	v_mfma_f32_16x16x32_bf16 v[24:27], v[228:231], v[204:207], v[24:27]
	ds_read_b128 v[180:183], v166 offset:55296
	v_mfma_f32_16x16x32_bf16 v[28:31], v[232:235], v[204:207], v[28:31]
	ds_read_b128 v[196:199], v250 offset:1536
	v_mfma_f32_16x16x32_bf16 v[32:35], v[216:219], v[208:211], v[32:35]
	v_mfma_f32_16x16x32_bf16 v[36:39], v[220:223], v[208:211], v[36:39]
	v_mfma_f32_16x16x32_bf16 v[40:43], v[228:231], v[208:211], v[40:43]
	v_mfma_f32_16x16x32_bf16 v[44:47], v[232:235], v[208:211], v[44:47]
	v_mfma_f32_16x16x32_bf16 v[48:51], v[216:219], v[212:215], v[48:51]
	v_mfma_f32_16x16x32_bf16 v[52:55], v[220:223], v[212:215], v[52:55]
	v_mfma_f32_16x16x32_bf16 v[56:59], v[228:231], v[212:215], v[56:59]
	v_mfma_f32_16x16x32_bf16 v[60:63], v[232:235], v[212:215], v[60:63]
	s_waitcnt lgkmcnt(0)
; template <int NI> ...
;     ...
;   for (int kt = 0; kt < nk; kt += 2) {
;     G_LOAD(a0, b0, min((kt + 2) * 32, klast));
;     G_COMPUTE(0);
;     G_WRITE(a1, b1, 1);
;     __syncthreads();
;     G_LOAD(a1, b1, min((kt + 3) * 32, klast));
;     G_COMPUTE(1);
;     G_WRITE(a0, b0, 0);
;     __syncthreads();
;   }
; __device__ void phase_merge4(CParams& p, int l, int tm, int tn, char* smem) {
;     ...
;     gemm_mainloop<4>(p.hbuf + (size_t)row0 * DM, DM,
;                      p.WgT + (((size_t)l * 4 + kb) * 1024 + col0) * 1024, 1024, 1024, sA, sB, acc, tid2);
	s_add_u32 m0, s56, 0xc000
	s_nop 0
	global_load_lds_dwordx4 v236, s[24:25]
	s_add_u32 m0, s56, 0xc400
	s_nop 0
	global_load_lds_dwordx4 v237, s[24:25]
	s_add_u32 m0, s56, 0xc800
	s_nop 0
	global_load_lds_dwordx4 v238, s[24:25]
	s_add_u32 m0, s56, 0xcc00
	s_nop 0
	global_load_lds_dwordx4 v239, s[24:25]
	s_add_u32 s24, s24, 128
	s_addc_u32 s25, s25, 0
	v_mfma_f32_16x16x32_bf16 v[0:3], v[184:187], v[168:171], v[0:3]
	ds_read_b128 v[200:203], v167 offset:49152
	v_mfma_f32_16x16x32_bf16 v[4:7], v[188:191], v[168:171], v[4:7]
	ds_read_b128 v[216:219], v251 offset:0
	v_mfma_f32_16x16x32_bf16 v[8:11], v[192:195], v[168:171], v[8:11]
	ds_read_b128 v[204:207], v167 offset:51200
	v_mfma_f32_16x16x32_bf16 v[12:15], v[196:199], v[168:171], v[12:15]
	ds_read_b128 v[220:223], v251 offset:512
	v_mfma_f32_16x16x32_bf16 v[16:19], v[184:187], v[172:175], v[16:19]
	ds_read_b128 v[208:211], v167 offset:53248
	v_mfma_f32_16x16x32_bf16 v[20:23], v[188:191], v[172:175], v[20:23]
	ds_read_b128 v[228:231], v251 offset:1024
	v_mfma_f32_16x16x32_bf16 v[24:27], v[192:195], v[172:175], v[24:27]
	ds_read_b128 v[212:215], v167 offset:55296
	v_mfma_f32_16x16x32_bf16 v[28:31], v[196:199], v[172:175], v[28:31]
	ds_read_b128 v[232:235], v251 offset:1536
	v_mfma_f32_16x16x32_bf16 v[32:35], v[184:187], v[176:179], v[32:35]
	v_mfma_f32_16x16x32_bf16 v[36:39], v[188:191], v[176:179], v[36:39]
	v_mfma_f32_16x16x32_bf16 v[40:43], v[192:195], v[176:179], v[40:43]
	v_mfma_f32_16x16x32_bf16 v[44:47], v[196:199], v[176:179], v[44:47]
	v_mfma_f32_16x16x32_bf16 v[48:51], v[184:187], v[180:183], v[48:51]
	v_mfma_f32_16x16x32_bf16 v[52:55], v[188:191], v[180:183], v[52:55]
	v_mfma_f32_16x16x32_bf16 v[56:59], v[192:195], v[180:183], v[56:59]
	v_mfma_f32_16x16x32_bf16 v[60:63], v[196:199], v[180:183], v[60:63]
	s_waitcnt vmcnt(4) lgkmcnt(0)
	s_barrier
	s_add_u32 m0, s56, 0x10000
	s_nop 0
	global_load_lds_dwordx4 v244, s[26:27]
	s_add_u32 m0, s56, 0x10400
	s_nop 0
	global_load_lds_dwordx4 v245, s[26:27]
	s_add_u32 m0, s56, 0x10800
	s_nop 0
	global_load_lds_dwordx4 v246, s[26:27]
	s_add_u32 m0, s56, 0x10c00
	s_nop 0
	global_load_lds_dwordx4 v247, s[26:27]
	s_add_u32 s26, s26, 128
	s_addc_u32 s27, s27, 0
	v_mfma_f32_16x16x32_bf16 v[0:3], v[216:219], v[200:203], v[0:3]
	ds_read_b128 v[168:171], v248 offset:16384
	v_mfma_f32_16x16x32_bf16 v[4:7], v[220:223], v[200:203], v[4:7]
	ds_read_b128 v[184:187], v250 offset:32768
	v_mfma_f32_16x16x32_bf16 v[8:11], v[228:231], v[200:203], v[8:11]
	ds_read_b128 v[172:175], v248 offset:18432
	v_mfma_f32_16x16x32_bf16 v[12:15], v[232:235], v[200:203], v[12:15]
	ds_read_b128 v[188:191], v250 offset:33280
	v_mfma_f32_16x16x32_bf16 v[16:19], v[216:219], v[204:207], v[16:19]
	ds_read_b128 v[176:179], v248 offset:20480
	v_mfma_f32_16x16x32_bf16 v[20:23], v[220:223], v[204:207], v[20:23]
	ds_read_b128 v[192:195], v250 offset:33792
	v_mfma_f32_16x16x32_bf16 v[24:27], v[228:231], v[204:207], v[24:27]
	ds_read_b128 v[180:183], v248 offset:22528
	v_mfma_f32_16x16x32_bf16 v[28:31], v[232:235], v[204:207], v[28:31]
	ds_read_b128 v[196:199], v250 offset:34304
	v_mfma_f32_16x16x32_bf16 v[32:35], v[216:219], v[208:211], v[32:35]
	v_mfma_f32_16x16x32_bf16 v[36:39], v[220:223], v[208:211], v[36:39]
	v_mfma_f32_16x16x32_bf16 v[40:43], v[228:231], v[208:211], v[40:43]
	v_mfma_f32_16x16x32_bf16 v[44:47], v[232:235], v[208:211], v[44:47]
	v_mfma_f32_16x16x32_bf16 v[48:51], v[216:219], v[212:215], v[48:51]
	v_mfma_f32_16x16x32_bf16 v[52:55], v[220:223], v[212:215], v[52:55]
	v_mfma_f32_16x16x32_bf16 v[56:59], v[228:231], v[212:215], v[56:59]
	v_mfma_f32_16x16x32_bf16 v[60:63], v[232:235], v[212:215], v[60:63]
	s_waitcnt lgkmcnt(0)
	s_add_u32 m0, s56, 0x0
	s_nop 0
	global_load_lds_dwordx4 v236, s[24:25]
	s_add_u32 m0, s56, 0x400
	s_nop 0
	global_load_lds_dwordx4 v237, s[24:25]
	s_add_u32 m0, s56, 0x800
	s_nop 0
	global_load_lds_dwordx4 v238, s[24:25]
	s_add_u32 m0, s56, 0xc00
	s_nop 0
	global_load_lds_dwordx4 v239, s[24:25]
	s_add_u32 s24, s24, 128
	s_addc_u32 s25, s25, 0
	v_mfma_f32_16x16x32_bf16 v[0:3], v[184:187], v[168:171], v[0:3]
	ds_read_b128 v[200:203], v249 offset:16384
	v_mfma_f32_16x16x32_bf16 v[4:7], v[188:191], v[168:171], v[4:7]
	ds_read_b128 v[216:219], v251 offset:32768
	v_mfma_f32_16x16x32_bf16 v[8:11], v[192:195], v[168:171], v[8:11]
	ds_read_b128 v[204:207], v249 offset:18432
	v_mfma_f32_16x16x32_bf16 v[12:15], v[196:199], v[168:171], v[12:15]
	ds_read_b128 v[220:223], v251 offset:33280
	v_mfma_f32_16x16x32_bf16 v[16:19], v[184:187], v[172:175], v[16:19]
	ds_read_b128 v[208:211], v249 offset:20480
	v_mfma_f32_16x16x32_bf16 v[20:23], v[188:191], v[172:175], v[20:23]
	ds_read_b128 v[228:231], v251 offset:33792
	v_mfma_f32_16x16x32_bf16 v[24:27], v[192:195], v[172:175], v[24:27]
	ds_read_b128 v[212:215], v249 offset:22528
	v_mfma_f32_16x16x32_bf16 v[28:31], v[196:199], v[172:175], v[28:31]
	ds_read_b128 v[232:235], v251 offset:34304
	v_mfma_f32_16x16x32_bf16 v[32:35], v[184:187], v[176:179], v[32:35]
	v_mfma_f32_16x16x32_bf16 v[36:39], v[188:191], v[176:179], v[36:39]
	v_mfma_f32_16x16x32_bf16 v[40:43], v[192:195], v[176:179], v[40:43]
	v_mfma_f32_16x16x32_bf16 v[44:47], v[196:199], v[176:179], v[44:47]
	v_mfma_f32_16x16x32_bf16 v[48:51], v[184:187], v[180:183], v[48:51]
	v_mfma_f32_16x16x32_bf16 v[52:55], v[188:191], v[180:183], v[52:55]
	v_mfma_f32_16x16x32_bf16 v[56:59], v[192:195], v[180:183], v[56:59]
	v_mfma_f32_16x16x32_bf16 v[60:63], v[196:199], v[180:183], v[60:63]
	s_waitcnt vmcnt(4) lgkmcnt(0)
	s_barrier
; template <int NI> ...
;     ...
;   for (int kt = 0; kt < nk; kt += 2) {
;     G_LOAD(a0, b0, min((kt + 2) * 32, klast));
;     G_COMPUTE(0);
;     G_WRITE(a1, b1, 1);
;     __syncthreads();
;     G_LOAD(a1, b1, min((kt + 3) * 32, klast));
;     G_COMPUTE(1);
;     G_WRITE(a0, b0, 0);
;     __syncthreads();
;   }
; __device__ void phase_merge4(CParams& p, int l, int tm, int tn, char* smem) {
;     ...
;     gemm_mainloop<4>(p.hbuf + (size_t)row0 * DM, DM,
;                      p.WgT + (((size_t)l * 4 + kb) * 1024 + col0) * 1024, 1024, 1024, sA, sB, acc, tid2);
	s_add_u32 m0, s56, 0x4000
	s_nop 0
	global_load_lds_dwordx4 v244, s[26:27]
	s_add_u32 m0, s56, 0x4400
	s_nop 0
	global_load_lds_dwordx4 v245, s[26:27]
	s_add_u32 m0, s56, 0x4800
	s_nop 0
	global_load_lds_dwordx4 v246, s[26:27]
	s_add_u32 m0, s56, 0x4c00
	s_nop 0
	global_load_lds_dwordx4 v247, s[26:27]
	s_add_u32 s26, s26, 128
	s_addc_u32 s27, s27, 0
	v_mfma_f32_16x16x32_bf16 v[0:3], v[216:219], v[200:203], v[0:3]
	ds_read_b128 v[168:171], v248 offset:49152
	v_mfma_f32_16x16x32_bf16 v[4:7], v[220:223], v[200:203], v[4:7]
	ds_read_b128 v[184:187], v226 offset:49152
	v_mfma_f32_16x16x32_bf16 v[8:11], v[228:231], v[200:203], v[8:11]
	ds_read_b128 v[172:175], v248 offset:51200
	v_mfma_f32_16x16x32_bf16 v[12:15], v[232:235], v[200:203], v[12:15]
	ds_read_b128 v[188:191], v226 offset:49664
	v_mfma_f32_16x16x32_bf16 v[16:19], v[216:219], v[204:207], v[16:19]
	ds_read_b128 v[176:179], v248 offset:53248
	v_mfma_f32_16x16x32_bf16 v[20:23], v[220:223], v[204:207], v[20:23]
	ds_read_b128 v[192:195], v226 offset:50176
	v_mfma_f32_16x16x32_bf16 v[24:27], v[228:231], v[204:207], v[24:27]
	ds_read_b128 v[180:183], v248 offset:55296
	v_mfma_f32_16x16x32_bf16 v[28:31], v[232:235], v[204:207], v[28:31]
	ds_read_b128 v[196:199], v226 offset:50688
	v_mfma_f32_16x16x32_bf16 v[32:35], v[216:219], v[208:211], v[32:35]
	v_mfma_f32_16x16x32_bf16 v[36:39], v[220:223], v[208:211], v[36:39]
	v_mfma_f32_16x16x32_bf16 v[40:43], v[228:231], v[208:211], v[40:43]
	v_mfma_f32_16x16x32_bf16 v[44:47], v[232:235], v[208:211], v[44:47]
	v_mfma_f32_16x16x32_bf16 v[48:51], v[216:219], v[212:215], v[48:51]
	v_mfma_f32_16x16x32_bf16 v[52:55], v[220:223], v[212:215], v[52:55]
	v_mfma_f32_16x16x32_bf16 v[56:59], v[228:231], v[212:215], v[56:59]
	v_mfma_f32_16x16x32_bf16 v[60:63], v[232:235], v[212:215], v[60:63]
	s_waitcnt lgkmcnt(0)
	s_add_u32 m0, s56, 0x8000
	s_nop 0
	global_load_lds_dwordx4 v236, s[24:25]
	s_add_u32 m0, s56, 0x8400
	s_nop 0
	global_load_lds_dwordx4 v237, s[24:25]
	s_add_u32 m0, s56, 0x8800
	s_nop 0
	global_load_lds_dwordx4 v238, s[24:25]
	s_add_u32 m0, s56, 0x8c00
	s_nop 0
	global_load_lds_dwordx4 v239, s[24:25]
	s_add_u32 s24, s24, 128
	s_addc_u32 s25, s25, 0
	v_mfma_f32_16x16x32_bf16 v[0:3], v[184:187], v[168:171], v[0:3]
	ds_read_b128 v[200:203], v249 offset:49152
	v_mfma_f32_16x16x32_bf16 v[4:7], v[188:191], v[168:171], v[4:7]
	ds_read_b128 v[216:219], v227 offset:49152
	v_mfma_f32_16x16x32_bf16 v[8:11], v[192:195], v[168:171], v[8:11]
	ds_read_b128 v[204:207], v249 offset:51200
	v_mfma_f32_16x16x32_bf16 v[12:15], v[196:199], v[168:171], v[12:15]
	ds_read_b128 v[220:223], v227 offset:49664
	v_mfma_f32_16x16x32_bf16 v[16:19], v[184:187], v[172:175], v[16:19]
	ds_read_b128 v[208:211], v249 offset:53248
	v_mfma_f32_16x16x32_bf16 v[20:23], v[188:191], v[172:175], v[20:23]
	ds_read_b128 v[228:231], v227 offset:50176
	v_mfma_f32_16x16x32_bf16 v[24:27], v[192:195], v[172:175], v[24:27]
	ds_read_b128 v[212:215], v249 offset:55296
	v_mfma_f32_16x16x32_bf16 v[28:31], v[196:199], v[172:175], v[28:31]
	ds_read_b128 v[232:235], v227 offset:50688
	v_mfma_f32_16x16x32_bf16 v[32:35], v[184:187], v[176:179], v[32:35]
	v_mfma_f32_16x16x32_bf16 v[36:39], v[188:191], v[176:179], v[36:39]
	v_mfma_f32_16x16x32_bf16 v[40:43], v[192:195], v[176:179], v[40:43]
	v_mfma_f32_16x16x32_bf16 v[44:47], v[196:199], v[176:179], v[44:47]
	v_mfma_f32_16x16x32_bf16 v[48:51], v[184:187], v[180:183], v[48:51]
	v_mfma_f32_16x16x32_bf16 v[52:55], v[188:191], v[180:183], v[52:55]
	v_mfma_f32_16x16x32_bf16 v[56:59], v[192:195], v[180:183], v[56:59]
	v_mfma_f32_16x16x32_bf16 v[60:63], v[196:199], v[180:183], v[60:63]
	s_waitcnt vmcnt(4) lgkmcnt(0)
	s_barrier
	s_add_u32 m0, s56, 0xc000
	s_nop 0
	global_load_lds_dwordx4 v244, s[26:27]
	s_add_u32 m0, s56, 0xc400
	s_nop 0
	global_load_lds_dwordx4 v245, s[26:27]
	s_add_u32 m0, s56, 0xc800
	s_nop 0
	global_load_lds_dwordx4 v246, s[26:27]
	s_add_u32 m0, s56, 0xcc00
	s_nop 0
	global_load_lds_dwordx4 v247, s[26:27]
	s_add_u32 s26, s26, 128
	s_addc_u32 s27, s27, 0
	v_mfma_f32_16x16x32_bf16 v[0:3], v[216:219], v[200:203], v[0:3]
	ds_read_b128 v[168:171], v248 offset:0
	v_mfma_f32_16x16x32_bf16 v[4:7], v[220:223], v[200:203], v[4:7]
	ds_read_b128 v[184:187], v250 offset:16384
	v_mfma_f32_16x16x32_bf16 v[8:11], v[228:231], v[200:203], v[8:11]
	ds_read_b128 v[172:175], v248 offset:2048
	v_mfma_f32_16x16x32_bf16 v[12:15], v[232:235], v[200:203], v[12:15]
	ds_read_b128 v[188:191], v250 offset:16896
	v_mfma_f32_16x16x32_bf16 v[16:19], v[216:219], v[204:207], v[16:19]
	ds_read_b128 v[176:179], v248 offset:4096
	v_mfma_f32_16x16x32_bf16 v[20:23], v[220:223], v[204:207], v[20:23]
	ds_read_b128 v[192:195], v250 offset:17408
	v_mfma_f32_16x16x32_bf16 v[24:27], v[228:231], v[204:207], v[24:27]
	ds_read_b128 v[180:183], v248 offset:6144
	v_mfma_f32_16x16x32_bf16 v[28:31], v[232:235], v[204:207], v[28:31]
	ds_read_b128 v[196:199], v250 offset:17920
	v_mfma_f32_16x16x32_bf16 v[32:35], v[216:219], v[208:211], v[32:35]
	v_mfma_f32_16x16x32_bf16 v[36:39], v[220:223], v[208:211], v[36:39]
	v_mfma_f32_16x16x32_bf16 v[40:43], v[228:231], v[208:211], v[40:43]
	v_mfma_f32_16x16x32_bf16 v[44:47], v[232:235], v[208:211], v[44:47]
	v_mfma_f32_16x16x32_bf16 v[48:51], v[216:219], v[212:215], v[48:51]
	v_mfma_f32_16x16x32_bf16 v[52:55], v[220:223], v[212:215], v[52:55]
	v_mfma_f32_16x16x32_bf16 v[56:59], v[228:231], v[212:215], v[56:59]
	v_mfma_f32_16x16x32_bf16 v[60:63], v[232:235], v[212:215], v[60:63]
	s_waitcnt lgkmcnt(0)
; template <int NI> ...
;     ...
;   for (int kt = 0; kt < nk; kt += 2) {
;     G_LOAD(a0, b0, min((kt + 2) * 32, klast));
;     G_COMPUTE(0);
;     G_WRITE(a1, b1, 1);
;     __syncthreads();
;     G_LOAD(a1, b1, min((kt + 3) * 32, klast));
;     G_COMPUTE(1);
;     G_WRITE(a0, b0, 0);
;     __syncthreads();
;   }
; __device__ void phase_merge4(CParams& p, int l, int tm, int tn, char* smem) {
;     ...
;     gemm_mainloop<4>(p.hbuf + (size_t)row0 * DM, DM,
;                      p.WgT + (((size_t)l * 4 + kb) * 1024 + col0) * 1024, 1024, 1024, sA, sB, acc, tid2);
	s_add_u32 m0, s56, 0x10000
	s_nop 0
	global_load_lds_dwordx4 v236, s[24:25]
	s_add_u32 m0, s56, 0x10400
	s_nop 0
	global_load_lds_dwordx4 v237, s[24:25]
	s_add_u32 m0, s56, 0x10800
	s_nop 0
	global_load_lds_dwordx4 v238, s[24:25]
	s_add_u32 m0, s56, 0x10c00
	s_nop 0
	global_load_lds_dwordx4 v239, s[24:25]
	s_add_u32 s24, s24, 128
	s_addc_u32 s25, s25, 0
	v_mfma_f32_16x16x32_bf16 v[0:3], v[184:187], v[168:171], v[0:3]
	ds_read_b128 v[200:203], v249 offset:0
	v_mfma_f32_16x16x32_bf16 v[4:7], v[188:191], v[168:171], v[4:7]
	ds_read_b128 v[216:219], v251 offset:16384
	v_mfma_f32_16x16x32_bf16 v[8:11], v[192:195], v[168:171], v[8:11]
	ds_read_b128 v[204:207], v249 offset:2048
	v_mfma_f32_16x16x32_bf16 v[12:15], v[196:199], v[168:171], v[12:15]
	ds_read_b128 v[220:223], v251 offset:16896
	v_mfma_f32_16x16x32_bf16 v[16:19], v[184:187], v[172:175], v[16:19]
	ds_read_b128 v[208:211], v249 offset:4096
	v_mfma_f32_16x16x32_bf16 v[20:23], v[188:191], v[172:175], v[20:23]
	ds_read_b128 v[228:231], v251 offset:17408
	v_mfma_f32_16x16x32_bf16 v[24:27], v[192:195], v[172:175], v[24:27]
	ds_read_b128 v[212:215], v249 offset:6144
	v_mfma_f32_16x16x32_bf16 v[28:31], v[196:199], v[172:175], v[28:31]
	ds_read_b128 v[232:235], v251 offset:17920
	v_mfma_f32_16x16x32_bf16 v[32:35], v[184:187], v[176:179], v[32:35]
	v_mfma_f32_16x16x32_bf16 v[36:39], v[188:191], v[176:179], v[36:39]
	v_mfma_f32_16x16x32_bf16 v[40:43], v[192:195], v[176:179], v[40:43]
	v_mfma_f32_16x16x32_bf16 v[44:47], v[196:199], v[176:179], v[44:47]
	v_mfma_f32_16x16x32_bf16 v[48:51], v[184:187], v[180:183], v[48:51]
	v_mfma_f32_16x16x32_bf16 v[52:55], v[188:191], v[180:183], v[52:55]
	v_mfma_f32_16x16x32_bf16 v[56:59], v[192:195], v[180:183], v[56:59]
	v_mfma_f32_16x16x32_bf16 v[60:63], v[196:199], v[180:183], v[60:63]
	s_waitcnt vmcnt(4) lgkmcnt(0)
	s_barrier
	s_add_u32 m0, s56, 0x0
	s_nop 0
	global_load_lds_dwordx4 v244, s[26:27]
	s_add_u32 m0, s56, 0x400
	s_nop 0
	global_load_lds_dwordx4 v245, s[26:27]
	s_add_u32 m0, s56, 0x800
	s_nop 0
	global_load_lds_dwordx4 v246, s[26:27]
	s_add_u32 m0, s56, 0xc00
	s_nop 0
	global_load_lds_dwordx4 v247, s[26:27]
	s_add_u32 s26, s26, 128
	s_addc_u32 s27, s27, 0
	v_mfma_f32_16x16x32_bf16 v[0:3], v[216:219], v[200:203], v[0:3]
	ds_read_b128 v[168:171], v248 offset:32768
	v_mfma_f32_16x16x32_bf16 v[4:7], v[220:223], v[200:203], v[4:7]
	ds_read_b128 v[184:187], v250 offset:49152
	v_mfma_f32_16x16x32_bf16 v[8:11], v[228:231], v[200:203], v[8:11]
	ds_read_b128 v[172:175], v248 offset:34816
	v_mfma_f32_16x16x32_bf16 v[12:15], v[232:235], v[200:203], v[12:15]
	ds_read_b128 v[188:191], v250 offset:49664
	v_mfma_f32_16x16x32_bf16 v[16:19], v[216:219], v[204:207], v[16:19]
	ds_read_b128 v[176:179], v248 offset:36864
	v_mfma_f32_16x16x32_bf16 v[20:23], v[220:223], v[204:207], v[20:23]
	ds_read_b128 v[192:195], v250 offset:50176
	v_mfma_f32_16x16x32_bf16 v[24:27], v[228:231], v[204:207], v[24:27]
	ds_read_b128 v[180:183], v248 offset:38912
	v_mfma_f32_16x16x32_bf16 v[28:31], v[232:235], v[204:207], v[28:31]
	ds_read_b128 v[196:199], v250 offset:50688
	v_mfma_f32_16x16x32_bf16 v[32:35], v[216:219], v[208:211], v[32:35]
	v_mfma_f32_16x16x32_bf16 v[36:39], v[220:223], v[208:211], v[36:39]
	v_mfma_f32_16x16x32_bf16 v[40:43], v[228:231], v[208:211], v[40:43]
	v_mfma_f32_16x16x32_bf16 v[44:47], v[232:235], v[208:211], v[44:47]
	v_mfma_f32_16x16x32_bf16 v[48:51], v[216:219], v[212:215], v[48:51]
	v_mfma_f32_16x16x32_bf16 v[52:55], v[220:223], v[212:215], v[52:55]
	v_mfma_f32_16x16x32_bf16 v[56:59], v[228:231], v[212:215], v[56:59]
	v_mfma_f32_16x16x32_bf16 v[60:63], v[232:235], v[212:215], v[60:63]
	s_waitcnt lgkmcnt(0)
	s_add_u32 m0, s56, 0x4000
	s_nop 0
	global_load_lds_dwordx4 v236, s[24:25]
	s_add_u32 m0, s56, 0x4400
	s_nop 0
	global_load_lds_dwordx4 v237, s[24:25]
	s_add_u32 m0, s56, 0x4800
	s_nop 0
	global_load_lds_dwordx4 v238, s[24:25]
	s_add_u32 m0, s56, 0x4c00
	s_nop 0
	global_load_lds_dwordx4 v239, s[24:25]
	s_add_u32 s24, s24, 128
	s_addc_u32 s25, s25, 0
	v_mfma_f32_16x16x32_bf16 v[0:3], v[184:187], v[168:171], v[0:3]
	ds_read_b128 v[200:203], v249 offset:32768
	v_mfma_f32_16x16x32_bf16 v[4:7], v[188:191], v[168:171], v[4:7]
	ds_read_b128 v[216:219], v251 offset:49152
	v_mfma_f32_16x16x32_bf16 v[8:11], v[192:195], v[168:171], v[8:11]
	ds_read_b128 v[204:207], v249 offset:34816
	v_mfma_f32_16x16x32_bf16 v[12:15], v[196:199], v[168:171], v[12:15]
	ds_read_b128 v[220:223], v251 offset:49664
	v_mfma_f32_16x16x32_bf16 v[16:19], v[184:187], v[172:175], v[16:19]
	ds_read_b128 v[208:211], v249 offset:36864
	v_mfma_f32_16x16x32_bf16 v[20:23], v[188:191], v[172:175], v[20:23]
	ds_read_b128 v[228:231], v251 offset:50176
	v_mfma_f32_16x16x32_bf16 v[24:27], v[192:195], v[172:175], v[24:27]
	ds_read_b128 v[212:215], v249 offset:38912
	v_mfma_f32_16x16x32_bf16 v[28:31], v[196:199], v[172:175], v[28:31]
	ds_read_b128 v[232:235], v251 offset:50688
	v_mfma_f32_16x16x32_bf16 v[32:35], v[184:187], v[176:179], v[32:35]
	v_mfma_f32_16x16x32_bf16 v[36:39], v[188:191], v[176:179], v[36:39]
	v_mfma_f32_16x16x32_bf16 v[40:43], v[192:195], v[176:179], v[40:43]
	v_mfma_f32_16x16x32_bf16 v[44:47], v[196:199], v[176:179], v[44:47]
	v_mfma_f32_16x16x32_bf16 v[48:51], v[184:187], v[180:183], v[48:51]
	v_mfma_f32_16x16x32_bf16 v[52:55], v[188:191], v[180:183], v[52:55]
	v_mfma_f32_16x16x32_bf16 v[56:59], v[192:195], v[180:183], v[56:59]
	v_mfma_f32_16x16x32_bf16 v[60:63], v[196:199], v[180:183], v[60:63]
	s_waitcnt vmcnt(4) lgkmcnt(0)
	s_barrier
; template <int NI> ...
;     ...
;   for (int kt = 0; kt < nk; kt += 2) {
;     G_LOAD(a0, b0, min((kt + 2) * 32, klast));
;     G_COMPUTE(0);
;     G_WRITE(a1, b1, 1);
;     __syncthreads();
;     G_LOAD(a1, b1, min((kt + 3) * 32, klast));
;     G_COMPUTE(1);
;     G_WRITE(a0, b0, 0);
;     __syncthreads();
;   }
; __device__ void phase_merge4(CParams& p, int l, int tm, int tn, char* smem) {
;     ...
;     gemm_mainloop<4>(p.hbuf + (size_t)row0 * DM, DM,
;                      p.WgT + (((size_t)l * 4 + kb) * 1024 + col0) * 1024, 1024, 1024, sA, sB, acc, tid2);
	s_add_u32 m0, s56, 0x8000
	s_nop 0
	global_load_lds_dwordx4 v244, s[26:27]
	s_add_u32 m0, s56, 0x8400
	s_nop 0
	global_load_lds_dwordx4 v245, s[26:27]
	s_add_u32 m0, s56, 0x8800
	s_nop 0
	global_load_lds_dwordx4 v246, s[26:27]
	s_add_u32 m0, s56, 0x8c00
	s_nop 0
	global_load_lds_dwordx4 v247, s[26:27]
	s_add_u32 s26, s26, 128
	s_addc_u32 s27, s27, 0
	v_mfma_f32_16x16x32_bf16 v[0:3], v[216:219], v[200:203], v[0:3]
	ds_read_b128 v[168:171], v166 offset:49152
	v_mfma_f32_16x16x32_bf16 v[4:7], v[220:223], v[200:203], v[4:7]
	ds_read_b128 v[184:187], v250 offset:0
	v_mfma_f32_16x16x32_bf16 v[8:11], v[228:231], v[200:203], v[8:11]
	ds_read_b128 v[172:175], v166 offset:51200
	v_mfma_f32_16x16x32_bf16 v[12:15], v[232:235], v[200:203], v[12:15]
	ds_read_b128 v[188:191], v250 offset:512
	v_mfma_f32_16x16x32_bf16 v[16:19], v[216:219], v[204:207], v[16:19]
	ds_read_b128 v[176:179], v166 offset:53248
	v_mfma_f32_16x16x32_bf16 v[20:23], v[220:223], v[204:207], v[20:23]
	ds_read_b128 v[192:195], v250 offset:1024
	v_mfma_f32_16x16x32_bf16 v[24:27], v[228:231], v[204:207], v[24:27]
	ds_read_b128 v[180:183], v166 offset:55296
	v_mfma_f32_16x16x32_bf16 v[28:31], v[232:235], v[204:207], v[28:31]
	ds_read_b128 v[196:199], v250 offset:1536
	v_mfma_f32_16x16x32_bf16 v[32:35], v[216:219], v[208:211], v[32:35]
	v_mfma_f32_16x16x32_bf16 v[36:39], v[220:223], v[208:211], v[36:39]
	v_mfma_f32_16x16x32_bf16 v[40:43], v[228:231], v[208:211], v[40:43]
	v_mfma_f32_16x16x32_bf16 v[44:47], v[232:235], v[208:211], v[44:47]
	v_mfma_f32_16x16x32_bf16 v[48:51], v[216:219], v[212:215], v[48:51]
	v_mfma_f32_16x16x32_bf16 v[52:55], v[220:223], v[212:215], v[52:55]
	v_mfma_f32_16x16x32_bf16 v[56:59], v[228:231], v[212:215], v[56:59]
	v_mfma_f32_16x16x32_bf16 v[60:63], v[232:235], v[212:215], v[60:63]
	s_waitcnt lgkmcnt(0)
	s_add_u32 m0, s56, 0xc000
	s_nop 0
	global_load_lds_dwordx4 v236, s[24:25]
	s_add_u32 m0, s56, 0xc400
	s_nop 0
	global_load_lds_dwordx4 v237, s[24:25]
	s_add_u32 m0, s56, 0xc800
	s_nop 0
	global_load_lds_dwordx4 v238, s[24:25]
	s_add_u32 m0, s56, 0xcc00
	s_nop 0
	global_load_lds_dwordx4 v239, s[24:25]
	s_add_u32 s24, s24, 128
	s_addc_u32 s25, s25, 0
	v_mfma_f32_16x16x32_bf16 v[0:3], v[184:187], v[168:171], v[0:3]
	ds_read_b128 v[200:203], v167 offset:49152
	v_mfma_f32_16x16x32_bf16 v[4:7], v[188:191], v[168:171], v[4:7]
	ds_read_b128 v[216:219], v251 offset:0
	v_mfma_f32_16x16x32_bf16 v[8:11], v[192:195], v[168:171], v[8:11]
	ds_read_b128 v[204:207], v167 offset:51200
	v_mfma_f32_16x16x32_bf16 v[12:15], v[196:199], v[168:171], v[12:15]
	ds_read_b128 v[220:223], v251 offset:512
	v_mfma_f32_16x16x32_bf16 v[16:19], v[184:187], v[172:175], v[16:19]
	ds_read_b128 v[208:211], v167 offset:53248
	v_mfma_f32_16x16x32_bf16 v[20:23], v[188:191], v[172:175], v[20:23]
	ds_read_b128 v[228:231], v251 offset:1024
	v_mfma_f32_16x16x32_bf16 v[24:27], v[192:195], v[172:175], v[24:27]
	ds_read_b128 v[212:215], v167 offset:55296
	v_mfma_f32_16x16x32_bf16 v[28:31], v[196:199], v[172:175], v[28:31]
	ds_read_b128 v[232:235], v251 offset:1536
	v_mfma_f32_16x16x32_bf16 v[32:35], v[184:187], v[176:179], v[32:35]
	v_mfma_f32_16x16x32_bf16 v[36:39], v[188:191], v[176:179], v[36:39]
	v_mfma_f32_16x16x32_bf16 v[40:43], v[192:195], v[176:179], v[40:43]
	v_mfma_f32_16x16x32_bf16 v[44:47], v[196:199], v[176:179], v[44:47]
	v_mfma_f32_16x16x32_bf16 v[48:51], v[184:187], v[180:183], v[48:51]
	v_mfma_f32_16x16x32_bf16 v[52:55], v[188:191], v[180:183], v[52:55]
	v_mfma_f32_16x16x32_bf16 v[56:59], v[192:195], v[180:183], v[56:59]
	v_mfma_f32_16x16x32_bf16 v[60:63], v[196:199], v[180:183], v[60:63]
	s_waitcnt vmcnt(4) lgkmcnt(0)
	s_barrier
	s_add_u32 m0, s56, 0x10000
	s_nop 0
	global_load_lds_dwordx4 v244, s[26:27]
	s_add_u32 m0, s56, 0x10400
	s_nop 0
	global_load_lds_dwordx4 v245, s[26:27]
	s_add_u32 m0, s56, 0x10800
	s_nop 0
	global_load_lds_dwordx4 v246, s[26:27]
	s_add_u32 m0, s56, 0x10c00
	s_nop 0
	global_load_lds_dwordx4 v247, s[26:27]
	s_add_u32 s26, s26, 128
	s_addc_u32 s27, s27, 0
	v_mfma_f32_16x16x32_bf16 v[0:3], v[216:219], v[200:203], v[0:3]
	ds_read_b128 v[168:171], v248 offset:16384
	v_mfma_f32_16x16x32_bf16 v[4:7], v[220:223], v[200:203], v[4:7]
	ds_read_b128 v[184:187], v250 offset:32768
	v_mfma_f32_16x16x32_bf16 v[8:11], v[228:231], v[200:203], v[8:11]
	ds_read_b128 v[172:175], v248 offset:18432
	v_mfma_f32_16x16x32_bf16 v[12:15], v[232:235], v[200:203], v[12:15]
	ds_read_b128 v[188:191], v250 offset:33280
	v_mfma_f32_16x16x32_bf16 v[16:19], v[216:219], v[204:207], v[16:19]
	ds_read_b128 v[176:179], v248 offset:20480
	v_mfma_f32_16x16x32_bf16 v[20:23], v[220:223], v[204:207], v[20:23]
	ds_read_b128 v[192:195], v250 offset:33792
	v_mfma_f32_16x16x32_bf16 v[24:27], v[228:231], v[204:207], v[24:27]
	ds_read_b128 v[180:183], v248 offset:22528
	v_mfma_f32_16x16x32_bf16 v[28:31], v[232:235], v[204:207], v[28:31]
	ds_read_b128 v[196:199], v250 offset:34304
	v_mfma_f32_16x16x32_bf16 v[32:35], v[216:219], v[208:211], v[32:35]
	v_mfma_f32_16x16x32_bf16 v[36:39], v[220:223], v[208:211], v[36:39]
	v_mfma_f32_16x16x32_bf16 v[40:43], v[228:231], v[208:211], v[40:43]
	v_mfma_f32_16x16x32_bf16 v[44:47], v[232:235], v[208:211], v[44:47]
	v_mfma_f32_16x16x32_bf16 v[48:51], v[216:219], v[212:215], v[48:51]
	v_mfma_f32_16x16x32_bf16 v[52:55], v[220:223], v[212:215], v[52:55]
	v_mfma_f32_16x16x32_bf16 v[56:59], v[228:231], v[212:215], v[56:59]
	v_mfma_f32_16x16x32_bf16 v[60:63], v[232:235], v[212:215], v[60:63]
	s_waitcnt lgkmcnt(0)
; template <int NI> ...
;     ...
;   for (int kt = 0; kt < nk; kt += 2) {
;     G_LOAD(a0, b0, min((kt + 2) * 32, klast));
;     G_COMPUTE(0);
;     G_WRITE(a1, b1, 1);
;     __syncthreads();
;     G_LOAD(a1, b1, min((kt + 3) * 32, klast));
;     G_COMPUTE(1);
;     G_WRITE(a0, b0, 0);
;     __syncthreads();
;   }
; __device__ void phase_merge4(CParams& p, int l, int tm, int tn, char* smem) {
;     ...
;       gemm_mainloop<4>(p.br + (size_t)row0 * 1024 + kb * 256, 1024,
;                        p.WbT + (((size_t)l * 4 + kb) * 1024 + col0) * 256, 256, 256, sA, sB, acc, tid2);
	s_mov_b64 s[24:25], s[28:29]
	s_add_u32 m0, s56, 0x0
	s_nop 0
	global_load_lds_dwordx4 v236, s[24:25]
	s_add_u32 m0, s56, 0x400
	s_nop 0
	global_load_lds_dwordx4 v237, s[24:25]
	s_add_u32 m0, s56, 0x800
	s_nop 0
	global_load_lds_dwordx4 v238, s[24:25]
	s_add_u32 m0, s56, 0xc00
	s_nop 0
	global_load_lds_dwordx4 v239, s[24:25]
	s_add_u32 s24, s24, 128
	s_addc_u32 s25, s25, 0
	v_mfma_f32_16x16x32_bf16 v[0:3], v[184:187], v[168:171], v[0:3]
	ds_read_b128 v[200:203], v249 offset:16384
	v_mfma_f32_16x16x32_bf16 v[4:7], v[188:191], v[168:171], v[4:7]
	ds_read_b128 v[216:219], v251 offset:32768
	v_mfma_f32_16x16x32_bf16 v[8:11], v[192:195], v[168:171], v[8:11]
	ds_read_b128 v[204:207], v249 offset:18432
	v_mfma_f32_16x16x32_bf16 v[12:15], v[196:199], v[168:171], v[12:15]
	ds_read_b128 v[220:223], v251 offset:33280
	v_mfma_f32_16x16x32_bf16 v[16:19], v[184:187], v[172:175], v[16:19]
	ds_read_b128 v[208:211], v249 offset:20480
	v_mfma_f32_16x16x32_bf16 v[20:23], v[188:191], v[172:175], v[20:23]
	ds_read_b128 v[228:231], v251 offset:33792
	v_mfma_f32_16x16x32_bf16 v[24:27], v[192:195], v[172:175], v[24:27]
	ds_read_b128 v[212:215], v249 offset:22528
	v_mfma_f32_16x16x32_bf16 v[28:31], v[196:199], v[172:175], v[28:31]
	ds_read_b128 v[232:235], v251 offset:34304
	v_mfma_f32_16x16x32_bf16 v[32:35], v[184:187], v[176:179], v[32:35]
	v_mfma_f32_16x16x32_bf16 v[36:39], v[188:191], v[176:179], v[36:39]
	v_mfma_f32_16x16x32_bf16 v[40:43], v[192:195], v[176:179], v[40:43]
	v_mfma_f32_16x16x32_bf16 v[44:47], v[196:199], v[176:179], v[44:47]
	v_mfma_f32_16x16x32_bf16 v[48:51], v[184:187], v[180:183], v[48:51]
	v_mfma_f32_16x16x32_bf16 v[52:55], v[188:191], v[180:183], v[52:55]
	v_mfma_f32_16x16x32_bf16 v[56:59], v[192:195], v[180:183], v[56:59]
	v_mfma_f32_16x16x32_bf16 v[60:63], v[196:199], v[180:183], v[60:63]
	s_waitcnt vmcnt(4) lgkmcnt(0)
	s_barrier
	s_mov_b64 s[26:27], s[44:45]
	s_add_u32 m0, s56, 0x4000
	s_nop 0
	global_load_lds_dwordx4 v240, s[26:27]
	s_add_u32 m0, s56, 0x4400
	s_nop 0
	global_load_lds_dwordx4 v241, s[26:27]
	s_add_u32 m0, s56, 0x4800
	s_nop 0
	global_load_lds_dwordx4 v242, s[26:27]
	s_add_u32 m0, s56, 0x4c00
	s_nop 0
	global_load_lds_dwordx4 v243, s[26:27]
	s_add_u32 s26, s26, 128
	s_addc_u32 s27, s27, 0
	v_mfma_f32_16x16x32_bf16 v[0:3], v[216:219], v[200:203], v[0:3]
	ds_read_b128 v[168:171], v248 offset:49152
	v_mfma_f32_16x16x32_bf16 v[4:7], v[220:223], v[200:203], v[4:7]
	ds_read_b128 v[184:187], v226 offset:49152
	v_mfma_f32_16x16x32_bf16 v[8:11], v[228:231], v[200:203], v[8:11]
	ds_read_b128 v[172:175], v248 offset:51200
	v_mfma_f32_16x16x32_bf16 v[12:15], v[232:235], v[200:203], v[12:15]
	ds_read_b128 v[188:191], v226 offset:49664
	v_mfma_f32_16x16x32_bf16 v[16:19], v[216:219], v[204:207], v[16:19]
	ds_read_b128 v[176:179], v248 offset:53248
	v_mfma_f32_16x16x32_bf16 v[20:23], v[220:223], v[204:207], v[20:23]
	ds_read_b128 v[192:195], v226 offset:50176
	v_mfma_f32_16x16x32_bf16 v[24:27], v[228:231], v[204:207], v[24:27]
	ds_read_b128 v[180:183], v248 offset:55296
	v_mfma_f32_16x16x32_bf16 v[28:31], v[232:235], v[204:207], v[28:31]
	ds_read_b128 v[196:199], v226 offset:50688
	v_mfma_f32_16x16x32_bf16 v[32:35], v[216:219], v[208:211], v[32:35]
	v_mfma_f32_16x16x32_bf16 v[36:39], v[220:223], v[208:211], v[36:39]
	v_mfma_f32_16x16x32_bf16 v[40:43], v[228:231], v[208:211], v[40:43]
	v_mfma_f32_16x16x32_bf16 v[44:47], v[232:235], v[208:211], v[44:47]
	v_mfma_f32_16x16x32_bf16 v[48:51], v[216:219], v[212:215], v[48:51]
	v_mfma_f32_16x16x32_bf16 v[52:55], v[220:223], v[212:215], v[52:55]
	v_mfma_f32_16x16x32_bf16 v[56:59], v[228:231], v[212:215], v[56:59]
	v_mfma_f32_16x16x32_bf16 v[60:63], v[232:235], v[212:215], v[60:63]
	s_waitcnt lgkmcnt(0)
	s_add_u32 m0, s56, 0x8000
	s_nop 0
	global_load_lds_dwordx4 v236, s[24:25]
	s_add_u32 m0, s56, 0x8400
	s_nop 0
	global_load_lds_dwordx4 v237, s[24:25]
	s_add_u32 m0, s56, 0x8800
	s_nop 0
	global_load_lds_dwordx4 v238, s[24:25]
	s_add_u32 m0, s56, 0x8c00
	s_nop 0
	global_load_lds_dwordx4 v239, s[24:25]
	s_add_u32 s24, s24, 128
	s_addc_u32 s25, s25, 0
	v_mfma_f32_16x16x32_bf16 v[0:3], v[184:187], v[168:171], v[0:3]
	ds_read_b128 v[200:203], v249 offset:49152
	v_mfma_f32_16x16x32_bf16 v[4:7], v[188:191], v[168:171], v[4:7]
	ds_read_b128 v[216:219], v227 offset:49152
	v_mfma_f32_16x16x32_bf16 v[8:11], v[192:195], v[168:171], v[8:11]
	ds_read_b128 v[204:207], v249 offset:51200
	v_mfma_f32_16x16x32_bf16 v[12:15], v[196:199], v[168:171], v[12:15]
	ds_read_b128 v[220:223], v227 offset:49664
	v_mfma_f32_16x16x32_bf16 v[16:19], v[184:187], v[172:175], v[16:19]
	ds_read_b128 v[208:211], v249 offset:53248
	v_mfma_f32_16x16x32_bf16 v[20:23], v[188:191], v[172:175], v[20:23]
	ds_read_b128 v[228:231], v227 offset:50176
	v_mfma_f32_16x16x32_bf16 v[24:27], v[192:195], v[172:175], v[24:27]
	ds_read_b128 v[212:215], v249 offset:55296
	v_mfma_f32_16x16x32_bf16 v[28:31], v[196:199], v[172:175], v[28:31]
	ds_read_b128 v[232:235], v227 offset:50688
	v_mfma_f32_16x16x32_bf16 v[32:35], v[184:187], v[176:179], v[32:35]
	v_mfma_f32_16x16x32_bf16 v[36:39], v[188:191], v[176:179], v[36:39]
	v_mfma_f32_16x16x32_bf16 v[40:43], v[192:195], v[176:179], v[40:43]
	v_mfma_f32_16x16x32_bf16 v[44:47], v[196:199], v[176:179], v[44:47]
	v_mfma_f32_16x16x32_bf16 v[48:51], v[184:187], v[180:183], v[48:51]
	v_mfma_f32_16x16x32_bf16 v[52:55], v[188:191], v[180:183], v[52:55]
	v_mfma_f32_16x16x32_bf16 v[56:59], v[192:195], v[180:183], v[56:59]
	v_mfma_f32_16x16x32_bf16 v[60:63], v[196:199], v[180:183], v[60:63]
	s_waitcnt vmcnt(4) lgkmcnt(0)
	s_barrier
; __device__ __forceinline__ float sigmoidf_(float v) { return 1.f / (1.f + __expf(-v)); }
; __device__ void phase_merge4(CParams& p, int l, int tm, int tn, char* smem) {
;     ...
; #pragma unroll
;     for (int mi = 0; mi < 4; mi++)
; #pragma unroll
;       for (int ni = 0; ni < 4; ni++) {
;         unsigned p0 = pk[mi][ni][0], p1 = pk[mi][ni][1], m0 = mer[mi][ni][0], m1 = mer[mi][ni][1];
;         float r0 = __uint_as_float(m0 << 16) + sigmoidf_(acc[mi][ni][0]) * __uint_as_float(p0 << 16);
;         float r1 = __uint_as_float(m0 & 0xffff0000u) + sigmoidf_(acc[mi][ni][1]) * __uint_as_float(p0 & 0xffff0000u);
;         float r2 = __uint_as_float(m1 << 16) + sigmoidf_(acc[mi][ni][2]) * __uint_as_float(p1 << 16);
;         float r3 = __uint_as_float(m1 & 0xffff0000u) + sigmoidf_(acc[mi][ni][3]) * __uint_as_float(p1 & 0xffff0000u);
;         mer[mi][ni][0] = (unsigned)f2bf(r0) | ((unsigned)f2bf(r1) << 16);
;         mer[mi][ni][1] = (unsigned)f2bf(r2) | ((unsigned)f2bf(r3) << 16);
;       }
	s_add_u32 m0, s56, 0xc000
	s_nop 0
	global_load_lds_dwordx4 v240, s[26:27]
	s_add_u32 m0, s56, 0xc400
	s_nop 0
	global_load_lds_dwordx4 v241, s[26:27]
	s_add_u32 m0, s56, 0xc800
	s_nop 0
	global_load_lds_dwordx4 v242, s[26:27]
	s_add_u32 m0, s56, 0xcc00
	s_nop 0
	global_load_lds_dwordx4 v243, s[26:27]
	s_add_u32 s26, s26, 128
	s_addc_u32 s27, s27, 0
	v_mfma_f32_16x16x32_bf16 v[0:3], v[216:219], v[200:203], v[0:3]
	ds_read_b128 v[168:171], v248 offset:0
	v_mfma_f32_16x16x32_bf16 v[4:7], v[220:223], v[200:203], v[4:7]
	ds_read_b128 v[184:187], v250 offset:16384
	v_mfma_f32_16x16x32_bf16 v[8:11], v[228:231], v[200:203], v[8:11]
	ds_read_b128 v[172:175], v248 offset:2048
	v_mfma_f32_16x16x32_bf16 v[12:15], v[232:235], v[200:203], v[12:15]
	ds_read_b128 v[188:191], v250 offset:16896
	v_mfma_f32_16x16x32_bf16 v[16:19], v[216:219], v[204:207], v[16:19]
	ds_read_b128 v[176:179], v248 offset:4096
	v_mfma_f32_16x16x32_bf16 v[20:23], v[220:223], v[204:207], v[20:23]
	ds_read_b128 v[192:195], v250 offset:17408
	v_mfma_f32_16x16x32_bf16 v[24:27], v[228:231], v[204:207], v[24:27]
	ds_read_b128 v[180:183], v248 offset:6144
	v_mfma_f32_16x16x32_bf16 v[28:31], v[232:235], v[204:207], v[28:31]
	ds_read_b128 v[196:199], v250 offset:17920
	v_mfma_f32_16x16x32_bf16 v[32:35], v[216:219], v[208:211], v[32:35]
	v_mfma_f32_16x16x32_bf16 v[36:39], v[220:223], v[208:211], v[36:39]
	v_mfma_f32_16x16x32_bf16 v[40:43], v[228:231], v[208:211], v[40:43]
	v_mfma_f32_16x16x32_bf16 v[44:47], v[232:235], v[208:211], v[44:47]
	v_mfma_f32_16x16x32_bf16 v[48:51], v[216:219], v[212:215], v[48:51]
	v_mfma_f32_16x16x32_bf16 v[52:55], v[220:223], v[212:215], v[52:55]
	v_mfma_f32_16x16x32_bf16 v[56:59], v[228:231], v[212:215], v[56:59]
	v_mfma_f32_16x16x32_bf16 v[60:63], v[232:235], v[212:215], v[60:63]
	s_nop 15
	s_nop 7
	v_mul_f32_e32 v200, 0xbfb8aa3b, v0
	v_mul_f32_e32 v201, 0xbfb8aa3b, v1
	v_mul_f32_e32 v202, 0xbfb8aa3b, v2
	v_mul_f32_e32 v203, 0xbfb8aa3b, v3
	v_mul_f32_e32 v204, 0xbfb8aa3b, v4
	v_mul_f32_e32 v205, 0xbfb8aa3b, v5
	v_mul_f32_e32 v206, 0xbfb8aa3b, v6
	v_mul_f32_e32 v207, 0xbfb8aa3b, v7
	v_exp_f32_e32 v200, v200
	v_exp_f32_e32 v201, v201
	v_exp_f32_e32 v202, v202
	v_exp_f32_e32 v203, v203
	v_exp_f32_e32 v204, v204
	v_exp_f32_e32 v205, v205
	v_exp_f32_e32 v206, v206
	v_exp_f32_e32 v207, v207
	v_add_f32_e32 v200, 1.0, v200
	v_add_f32_e32 v201, 1.0, v201
	v_add_f32_e32 v202, 1.0, v202
	v_add_f32_e32 v203, 1.0, v203
	v_add_f32_e32 v204, 1.0, v204
	v_add_f32_e32 v205, 1.0, v205
	v_add_f32_e32 v206, 1.0, v206
	v_add_f32_e32 v207, 1.0, v207
	v_rcp_f32_e32 v200, v200
	v_rcp_f32_e32 v201, v201
	v_rcp_f32_e32 v202, v202
	v_rcp_f32_e32 v203, v203
	v_rcp_f32_e32 v204, v204
	v_rcp_f32_e32 v205, v205
	v_rcp_f32_e32 v206, v206
	v_rcp_f32_e32 v207, v207
	v_lshlrev_b32_e32 v208, 16, v128
	v_and_b32_e32 v209, 0xffff0000, v128
	v_lshlrev_b32_e32 v210, 16, v129
	v_and_b32_e32 v211, 0xffff0000, v129
	v_lshlrev_b32_e32 v212, 16, v130
	v_and_b32_e32 v213, 0xffff0000, v130
	v_lshlrev_b32_e32 v214, 16, v131
	v_and_b32_e32 v215, 0xffff0000, v131
	v_fmac_f32_e32 v64, v200, v208
	v_fmac_f32_e32 v65, v201, v209
	v_fmac_f32_e32 v66, v202, v210
	v_fmac_f32_e32 v67, v203, v211
	v_fmac_f32_e32 v68, v204, v212
	v_fmac_f32_e32 v69, v205, v213
	v_fmac_f32_e32 v70, v206, v214
	v_fmac_f32_e32 v71, v207, v215
	v_mul_f32_e32 v200, 0xbfb8aa3b, v8
	v_mul_f32_e32 v201, 0xbfb8aa3b, v9
	v_mul_f32_e32 v202, 0xbfb8aa3b, v10
	v_mul_f32_e32 v203, 0xbfb8aa3b, v11
	v_mul_f32_e32 v204, 0xbfb8aa3b, v12
	v_mul_f32_e32 v205, 0xbfb8aa3b, v13
	v_mul_f32_e32 v206, 0xbfb8aa3b, v14
	v_mul_f32_e32 v207, 0xbfb8aa3b, v15
	v_exp_f32_e32 v200, v200
	v_exp_f32_e32 v201, v201
	v_exp_f32_e32 v202, v202
	v_exp_f32_e32 v203, v203
	v_exp_f32_e32 v204, v204
	v_exp_f32_e32 v205, v205
	v_exp_f32_e32 v206, v206
	v_exp_f32_e32 v207, v207
	v_add_f32_e32 v200, 1.0, v200
	v_add_f32_e32 v201, 1.0, v201
	v_add_f32_e32 v202, 1.0, v202
	v_add_f32_e32 v203, 1.0, v203
	v_add_f32_e32 v204, 1.0, v204
	v_add_f32_e32 v205, 1.0, v205
	v_add_f32_e32 v206, 1.0, v206
	v_add_f32_e32 v207, 1.0, v207
	v_rcp_f32_e32 v200, v200
	v_rcp_f32_e32 v201, v201
	v_rcp_f32_e32 v202, v202
	v_rcp_f32_e32 v203, v203
	v_rcp_f32_e32 v204, v204
	v_rcp_f32_e32 v205, v205
	v_rcp_f32_e32 v206, v206
	v_rcp_f32_e32 v207, v207
	v_lshlrev_b32_e32 v208, 16, v132
	v_and_b32_e32 v209, 0xffff0000, v132
	v_lshlrev_b32_e32 v210, 16, v133
	v_and_b32_e32 v211, 0xffff0000, v133
	v_lshlrev_b32_e32 v212, 16, v134
	v_and_b32_e32 v213, 0xffff0000, v134
	v_lshlrev_b32_e32 v214, 16, v135
	v_and_b32_e32 v215, 0xffff0000, v135
	v_fmac_f32_e32 v72, v200, v208
	v_fmac_f32_e32 v73, v201, v209
	v_fmac_f32_e32 v74, v202, v210
	v_fmac_f32_e32 v75, v203, v211
	v_fmac_f32_e32 v76, v204, v212
	v_fmac_f32_e32 v77, v205, v213
	v_fmac_f32_e32 v78, v206, v214
	v_fmac_f32_e32 v79, v207, v215
	v_mul_f32_e32 v200, 0xbfb8aa3b, v16
	v_mul_f32_e32 v201, 0xbfb8aa3b, v17
	v_mul_f32_e32 v202, 0xbfb8aa3b, v18
	v_mul_f32_e32 v203, 0xbfb8aa3b, v19
	v_mul_f32_e32 v204, 0xbfb8aa3b, v20
	v_mul_f32_e32 v205, 0xbfb8aa3b, v21
	v_mul_f32_e32 v206, 0xbfb8aa3b, v22
	v_mul_f32_e32 v207, 0xbfb8aa3b, v23
	v_exp_f32_e32 v200, v200
	v_exp_f32_e32 v201, v201
	v_exp_f32_e32 v202, v202
	v_exp_f32_e32 v203, v203
	v_exp_f32_e32 v204, v204
	v_exp_f32_e32 v205, v205
	v_exp_f32_e32 v206, v206
	v_exp_f32_e32 v207, v207
	v_add_f32_e32 v200, 1.0, v200
	v_add_f32_e32 v201, 1.0, v201
	v_add_f32_e32 v202, 1.0, v202
	v_add_f32_e32 v203, 1.0, v203
	v_add_f32_e32 v204, 1.0, v204
	v_add_f32_e32 v205, 1.0, v205
	v_add_f32_e32 v206, 1.0, v206
	v_add_f32_e32 v207, 1.0, v207
	v_rcp_f32_e32 v200, v200
	v_rcp_f32_e32 v201, v201
	v_rcp_f32_e32 v202, v202
; __device__ __forceinline__ float sigmoidf_(float v) { return 1.f / (1.f + __expf(-v)); }
; __device__ void phase_merge4(CParams& p, int l, int tm, int tn, char* smem) {
;     ...
; #pragma unroll
;     for (int mi = 0; mi < 4; mi++)
; #pragma unroll
;       for (int ni = 0; ni < 4; ni++) {
;         unsigned p0 = pk[mi][ni][0], p1 = pk[mi][ni][1], m0 = mer[mi][ni][0], m1 = mer[mi][ni][1];
;         float r0 = __uint_as_float(m0 << 16) + sigmoidf_(acc[mi][ni][0]) * __uint_as_float(p0 << 16);
;         float r1 = __uint_as_float(m0 & 0xffff0000u) + sigmoidf_(acc[mi][ni][1]) * __uint_as_float(p0 & 0xffff0000u);
;         float r2 = __uint_as_float(m1 << 16) + sigmoidf_(acc[mi][ni][2]) * __uint_as_float(p1 << 16);
;         float r3 = __uint_as_float(m1 & 0xffff0000u) + sigmoidf_(acc[mi][ni][3]) * __uint_as_float(p1 & 0xffff0000u);
;         mer[mi][ni][0] = (unsigned)f2bf(r0) | ((unsigned)f2bf(r1) << 16);
;         mer[mi][ni][1] = (unsigned)f2bf(r2) | ((unsigned)f2bf(r3) << 16);
;       }
	v_rcp_f32_e32 v203, v203
	v_rcp_f32_e32 v204, v204
	v_rcp_f32_e32 v205, v205
	v_rcp_f32_e32 v206, v206
	v_rcp_f32_e32 v207, v207
	v_lshlrev_b32_e32 v208, 16, v136
	v_and_b32_e32 v209, 0xffff0000, v136
	v_lshlrev_b32_e32 v210, 16, v137
	v_and_b32_e32 v211, 0xffff0000, v137
	v_lshlrev_b32_e32 v212, 16, v138
	v_and_b32_e32 v213, 0xffff0000, v138
	v_lshlrev_b32_e32 v214, 16, v139
	v_and_b32_e32 v215, 0xffff0000, v139
	v_fmac_f32_e32 v80, v200, v208
	v_fmac_f32_e32 v81, v201, v209
	v_fmac_f32_e32 v82, v202, v210
	v_fmac_f32_e32 v83, v203, v211
	v_fmac_f32_e32 v84, v204, v212
	v_fmac_f32_e32 v85, v205, v213
	v_fmac_f32_e32 v86, v206, v214
	v_fmac_f32_e32 v87, v207, v215
	v_mul_f32_e32 v200, 0xbfb8aa3b, v24
	v_mul_f32_e32 v201, 0xbfb8aa3b, v25
	v_mul_f32_e32 v202, 0xbfb8aa3b, v26
	v_mul_f32_e32 v203, 0xbfb8aa3b, v27
	v_mul_f32_e32 v204, 0xbfb8aa3b, v28
	v_mul_f32_e32 v205, 0xbfb8aa3b, v29
	v_mul_f32_e32 v206, 0xbfb8aa3b, v30
	v_mul_f32_e32 v207, 0xbfb8aa3b, v31
	v_exp_f32_e32 v200, v200
	v_exp_f32_e32 v201, v201
	v_exp_f32_e32 v202, v202
	v_exp_f32_e32 v203, v203
	v_exp_f32_e32 v204, v204
	v_exp_f32_e32 v205, v205
	v_exp_f32_e32 v206, v206
	v_exp_f32_e32 v207, v207
	v_add_f32_e32 v200, 1.0, v200
	v_add_f32_e32 v201, 1.0, v201
	v_add_f32_e32 v202, 1.0, v202
	v_add_f32_e32 v203, 1.0, v203
	v_add_f32_e32 v204, 1.0, v204
	v_add_f32_e32 v205, 1.0, v205
	v_add_f32_e32 v206, 1.0, v206
	v_add_f32_e32 v207, 1.0, v207
	v_rcp_f32_e32 v200, v200
	v_rcp_f32_e32 v201, v201
	v_rcp_f32_e32 v202, v202
	v_rcp_f32_e32 v203, v203
	v_rcp_f32_e32 v204, v204
	v_rcp_f32_e32 v205, v205
	v_rcp_f32_e32 v206, v206
	v_rcp_f32_e32 v207, v207
	v_lshlrev_b32_e32 v208, 16, v140
	v_and_b32_e32 v209, 0xffff0000, v140
	v_lshlrev_b32_e32 v210, 16, v141
	v_and_b32_e32 v211, 0xffff0000, v141
	v_lshlrev_b32_e32 v212, 16, v142
	v_and_b32_e32 v213, 0xffff0000, v142
	v_lshlrev_b32_e32 v214, 16, v143
	v_and_b32_e32 v215, 0xffff0000, v143
	v_fmac_f32_e32 v88, v200, v208
	v_fmac_f32_e32 v89, v201, v209
	v_fmac_f32_e32 v90, v202, v210
	v_fmac_f32_e32 v91, v203, v211
	v_fmac_f32_e32 v92, v204, v212
	v_fmac_f32_e32 v93, v205, v213
	v_fmac_f32_e32 v94, v206, v214
	v_fmac_f32_e32 v95, v207, v215
	v_mul_f32_e32 v200, 0xbfb8aa3b, v32
	v_mul_f32_e32 v201, 0xbfb8aa3b, v33
	v_mul_f32_e32 v202, 0xbfb8aa3b, v34
	v_mul_f32_e32 v203, 0xbfb8aa3b, v35
	v_mul_f32_e32 v204, 0xbfb8aa3b, v36
	v_mul_f32_e32 v205, 0xbfb8aa3b, v37
	v_mul_f32_e32 v206, 0xbfb8aa3b, v38
	v_mul_f32_e32 v207, 0xbfb8aa3b, v39
	v_exp_f32_e32 v200, v200
	v_exp_f32_e32 v201, v201
	v_exp_f32_e32 v202, v202
	v_exp_f32_e32 v203, v203
	v_exp_f32_e32 v204, v204
	v_exp_f32_e32 v205, v205
	v_exp_f32_e32 v206, v206
	v_exp_f32_e32 v207, v207
	v_add_f32_e32 v200, 1.0, v200
	v_add_f32_e32 v201, 1.0, v201
	v_add_f32_e32 v202, 1.0, v202
	v_add_f32_e32 v203, 1.0, v203
	v_add_f32_e32 v204, 1.0, v204
	v_add_f32_e32 v205, 1.0, v205
	v_add_f32_e32 v206, 1.0, v206
	v_add_f32_e32 v207, 1.0, v207
	v_rcp_f32_e32 v200, v200
	v_rcp_f32_e32 v201, v201
	v_rcp_f32_e32 v202, v202
	v_rcp_f32_e32 v203, v203
	v_rcp_f32_e32 v204, v204
	v_rcp_f32_e32 v205, v205
	v_rcp_f32_e32 v206, v206
	v_rcp_f32_e32 v207, v207
	v_lshlrev_b32_e32 v208, 16, v148
	v_and_b32_e32 v209, 0xffff0000, v148
	v_lshlrev_b32_e32 v210, 16, v149
	v_and_b32_e32 v211, 0xffff0000, v149
	v_lshlrev_b32_e32 v212, 16, v150
	v_and_b32_e32 v213, 0xffff0000, v150
	v_lshlrev_b32_e32 v214, 16, v151
	v_and_b32_e32 v215, 0xffff0000, v151
	v_fmac_f32_e32 v96, v200, v208
	v_fmac_f32_e32 v97, v201, v209
	v_fmac_f32_e32 v98, v202, v210
	v_fmac_f32_e32 v99, v203, v211
	v_fmac_f32_e32 v100, v204, v212
	v_fmac_f32_e32 v101, v205, v213
	v_fmac_f32_e32 v102, v206, v214
	v_fmac_f32_e32 v103, v207, v215
	v_mul_f32_e32 v200, 0xbfb8aa3b, v40
	v_mul_f32_e32 v201, 0xbfb8aa3b, v41
	v_mul_f32_e32 v202, 0xbfb8aa3b, v42
	v_mul_f32_e32 v203, 0xbfb8aa3b, v43
	v_mul_f32_e32 v204, 0xbfb8aa3b, v44
	v_mul_f32_e32 v205, 0xbfb8aa3b, v45
	v_mul_f32_e32 v206, 0xbfb8aa3b, v46
	v_mul_f32_e32 v207, 0xbfb8aa3b, v47
	v_exp_f32_e32 v200, v200
	v_exp_f32_e32 v201, v201
	v_exp_f32_e32 v202, v202
	v_exp_f32_e32 v203, v203
	v_exp_f32_e32 v204, v204
	v_exp_f32_e32 v205, v205
	v_exp_f32_e32 v206, v206
	v_exp_f32_e32 v207, v207
	v_add_f32_e32 v200, 1.0, v200
	v_add_f32_e32 v201, 1.0, v201
	v_add_f32_e32 v202, 1.0, v202
	v_add_f32_e32 v203, 1.0, v203
	v_add_f32_e32 v204, 1.0, v204
	v_add_f32_e32 v205, 1.0, v205
	v_add_f32_e32 v206, 1.0, v206
	v_add_f32_e32 v207, 1.0, v207
	v_rcp_f32_e32 v200, v200
	v_rcp_f32_e32 v201, v201
	v_rcp_f32_e32 v202, v202
	v_rcp_f32_e32 v203, v203
	v_rcp_f32_e32 v204, v204
	v_rcp_f32_e32 v205, v205
	v_rcp_f32_e32 v206, v206
	v_rcp_f32_e32 v207, v207
	v_lshlrev_b32_e32 v208, 16, v152
	v_and_b32_e32 v209, 0xffff0000, v152
	v_lshlrev_b32_e32 v210, 16, v153
	v_and_b32_e32 v211, 0xffff0000, v153
	v_lshlrev_b32_e32 v212, 16, v154
	v_and_b32_e32 v213, 0xffff0000, v154
	v_lshlrev_b32_e32 v214, 16, v155
	v_and_b32_e32 v215, 0xffff0000, v155
	v_fmac_f32_e32 v104, v200, v208
	v_fmac_f32_e32 v105, v201, v209
	v_fmac_f32_e32 v106, v202, v210
	v_fmac_f32_e32 v107, v203, v211
	v_fmac_f32_e32 v108, v204, v212
	v_fmac_f32_e32 v109, v205, v213
	v_fmac_f32_e32 v110, v206, v214
; __device__ __forceinline__ float sigmoidf_(float v) { return 1.f / (1.f + __expf(-v)); }
; __device__ void phase_merge4(CParams& p, int l, int tm, int tn, char* smem) {
;     ...
; #pragma unroll
;     for (int mi = 0; mi < 4; mi++)
; #pragma unroll
;       for (int ni = 0; ni < 4; ni++) {
;         unsigned p0 = pk[mi][ni][0], p1 = pk[mi][ni][1], m0 = mer[mi][ni][0], m1 = mer[mi][ni][1];
;         float r0 = __uint_as_float(m0 << 16) + sigmoidf_(acc[mi][ni][0]) * __uint_as_float(p0 << 16);
;         float r1 = __uint_as_float(m0 & 0xffff0000u) + sigmoidf_(acc[mi][ni][1]) * __uint_as_float(p0 & 0xffff0000u);
;         float r2 = __uint_as_float(m1 << 16) + sigmoidf_(acc[mi][ni][2]) * __uint_as_float(p1 << 16);
;         float r3 = __uint_as_float(m1 & 0xffff0000u) + sigmoidf_(acc[mi][ni][3]) * __uint_as_float(p1 & 0xffff0000u);
;         mer[mi][ni][0] = (unsigned)f2bf(r0) | ((unsigned)f2bf(r1) << 16);
;         mer[mi][ni][1] = (unsigned)f2bf(r2) | ((unsigned)f2bf(r3) << 16);
;       }
;   }
;   {
;     const int lane = tid & 63, wid = tid >> 6, wr = wid >> 1, wc = wid & 1;
; #pragma unroll
;     for (int mi = 0; mi < 4; mi++)
; #pragma unroll
;       for (int ni = 0; ni < 4; ni++)
; #pragma unroll
;         for (int j = 0; j < 4; j++) {
;           int rl = wr * 64 + mi * 16 + (lane >> 4) * 4 + j;
;           int cl = wc * 64 + ni * 16 + (lane & 15);
;           unsigned w = mer[mi][ni][j >> 1];
;           p.merged[(size_t)(row0 + rl) * 1024 + col0 + cl] = (bf16_t)((j & 1) ? (w >> 16) : (w & 0xffffu));
;         }
;   }
	v_fmac_f32_e32 v111, v207, v215
	v_mul_f32_e32 v200, 0xbfb8aa3b, v48
	v_mul_f32_e32 v201, 0xbfb8aa3b, v49
	v_mul_f32_e32 v202, 0xbfb8aa3b, v50
	v_mul_f32_e32 v203, 0xbfb8aa3b, v51
	v_mul_f32_e32 v204, 0xbfb8aa3b, v52
	v_mul_f32_e32 v205, 0xbfb8aa3b, v53
	v_mul_f32_e32 v206, 0xbfb8aa3b, v54
	v_mul_f32_e32 v207, 0xbfb8aa3b, v55
	v_exp_f32_e32 v200, v200
	v_exp_f32_e32 v201, v201
	v_exp_f32_e32 v202, v202
	v_exp_f32_e32 v203, v203
	v_exp_f32_e32 v204, v204
	v_exp_f32_e32 v205, v205
	v_exp_f32_e32 v206, v206
	v_exp_f32_e32 v207, v207
	v_add_f32_e32 v200, 1.0, v200
	v_add_f32_e32 v201, 1.0, v201
	v_add_f32_e32 v202, 1.0, v202
	v_add_f32_e32 v203, 1.0, v203
	v_add_f32_e32 v204, 1.0, v204
	v_add_f32_e32 v205, 1.0, v205
	v_add_f32_e32 v206, 1.0, v206
	v_add_f32_e32 v207, 1.0, v207
	v_rcp_f32_e32 v200, v200
	v_rcp_f32_e32 v201, v201
	v_rcp_f32_e32 v202, v202
	v_rcp_f32_e32 v203, v203
	v_rcp_f32_e32 v204, v204
	v_rcp_f32_e32 v205, v205
	v_rcp_f32_e32 v206, v206
	v_rcp_f32_e32 v207, v207
	v_lshlrev_b32_e32 v208, 16, v156
	v_and_b32_e32 v209, 0xffff0000, v156
	v_lshlrev_b32_e32 v210, 16, v157
	v_and_b32_e32 v211, 0xffff0000, v157
	v_lshlrev_b32_e32 v212, 16, v158
	v_and_b32_e32 v213, 0xffff0000, v158
	v_lshlrev_b32_e32 v214, 16, v159
	v_and_b32_e32 v215, 0xffff0000, v159
	v_fmac_f32_e32 v112, v200, v208
	v_fmac_f32_e32 v113, v201, v209
	v_fmac_f32_e32 v114, v202, v210
	v_fmac_f32_e32 v115, v203, v211
	v_fmac_f32_e32 v116, v204, v212
	v_fmac_f32_e32 v117, v205, v213
	v_fmac_f32_e32 v118, v206, v214
	v_fmac_f32_e32 v119, v207, v215
	v_mul_f32_e32 v200, 0xbfb8aa3b, v56
	v_mul_f32_e32 v201, 0xbfb8aa3b, v57
	v_mul_f32_e32 v202, 0xbfb8aa3b, v58
	v_mul_f32_e32 v203, 0xbfb8aa3b, v59
	v_mul_f32_e32 v204, 0xbfb8aa3b, v60
	v_mul_f32_e32 v205, 0xbfb8aa3b, v61
	v_mul_f32_e32 v206, 0xbfb8aa3b, v62
	v_mul_f32_e32 v207, 0xbfb8aa3b, v63
	v_exp_f32_e32 v200, v200
	v_exp_f32_e32 v201, v201
	v_exp_f32_e32 v202, v202
	v_exp_f32_e32 v203, v203
	v_exp_f32_e32 v204, v204
	v_exp_f32_e32 v205, v205
	v_exp_f32_e32 v206, v206
	v_exp_f32_e32 v207, v207
	v_add_f32_e32 v200, 1.0, v200
	v_add_f32_e32 v201, 1.0, v201
	v_add_f32_e32 v202, 1.0, v202
	v_add_f32_e32 v203, 1.0, v203
	v_add_f32_e32 v204, 1.0, v204
	v_add_f32_e32 v205, 1.0, v205
	v_add_f32_e32 v206, 1.0, v206
	v_add_f32_e32 v207, 1.0, v207
	v_rcp_f32_e32 v200, v200
	v_rcp_f32_e32 v201, v201
	v_rcp_f32_e32 v202, v202
	v_rcp_f32_e32 v203, v203
	v_rcp_f32_e32 v204, v204
	v_rcp_f32_e32 v205, v205
	v_rcp_f32_e32 v206, v206
	v_rcp_f32_e32 v207, v207
	v_lshlrev_b32_e32 v208, 16, v160
	v_and_b32_e32 v209, 0xffff0000, v160
	v_lshlrev_b32_e32 v210, 16, v161
	v_and_b32_e32 v211, 0xffff0000, v161
	v_lshlrev_b32_e32 v212, 16, v162
	v_and_b32_e32 v213, 0xffff0000, v162
	v_lshlrev_b32_e32 v214, 16, v163
	v_and_b32_e32 v215, 0xffff0000, v163
	v_fmac_f32_e32 v120, v200, v208
	v_fmac_f32_e32 v121, v201, v209
	v_fmac_f32_e32 v122, v202, v210
	v_fmac_f32_e32 v123, v203, v211
	v_fmac_f32_e32 v124, v204, v212
	v_fmac_f32_e32 v125, v205, v213
	v_fmac_f32_e32 v126, v206, v214
	v_fmac_f32_e32 v127, v207, v215
	s_and_b32 s63, s22, 3
	s_cmp_lg_u32 s63, 3
	s_cbranch_scc1 .Lmg4_nostore
	s_lshl_b32 s62, s23, 11
	s_lshl_b32 s92, s21, 1
	s_add_u32 s62, s62, s92
	s_add_u32 s58, s8, s62
	s_addc_u32 s59, s9, 0
	v_cvt_pk_bf16_f32 v200, v64, v65
	v_cvt_pk_bf16_f32 v201, v66, v67
	v_cvt_pk_bf16_f32 v202, v68, v69
	v_cvt_pk_bf16_f32 v203, v70, v71
	global_store_dwordx4 v144, v[200:203], s[58:59] offset:0
	v_cvt_pk_bf16_f32 v204, v72, v73
	v_cvt_pk_bf16_f32 v205, v74, v75
	v_cvt_pk_bf16_f32 v206, v76, v77
	v_cvt_pk_bf16_f32 v207, v78, v79
	global_store_dwordx4 v144, v[204:207], s[58:59] offset:16
	s_add_u32 s58, s58, 0x8000
	s_addc_u32 s59, s59, 0
	v_cvt_pk_bf16_f32 v208, v80, v81
	v_cvt_pk_bf16_f32 v209, v82, v83
	v_cvt_pk_bf16_f32 v210, v84, v85
	v_cvt_pk_bf16_f32 v211, v86, v87
	global_store_dwordx4 v144, v[208:211], s[58:59] offset:0
	v_cvt_pk_bf16_f32 v212, v88, v89
	v_cvt_pk_bf16_f32 v213, v90, v91
	v_cvt_pk_bf16_f32 v214, v92, v93
	v_cvt_pk_bf16_f32 v215, v94, v95
	global_store_dwordx4 v144, v[212:215], s[58:59] offset:16
	s_add_u32 s58, s58, 0x8000
	s_addc_u32 s59, s59, 0
	v_cvt_pk_bf16_f32 v216, v96, v97
	v_cvt_pk_bf16_f32 v217, v98, v99
	v_cvt_pk_bf16_f32 v218, v100, v101
	v_cvt_pk_bf16_f32 v219, v102, v103
	global_store_dwordx4 v144, v[216:219], s[58:59] offset:0
	v_cvt_pk_bf16_f32 v220, v104, v105
	v_cvt_pk_bf16_f32 v221, v106, v107
	v_cvt_pk_bf16_f32 v222, v108, v109
	v_cvt_pk_bf16_f32 v223, v110, v111
	global_store_dwordx4 v144, v[220:223], s[58:59] offset:16
	s_add_u32 s58, s58, 0x8000
	s_addc_u32 s59, s59, 0
	v_cvt_pk_bf16_f32 v228, v112, v113
	v_cvt_pk_bf16_f32 v229, v114, v115
	v_cvt_pk_bf16_f32 v230, v116, v117
	v_cvt_pk_bf16_f32 v231, v118, v119
	global_store_dwordx4 v144, v[228:231], s[58:59] offset:0
	v_cvt_pk_bf16_f32 v232, v120, v121
	v_cvt_pk_bf16_f32 v233, v122, v123
	v_cvt_pk_bf16_f32 v234, v124, v125
	v_cvt_pk_bf16_f32 v235, v126, v127
	global_store_dwordx4 v144, v[232:235], s[58:59] offset:16
.Lmg4_nostore:
	s_add_u32 s22, s22, 1
	s_cmp_lt_u32 s22, 8
	s_cbranch_scc1 .Lmg4_body
	s_waitcnt vmcnt(0) lgkmcnt(0)
	s_barrier
	ds_write_b128 v145, v[252:255] offset:40960
	s_waitcnt lgkmcnt(0)
	s_barrier

; template <int NI> ...
;     ...
;   G_LOAD(a0, b0, 0);
;   G_LOAD(a1, b1, 32);
;   __syncthreads();
;   G_WRITE(a0, b0, 0);
;   __syncthreads();
;   for (int kt = 0; kt < nk; kt += 2) {
;     G_LOAD(a0, b0, min((kt + 2) * 32, klast));
;     G_COMPUTE(0);
;     G_WRITE(a1, b1, 1);
;     __syncthreads();
;     G_LOAD(a1, b1, min((kt + 3) * 32, klast));
;     G_COMPUTE(1);
;     G_WRITE(a0, b0, 0);
;     __syncthreads();
;   }
.Loutp_pair:
	s_waitcnt lgkmcnt(0)
	s_cmp_eq_u32 s53, 14
	s_cselect_b64 s[8:9], s[18:19], s[8:9]
	s_add_u32 s54, s32, s93
	s_add_u32 m0, s54, 0x0
	s_nop 0
	global_load_lds_dwordx4 v236, s[8:9]
	s_add_u32 m0, s54, 0x400
	s_nop 0
	global_load_lds_dwordx4 v237, s[8:9]
	s_add_u32 m0, s54, 0x800
	s_nop 0
	global_load_lds_dwordx4 v238, s[8:9]
	s_add_u32 m0, s54, 0xc00
	s_nop 0
	global_load_lds_dwordx4 v239, s[8:9]
	s_add_u32 s8, s8, 128
	s_addc_u32 s9, s9, 0
	v_add_u32_e32 v129, s59, v249
	v_add_u32_e32 v131, s62, v251
	v_mfma_f32_16x16x32_bf16 v[0:3], v[184:187], v[168:171], v[0:3]
	ds_read_b128 v[200:203], v129 offset:0
	v_mfma_f32_16x16x32_bf16 v[4:7], v[188:191], v[168:171], v[4:7]
	ds_read_b128 v[216:219], v131 offset:0
	v_mfma_f32_16x16x32_bf16 v[8:11], v[192:195], v[168:171], v[8:11]
	ds_read_b128 v[204:207], v129 offset:2048
	v_mfma_f32_16x16x32_bf16 v[12:15], v[196:199], v[168:171], v[12:15]
	ds_read_b128 v[220:223], v131 offset:2048
	v_mfma_f32_16x16x32_bf16 v[16:19], v[184:187], v[172:175], v[16:19]
	ds_read_b128 v[208:211], v129 offset:4096
	v_mfma_f32_16x16x32_bf16 v[20:23], v[188:191], v[172:175], v[20:23]
	ds_read_b128 v[228:231], v131 offset:4096
	v_mfma_f32_16x16x32_bf16 v[24:27], v[192:195], v[172:175], v[24:27]
	ds_read_b128 v[212:215], v129 offset:6144
	v_mfma_f32_16x16x32_bf16 v[28:31], v[196:199], v[172:175], v[28:31]
	ds_read_b128 v[232:235], v131 offset:6144
	v_mfma_f32_16x16x32_bf16 v[32:35], v[184:187], v[176:179], v[32:35]
	v_mfma_f32_16x16x32_bf16 v[36:39], v[188:191], v[176:179], v[36:39]
	v_mfma_f32_16x16x32_bf16 v[40:43], v[192:195], v[176:179], v[40:43]
	v_mfma_f32_16x16x32_bf16 v[44:47], v[196:199], v[176:179], v[44:47]
	v_mfma_f32_16x16x32_bf16 v[48:51], v[184:187], v[180:183], v[48:51]
	v_mfma_f32_16x16x32_bf16 v[52:55], v[188:191], v[180:183], v[52:55]
	v_mfma_f32_16x16x32_bf16 v[56:59], v[192:195], v[180:183], v[56:59]
	v_mfma_f32_16x16x32_bf16 v[60:63], v[196:199], v[180:183], v[60:63]
	s_waitcnt vmcnt(4) lgkmcnt(0)
	s_barrier
	s_cmp_eq_u32 s53, 14
	s_cselect_b64 s[12:13], s[22:23], s[12:13]
	s_add_u32 s54, s32, s59
	s_add_u32 m0, s54, 0x0
	s_nop 0
	global_load_lds_dwordx4 v240, s[12:13]
	s_add_u32 m0, s54, 0x400
	s_nop 0
	global_load_lds_dwordx4 v241, s[12:13]
	s_add_u32 m0, s54, 0x800
	s_nop 0
	global_load_lds_dwordx4 v242, s[12:13]
	s_add_u32 m0, s54, 0xc00
	s_nop 0
	global_load_lds_dwordx4 v243, s[12:13]
	s_add_u32 s12, s12, 128
	s_addc_u32 s13, s13, 0
	v_add_u32_e32 v128, s63, v248
	v_add_u32_e32 v130, s92, v250
	v_mfma_f32_16x16x32_bf16 v[0:3], v[216:219], v[200:203], v[0:3]
	ds_read_b128 v[168:171], v128 offset:0
	v_mfma_f32_16x16x32_bf16 v[4:7], v[220:223], v[200:203], v[4:7]
	ds_read_b128 v[184:187], v130 offset:0
	v_mfma_f32_16x16x32_bf16 v[8:11], v[228:231], v[200:203], v[8:11]
	ds_read_b128 v[172:175], v128 offset:2048
	v_mfma_f32_16x16x32_bf16 v[12:15], v[232:235], v[200:203], v[12:15]
	ds_read_b128 v[188:191], v130 offset:2048
	v_mfma_f32_16x16x32_bf16 v[16:19], v[216:219], v[204:207], v[16:19]
	ds_read_b128 v[176:179], v128 offset:4096
	v_mfma_f32_16x16x32_bf16 v[20:23], v[220:223], v[204:207], v[20:23]
	ds_read_b128 v[192:195], v130 offset:4096
	v_mfma_f32_16x16x32_bf16 v[24:27], v[228:231], v[204:207], v[24:27]
	ds_read_b128 v[180:183], v128 offset:6144
	v_mfma_f32_16x16x32_bf16 v[28:31], v[232:235], v[204:207], v[28:31]
	ds_read_b128 v[196:199], v130 offset:6144
	v_mfma_f32_16x16x32_bf16 v[32:35], v[216:219], v[208:211], v[32:35]
	v_mfma_f32_16x16x32_bf16 v[36:39], v[220:223], v[208:211], v[36:39]
	v_mfma_f32_16x16x32_bf16 v[40:43], v[228:231], v[208:211], v[40:43]
	v_mfma_f32_16x16x32_bf16 v[44:47], v[232:235], v[208:211], v[44:47]
	v_mfma_f32_16x16x32_bf16 v[48:51], v[216:219], v[212:215], v[48:51]
	v_mfma_f32_16x16x32_bf16 v[52:55], v[220:223], v[212:215], v[52:55]
	v_mfma_f32_16x16x32_bf16 v[56:59], v[228:231], v[212:215], v[56:59]
	v_mfma_f32_16x16x32_bf16 v[60:63], v[232:235], v[212:215], v[60:63]
	s_mov_b32 s55, s59
	s_mov_b32 s56, s62
	s_mov_b32 s59, s63
	s_mov_b32 s62, s92
	s_mov_b32 s63, s93
	s_mov_b32 s92, s55
	s_mov_b32 s93, s56
	s_add_u32 s53, s53, 1
	s_cmp_lt_u32 s53, 16
	s_cbranch_scc1 .Loutp_pair
; __device__ void phase_proj_res(CParams& p, int l, int tm, int tn, char* smem, const bf16_t* A, int K,
;                                const bf16_t* Bt, int gate_off, float gscale) {
;     ...
;   f32x4 acc[4][4];
;   zero_acc<4>(acc);
;   gemm_mainloop<4>(A + (size_t)row0 * K, K, Bt + (size_t)col0 * K, K, K, sA, sB, acc, tid);
;   const float* md = p.mod + ((size_t)l * 3 + modvec_of_tok(row0)) * 6144 + gate_off;
;   EPI_LOOP({
;     float* xp = xrow(p, row0 + rl) + col0 + cl;
;     *xp = *xp + gscale * md[col0 + cl] * acc[mi][ni][j];
;   })
	s_nop 15
	s_nop 7
	global_load_dwordx4 v[200:203], v132, s[44:45] offset:0
	global_load_dwordx4 v[204:207], v132, s[44:45] offset:64
	global_load_dwordx4 v[208:211], v132, s[44:45] offset:128
	global_load_dwordx4 v[212:215], v132, s[44:45] offset:192
	s_mov_b64 s[44:45], s[26:27]
	global_load_dwordx4 v[64:67], v144, s[44:45] offset:0
	global_load_dwordx4 v[68:71], v144, s[44:45] offset:64
	global_load_dwordx4 v[72:75], v144, s[44:45] offset:128
	global_load_dwordx4 v[76:79], v144, s[44:45] offset:192
	s_add_u32 s44, s44, 0x10000
	s_addc_u32 s45, s45, 0
	global_load_dwordx4 v[80:83], v144, s[44:45] offset:0
	global_load_dwordx4 v[84:87], v144, s[44:45] offset:64
	global_load_dwordx4 v[88:91], v144, s[44:45] offset:128
	global_load_dwordx4 v[92:95], v144, s[44:45] offset:192
	s_add_u32 s44, s44, 0x10000
	s_addc_u32 s45, s45, 0
	global_load_dwordx4 v[96:99], v144, s[44:45] offset:0
	global_load_dwordx4 v[100:103], v144, s[44:45] offset:64
	global_load_dwordx4 v[104:107], v144, s[44:45] offset:128
	global_load_dwordx4 v[108:111], v144, s[44:45] offset:192
	s_add_u32 s44, s44, 0x10000
	s_addc_u32 s45, s45, 0
	global_load_dwordx4 v[112:115], v144, s[44:45] offset:0
	global_load_dwordx4 v[116:119], v144, s[44:45] offset:64
	global_load_dwordx4 v[120:123], v144, s[44:45] offset:128
	global_load_dwordx4 v[124:127], v144, s[44:45] offset:192
	s_waitcnt vmcnt(12)
	v_fmac_f32_e32 v64, v200, v0
	v_fmac_f32_e32 v65, v201, v1
	v_fmac_f32_e32 v66, v202, v2
	v_fmac_f32_e32 v67, v203, v3
	v_fmac_f32_e32 v68, v204, v4
	v_fmac_f32_e32 v69, v205, v5
	v_fmac_f32_e32 v70, v206, v6
	v_fmac_f32_e32 v71, v207, v7
	v_fmac_f32_e32 v72, v208, v8
	v_fmac_f32_e32 v73, v209, v9
	v_fmac_f32_e32 v74, v210, v10
	v_fmac_f32_e32 v75, v211, v11
	v_fmac_f32_e32 v76, v212, v12
	v_fmac_f32_e32 v77, v213, v13
	v_fmac_f32_e32 v78, v214, v14
	v_fmac_f32_e32 v79, v215, v15
	s_waitcnt vmcnt(8)
	v_fmac_f32_e32 v80, v200, v16
	v_fmac_f32_e32 v81, v201, v17
	v_fmac_f32_e32 v82, v202, v18
	v_fmac_f32_e32 v83, v203, v19
	v_fmac_f32_e32 v84, v204, v20
	v_fmac_f32_e32 v85, v205, v21
	v_fmac_f32_e32 v86, v206, v22
	v_fmac_f32_e32 v87, v207, v23
	v_fmac_f32_e32 v88, v208, v24
	v_fmac_f32_e32 v89, v209, v25
	v_fmac_f32_e32 v90, v210, v26
	v_fmac_f32_e32 v91, v211, v27
	v_fmac_f32_e32 v92, v212, v28
	v_fmac_f32_e32 v93, v213, v29
	v_fmac_f32_e32 v94, v214, v30
	v_fmac_f32_e32 v95, v215, v31
	s_waitcnt vmcnt(4)
	v_fmac_f32_e32 v96, v200, v32
	v_fmac_f32_e32 v97, v201, v33
	v_fmac_f32_e32 v98, v202, v34
	v_fmac_f32_e32 v99, v203, v35
	v_fmac_f32_e32 v100, v204, v36
	v_fmac_f32_e32 v101, v205, v37
	v_fmac_f32_e32 v102, v206, v38
	v_fmac_f32_e32 v103, v207, v39
	v_fmac_f32_e32 v104, v208, v40
	v_fmac_f32_e32 v105, v209, v41
	v_fmac_f32_e32 v106, v210, v42
	v_fmac_f32_e32 v107, v211, v43
	v_fmac_f32_e32 v108, v212, v44
	v_fmac_f32_e32 v109, v213, v45
	v_fmac_f32_e32 v110, v214, v46
	v_fmac_f32_e32 v111, v215, v47
	s_waitcnt vmcnt(0)
	v_fmac_f32_e32 v112, v200, v48
	v_fmac_f32_e32 v113, v201, v49
	v_fmac_f32_e32 v114, v202, v50
	v_fmac_f32_e32 v115, v203, v51
	v_fmac_f32_e32 v116, v204, v52
	v_fmac_f32_e32 v117, v205, v53
	v_fmac_f32_e32 v118, v206, v54
	v_fmac_f32_e32 v119, v207, v55
	v_fmac_f32_e32 v120, v208, v56
	v_fmac_f32_e32 v121, v209, v57
	v_fmac_f32_e32 v122, v210, v58
	v_fmac_f32_e32 v123, v211, v59
	v_fmac_f32_e32 v124, v212, v60
	v_fmac_f32_e32 v125, v213, v61
	v_fmac_f32_e32 v126, v214, v62
	v_fmac_f32_e32 v127, v215, v63
	global_store_dwordx4 v144, v[64:67], s[26:27] offset:0
	global_store_dwordx4 v144, v[68:71], s[26:27] offset:64
	global_store_dwordx4 v144, v[72:75], s[26:27] offset:128
	global_store_dwordx4 v144, v[76:79], s[26:27] offset:192
	s_add_u32 s26, s26, 0x10000
	s_addc_u32 s27, s27, 0
	global_store_dwordx4 v144, v[80:83], s[26:27] offset:0
	global_store_dwordx4 v144, v[84:87], s[26:27] offset:64
	global_store_dwordx4 v144, v[88:91], s[26:27] offset:128
	global_store_dwordx4 v144, v[92:95], s[26:27] offset:192
	s_add_u32 s26, s26, 0x10000
	s_addc_u32 s27, s27, 0
	global_store_dwordx4 v144, v[96:99], s[26:27] offset:0
	global_store_dwordx4 v144, v[100:103], s[26:27] offset:64
	global_store_dwordx4 v144, v[104:107], s[26:27] offset:128
	global_store_dwordx4 v144, v[108:111], s[26:27] offset:192
	s_add_u32 s26, s26, 0x10000
	s_addc_u32 s27, s27, 0
	global_store_dwordx4 v144, v[112:115], s[26:27] offset:0
	global_store_dwordx4 v144, v[116:119], s[26:27] offset:64
	global_store_dwordx4 v144, v[120:123], s[26:27] offset:128
	global_store_dwordx4 v144, v[124:127], s[26:27] offset:192
	v_mov_b32_e32 v0, 0
	v_mov_b32_e32 v1, 0
	v_mov_b32_e32 v2, 0
	v_mov_b32_e32 v3, 0
	v_mov_b32_e32 v4, 0
	v_mov_b32_e32 v5, 0
	v_mov_b32_e32 v6, 0
	v_mov_b32_e32 v7, 0
	v_mov_b32_e32 v8, 0
	v_mov_b32_e32 v9, 0
	v_mov_b32_e32 v10, 0
	v_mov_b32_e32 v11, 0
	v_mov_b32_e32 v12, 0
	v_mov_b32_e32 v13, 0
	v_mov_b32_e32 v14, 0
	v_mov_b32_e32 v15, 0
	v_mov_b32_e32 v16, 0
	v_mov_b32_e32 v17, 0
	v_mov_b32_e32 v18, 0
	v_mov_b32_e32 v19, 0
	v_mov_b32_e32 v20, 0
	v_mov_b32_e32 v21, 0
	v_mov_b32_e32 v22, 0
	v_mov_b32_e32 v23, 0
	v_mov_b32_e32 v24, 0
	v_mov_b32_e32 v25, 0
	v_mov_b32_e32 v26, 0
	v_mov_b32_e32 v27, 0
	v_mov_b32_e32 v28, 0
	v_mov_b32_e32 v29, 0
	v_mov_b32_e32 v30, 0
	v_mov_b32_e32 v31, 0
	v_mov_b32_e32 v32, 0
	v_mov_b32_e32 v33, 0
	v_mov_b32_e32 v34, 0
	v_mov_b32_e32 v35, 0
	v_mov_b32_e32 v36, 0
	v_mov_b32_e32 v37, 0
	v_mov_b32_e32 v38, 0
	v_mov_b32_e32 v39, 0
	v_mov_b32_e32 v40, 0
	v_mov_b32_e32 v41, 0
	v_mov_b32_e32 v42, 0
	v_mov_b32_e32 v43, 0
	v_mov_b32_e32 v44, 0
	v_mov_b32_e32 v45, 0
	v_mov_b32_e32 v46, 0
	v_mov_b32_e32 v47, 0
	v_mov_b32_e32 v48, 0
	v_mov_b32_e32 v49, 0
	v_mov_b32_e32 v50, 0
	v_mov_b32_e32 v51, 0
	v_mov_b32_e32 v52, 0
	v_mov_b32_e32 v53, 0
	v_mov_b32_e32 v54, 0
	v_mov_b32_e32 v55, 0
	v_mov_b32_e32 v56, 0
	v_mov_b32_e32 v57, 0
	v_mov_b32_e32 v58, 0
	v_mov_b32_e32 v59, 0
	v_mov_b32_e32 v60, 0
	v_mov_b32_e32 v61, 0
	v_mov_b32_e32 v62, 0
	v_mov_b32_e32 v63, 0
	s_add_u32 s52, s52, 1
	s_cmp_lt_u32 s52, 2
	s_cbranch_scc1 .Loutp_tile
	s_waitcnt vmcnt(0) lgkmcnt(0)
	s_barrier
	ds_write_b128 v145, v[252:255] offset:40960
	s_waitcnt lgkmcnt(0)
	s_barrier
	s_mov_b64 s[52:53], 0

; __device__ __forceinline__ void gemm_mainloop8(const bf16_t* __restrict__ A, int lda,
;                                                const bf16_t* __restrict__ B, int ldb, int K,
;                                                bf16_t* sbase, f32x4 (&acc)[4][8], const int tid) {
;     ...
;   for (int kt = 0; kt < nk; kt++) {
;     __syncthreads();
;     {
;       bf16_t* d_ = sbase + wofs;
;       *(u32x4*)(d_) = ra[0];
;       *(u32x4*)(d_ + 64 * GROW) = ra[1];
; #pragma unroll
;       for (int i = 0; i < 4; i++) *(u32x4*)(d_ + (128 + 64 * i) * GROW) = rb[i];
;     }
;     __syncthreads();
;     {
;       int kofs = min((kt + 1) * 32, K - 32);
;       ra[0] = *(const u32x4*)(pa + kofs); ra[1] = *(const u32x4*)(pa + a64 + kofs);
; #pragma unroll
;       for (int i = 0; i < 4; i++) rb[i] = *(const u32x4*)(pb + (size_t)i * b64 + kofs);
;     }
;     bf16x8 af[4], bfr[8];
; #pragma unroll
;     for (int mi = 0; mi < 4; mi++) af[mi] = *(const bf16x8*)(sbase + raofs + mi * 16 * GROW);
; #pragma unroll
;     for (int ni = 0; ni < 8; ni++) bfr[ni] = *(const bf16x8*)(sbase + rbofs + ni * 16 * GROW);
; #pragma unroll
;     for (int mi = 0; mi < 4; mi++)
; #pragma unroll
;       for (int ni = 0; ni < 8; ni++)
;         acc[mi][ni] = __builtin_amdgcn_mfma_f32_16x16x32_bf16(af[mi], bfr[ni], acc[mi][ni], 0, 0, 0);
;   }
.Lmlp1_pair:
	s_waitcnt lgkmcnt(0)
	s_cmp_eq_u32 s45, 14
	s_cselect_b64 s[12:13], s[24:25], s[12:13]
	s_add_u32 s50, s8, s63
	s_add_u32 m0, s50, 0x0
	s_nop 0
	global_load_lds_dwordx4 v236, s[12:13]
	s_add_u32 m0, s50, 0x400
	s_nop 0
	global_load_lds_dwordx4 v237, s[12:13]
	s_add_u32 m0, s50, 0x800
	s_nop 0
	global_load_lds_dwordx4 v238, s[12:13]
	s_add_u32 m0, s50, 0xc00
	s_nop 0
	global_load_lds_dwordx4 v239, s[12:13]
	s_add_u32 s12, s12, 128
	s_addc_u32 s13, s13, 0
	v_add_u32_e32 v129, s57, v249
	v_add_u32_e32 v131, s58, v251
	v_mfma_f32_16x16x32_bf16 v[0:3], v[184:187], v[168:171], v[0:3]
	ds_read_b128 v[200:203], v129 offset:0
	v_mfma_f32_16x16x32_bf16 v[4:7], v[188:191], v[168:171], v[4:7]
	ds_read_b128 v[216:219], v131 offset:0
	v_mfma_f32_16x16x32_bf16 v[8:11], v[192:195], v[168:171], v[8:11]
	ds_read_b128 v[204:207], v129 offset:2048
	v_mfma_f32_16x16x32_bf16 v[12:15], v[196:199], v[168:171], v[12:15]
	ds_read_b128 v[220:223], v131 offset:512
	v_mfma_f32_16x16x32_bf16 v[16:19], v[184:187], v[172:175], v[16:19]
	ds_read_b128 v[208:211], v129 offset:4096
	v_mfma_f32_16x16x32_bf16 v[20:23], v[188:191], v[172:175], v[20:23]
	ds_read_b128 v[228:231], v131 offset:1024
	v_mfma_f32_16x16x32_bf16 v[24:27], v[192:195], v[172:175], v[24:27]
	ds_read_b128 v[212:215], v129 offset:6144
	v_mfma_f32_16x16x32_bf16 v[28:31], v[196:199], v[172:175], v[28:31]
	ds_read_b128 v[232:235], v131 offset:1536
	v_mfma_f32_16x16x32_bf16 v[32:35], v[184:187], v[176:179], v[32:35]
	v_mfma_f32_16x16x32_bf16 v[36:39], v[188:191], v[176:179], v[36:39]
	v_mfma_f32_16x16x32_bf16 v[40:43], v[192:195], v[176:179], v[40:43]
	v_mfma_f32_16x16x32_bf16 v[44:47], v[196:199], v[176:179], v[44:47]
	v_mfma_f32_16x16x32_bf16 v[48:51], v[184:187], v[180:183], v[48:51]
	v_mfma_f32_16x16x32_bf16 v[52:55], v[188:191], v[180:183], v[52:55]
	v_mfma_f32_16x16x32_bf16 v[56:59], v[192:195], v[180:183], v[56:59]
	v_mfma_f32_16x16x32_bf16 v[60:63], v[196:199], v[180:183], v[60:63]
	s_waitcnt vmcnt(4) lgkmcnt(0)
	s_barrier
	s_cmp_eq_u32 s45, 14
	s_cselect_b64 s[16:17], s[26:27], s[16:17]
	s_add_u32 s50, s8, s57
	s_add_u32 m0, s50, 0x0
	s_nop 0
	global_load_lds_dwordx4 v240, s[16:17]
	s_add_u32 m0, s50, 0x400
	s_nop 0
	global_load_lds_dwordx4 v241, s[16:17]
	s_add_u32 m0, s50, 0x800
	s_nop 0
	global_load_lds_dwordx4 v242, s[16:17]
	s_add_u32 m0, s50, 0xc00
	s_nop 0
	global_load_lds_dwordx4 v243, s[16:17]
	s_add_u32 s16, s16, 128
	s_addc_u32 s17, s17, 0
	v_add_u32_e32 v128, s59, v248
	v_add_u32_e32 v130, s62, v250
	v_mfma_f32_16x16x32_bf16 v[0:3], v[216:219], v[200:203], v[0:3]
	ds_read_b128 v[168:171], v128 offset:0
	v_mfma_f32_16x16x32_bf16 v[4:7], v[220:223], v[200:203], v[4:7]
	ds_read_b128 v[184:187], v130 offset:0
	v_mfma_f32_16x16x32_bf16 v[8:11], v[228:231], v[200:203], v[8:11]
	ds_read_b128 v[172:175], v128 offset:2048
	v_mfma_f32_16x16x32_bf16 v[12:15], v[232:235], v[200:203], v[12:15]
	ds_read_b128 v[188:191], v130 offset:512
	v_mfma_f32_16x16x32_bf16 v[16:19], v[216:219], v[204:207], v[16:19]
	ds_read_b128 v[176:179], v128 offset:4096
	v_mfma_f32_16x16x32_bf16 v[20:23], v[220:223], v[204:207], v[20:23]
	ds_read_b128 v[192:195], v130 offset:1024
	v_mfma_f32_16x16x32_bf16 v[24:27], v[228:231], v[204:207], v[24:27]
	ds_read_b128 v[180:183], v128 offset:6144
	v_mfma_f32_16x16x32_bf16 v[28:31], v[232:235], v[204:207], v[28:31]
	ds_read_b128 v[196:199], v130 offset:1536
	v_mfma_f32_16x16x32_bf16 v[32:35], v[216:219], v[208:211], v[32:35]
	v_mfma_f32_16x16x32_bf16 v[36:39], v[220:223], v[208:211], v[36:39]
	v_mfma_f32_16x16x32_bf16 v[40:43], v[228:231], v[208:211], v[40:43]
	v_mfma_f32_16x16x32_bf16 v[44:47], v[232:235], v[208:211], v[44:47]
	v_mfma_f32_16x16x32_bf16 v[48:51], v[216:219], v[212:215], v[48:51]
	v_mfma_f32_16x16x32_bf16 v[52:55], v[220:223], v[212:215], v[52:55]
	v_mfma_f32_16x16x32_bf16 v[56:59], v[228:231], v[212:215], v[56:59]
	v_mfma_f32_16x16x32_bf16 v[60:63], v[232:235], v[212:215], v[60:63]
	s_mov_b32 s51, s57
	s_mov_b32 s54, s58
	s_mov_b32 s57, s59
	s_mov_b32 s58, s62
	s_mov_b32 s59, s63
	s_mov_b32 s62, s51
	s_mov_b32 s63, s54
	s_add_u32 s45, s45, 1
	s_cmp_lt_u32 s45, 16
	s_cbranch_scc1 .Lmlp1_pair
; __device__ void phase_mlp1_big(CParams& p, int l, int tm, int tn, char* smem) {
;     ...
;   const int lane = tid & 63, wid = tid >> 6, wr = wid >> 1, wc = wid & 1;
; #pragma unroll
;   for (int mi = 0; mi < 4; mi++)
; #pragma unroll
;     for (int ni = 0; ni < 8; ni++)
; #pragma unroll
;       for (int j = 0; j < 4; j++) {
;         int rl = wr * 64 + mi * 16 + (lane >> 4) * 4 + j;
;         int cl = wc * 128 + ni * 16 + (lane & 15);
;         float a = fmaxf(acc[mi][ni][j], 0.f);
;         p.hidden[(size_t)(row0 + rl) * DFF + col0 + cl] = f2bf(a * a);
;       }
	s_nop 15
	s_nop 7
	v_max_f32_e32 v0, 0, v0
	v_max_f32_e32 v1, 0, v1
	v_max_f32_e32 v2, 0, v2
	v_max_f32_e32 v3, 0, v3
	v_max_f32_e32 v4, 0, v4
	v_max_f32_e32 v5, 0, v5
	v_max_f32_e32 v6, 0, v6
	v_max_f32_e32 v7, 0, v7
	v_max_f32_e32 v8, 0, v8
	v_max_f32_e32 v9, 0, v9
	v_max_f32_e32 v10, 0, v10
	v_max_f32_e32 v11, 0, v11
	v_max_f32_e32 v12, 0, v12
	v_max_f32_e32 v13, 0, v13
	v_max_f32_e32 v14, 0, v14
	v_max_f32_e32 v15, 0, v15
	v_mul_f32_e32 v0, v0, v0
	v_mul_f32_e32 v1, v1, v1
	v_mul_f32_e32 v2, v2, v2
	v_mul_f32_e32 v3, v3, v3
	v_mul_f32_e32 v4, v4, v4
	v_mul_f32_e32 v5, v5, v5
	v_mul_f32_e32 v6, v6, v6
	v_mul_f32_e32 v7, v7, v7
	v_mul_f32_e32 v8, v8, v8
	v_mul_f32_e32 v9, v9, v9
	v_mul_f32_e32 v10, v10, v10
	v_mul_f32_e32 v11, v11, v11
	v_mul_f32_e32 v12, v12, v12
	v_mul_f32_e32 v13, v13, v13
	v_mul_f32_e32 v14, v14, v14
	v_mul_f32_e32 v15, v15, v15
	v_cvt_pk_bf16_f32 v64, v0, v1
	v_cvt_pk_bf16_f32 v65, v2, v3
	v_cvt_pk_bf16_f32 v66, v4, v5
	v_cvt_pk_bf16_f32 v67, v6, v7
	global_store_dwordx4 v144, v[64:67], s[42:43] offset:0
	v_cvt_pk_bf16_f32 v68, v8, v9
	v_cvt_pk_bf16_f32 v69, v10, v11
	v_cvt_pk_bf16_f32 v70, v12, v13
	v_cvt_pk_bf16_f32 v71, v14, v15
	global_store_dwordx4 v144, v[68:71], s[42:43] offset:16
	s_add_u32 s42, s42, 0x20000
	s_addc_u32 s43, s43, 0
	v_max_f32_e32 v16, 0, v16
	v_max_f32_e32 v17, 0, v17
	v_max_f32_e32 v18, 0, v18
	v_max_f32_e32 v19, 0, v19
	v_max_f32_e32 v20, 0, v20
	v_max_f32_e32 v21, 0, v21
	v_max_f32_e32 v22, 0, v22
	v_max_f32_e32 v23, 0, v23
	v_max_f32_e32 v24, 0, v24
	v_max_f32_e32 v25, 0, v25
	v_max_f32_e32 v26, 0, v26
	v_max_f32_e32 v27, 0, v27
	v_max_f32_e32 v28, 0, v28
	v_max_f32_e32 v29, 0, v29
	v_max_f32_e32 v30, 0, v30
	v_max_f32_e32 v31, 0, v31
	v_mul_f32_e32 v16, v16, v16
	v_mul_f32_e32 v17, v17, v17
	v_mul_f32_e32 v18, v18, v18
	v_mul_f32_e32 v19, v19, v19
	v_mul_f32_e32 v20, v20, v20
	v_mul_f32_e32 v21, v21, v21
	v_mul_f32_e32 v22, v22, v22
	v_mul_f32_e32 v23, v23, v23
	v_mul_f32_e32 v24, v24, v24
	v_mul_f32_e32 v25, v25, v25
	v_mul_f32_e32 v26, v26, v26
	v_mul_f32_e32 v27, v27, v27
	v_mul_f32_e32 v28, v28, v28
	v_mul_f32_e32 v29, v29, v29
	v_mul_f32_e32 v30, v30, v30
	v_mul_f32_e32 v31, v31, v31
	v_cvt_pk_bf16_f32 v72, v16, v17
	v_cvt_pk_bf16_f32 v73, v18, v19
	v_cvt_pk_bf16_f32 v74, v20, v21
	v_cvt_pk_bf16_f32 v75, v22, v23
	global_store_dwordx4 v144, v[72:75], s[42:43] offset:0
	v_cvt_pk_bf16_f32 v76, v24, v25
	v_cvt_pk_bf16_f32 v77, v26, v27
	v_cvt_pk_bf16_f32 v78, v28, v29
	v_cvt_pk_bf16_f32 v79, v30, v31
	global_store_dwordx4 v144, v[76:79], s[42:43] offset:16
	s_add_u32 s42, s42, 0x20000
	s_addc_u32 s43, s43, 0
	v_max_f32_e32 v32, 0, v32
	v_max_f32_e32 v33, 0, v33
	v_max_f32_e32 v34, 0, v34
	v_max_f32_e32 v35, 0, v35
	v_max_f32_e32 v36, 0, v36
	v_max_f32_e32 v37, 0, v37
	v_max_f32_e32 v38, 0, v38
	v_max_f32_e32 v39, 0, v39
	v_max_f32_e32 v40, 0, v40
	v_max_f32_e32 v41, 0, v41
	v_max_f32_e32 v42, 0, v42
	v_max_f32_e32 v43, 0, v43
	v_max_f32_e32 v44, 0, v44
	v_max_f32_e32 v45, 0, v45
	v_max_f32_e32 v46, 0, v46
	v_max_f32_e32 v47, 0, v47
	v_mul_f32_e32 v32, v32, v32
	v_mul_f32_e32 v33, v33, v33
	v_mul_f32_e32 v34, v34, v34
	v_mul_f32_e32 v35, v35, v35
	v_mul_f32_e32 v36, v36, v36
	v_mul_f32_e32 v37, v37, v37
	v_mul_f32_e32 v38, v38, v38
	v_mul_f32_e32 v39, v39, v39
	v_mul_f32_e32 v40, v40, v40
	v_mul_f32_e32 v41, v41, v41
	v_mul_f32_e32 v42, v42, v42
	v_mul_f32_e32 v43, v43, v43
	v_mul_f32_e32 v44, v44, v44
	v_mul_f32_e32 v45, v45, v45
	v_mul_f32_e32 v46, v46, v46
	v_mul_f32_e32 v47, v47, v47
	v_cvt_pk_bf16_f32 v80, v32, v33
	v_cvt_pk_bf16_f32 v81, v34, v35
	v_cvt_pk_bf16_f32 v82, v36, v37
	v_cvt_pk_bf16_f32 v83, v38, v39
	global_store_dwordx4 v144, v[80:83], s[42:43] offset:0
	v_cvt_pk_bf16_f32 v84, v40, v41
	v_cvt_pk_bf16_f32 v85, v42, v43
	v_cvt_pk_bf16_f32 v86, v44, v45
	v_cvt_pk_bf16_f32 v87, v46, v47
	global_store_dwordx4 v144, v[84:87], s[42:43] offset:16
	s_add_u32 s42, s42, 0x20000
	s_addc_u32 s43, s43, 0
	v_max_f32_e32 v48, 0, v48
	v_max_f32_e32 v49, 0, v49
	v_max_f32_e32 v50, 0, v50
	v_max_f32_e32 v51, 0, v51
	v_max_f32_e32 v52, 0, v52
	v_max_f32_e32 v53, 0, v53
	v_max_f32_e32 v54, 0, v54
	v_max_f32_e32 v55, 0, v55
	v_max_f32_e32 v56, 0, v56
	v_max_f32_e32 v57, 0, v57
	v_max_f32_e32 v58, 0, v58
	v_max_f32_e32 v59, 0, v59
	v_max_f32_e32 v60, 0, v60
	v_max_f32_e32 v61, 0, v61
	v_max_f32_e32 v62, 0, v62
	v_max_f32_e32 v63, 0, v63
	v_mul_f32_e32 v48, v48, v48
	v_mul_f32_e32 v49, v49, v49
	v_mul_f32_e32 v50, v50, v50
	v_mul_f32_e32 v51, v51, v51
	v_mul_f32_e32 v52, v52, v52
	v_mul_f32_e32 v53, v53, v53
	v_mul_f32_e32 v54, v54, v54
	v_mul_f32_e32 v55, v55, v55
	v_mul_f32_e32 v56, v56, v56
	v_mul_f32_e32 v57, v57, v57
	v_mul_f32_e32 v58, v58, v58
	v_mul_f32_e32 v59, v59, v59
	v_mul_f32_e32 v60, v60, v60
	v_mul_f32_e32 v61, v61, v61
	v_mul_f32_e32 v62, v62, v62
	v_mul_f32_e32 v63, v63, v63
	v_cvt_pk_bf16_f32 v88, v48, v49
	v_cvt_pk_bf16_f32 v89, v50, v51
	v_cvt_pk_bf16_f32 v90, v52, v53
	v_cvt_pk_bf16_f32 v91, v54, v55
	global_store_dwordx4 v144, v[88:91], s[42:43] offset:0
	v_cvt_pk_bf16_f32 v92, v56, v57
	v_cvt_pk_bf16_f32 v93, v58, v59
	v_cvt_pk_bf16_f32 v94, v60, v61
	v_cvt_pk_bf16_f32 v95, v62, v63
	global_store_dwordx4 v144, v[92:95], s[42:43] offset:16
	v_mov_b32_e32 v0, 0
	v_mov_b32_e32 v1, 0
	v_mov_b32_e32 v2, 0
	v_mov_b32_e32 v3, 0
	v_mov_b32_e32 v4, 0
	v_mov_b32_e32 v5, 0
	v_mov_b32_e32 v6, 0
	v_mov_b32_e32 v7, 0
	v_mov_b32_e32 v8, 0
	v_mov_b32_e32 v9, 0
	v_mov_b32_e32 v10, 0
	v_mov_b32_e32 v11, 0
	v_mov_b32_e32 v12, 0
	v_mov_b32_e32 v13, 0
	v_mov_b32_e32 v14, 0
	v_mov_b32_e32 v15, 0
	v_mov_b32_e32 v16, 0
	v_mov_b32_e32 v17, 0
	v_mov_b32_e32 v18, 0
	v_mov_b32_e32 v19, 0
	v_mov_b32_e32 v20, 0
	v_mov_b32_e32 v21, 0
	v_mov_b32_e32 v22, 0
	v_mov_b32_e32 v23, 0
	v_mov_b32_e32 v24, 0
	v_mov_b32_e32 v25, 0
	v_mov_b32_e32 v26, 0
	v_mov_b32_e32 v27, 0
	v_mov_b32_e32 v28, 0
	v_mov_b32_e32 v29, 0
	v_mov_b32_e32 v30, 0
	v_mov_b32_e32 v31, 0
	v_mov_b32_e32 v32, 0
	v_mov_b32_e32 v33, 0
	v_mov_b32_e32 v34, 0
	v_mov_b32_e32 v35, 0
	v_mov_b32_e32 v36, 0
	v_mov_b32_e32 v37, 0
	v_mov_b32_e32 v38, 0
	v_mov_b32_e32 v39, 0
	v_mov_b32_e32 v40, 0
	v_mov_b32_e32 v41, 0
	v_mov_b32_e32 v42, 0
	v_mov_b32_e32 v43, 0
	v_mov_b32_e32 v44, 0
	v_mov_b32_e32 v45, 0
	v_mov_b32_e32 v46, 0
	v_mov_b32_e32 v47, 0
	v_mov_b32_e32 v48, 0
	v_mov_b32_e32 v49, 0
	v_mov_b32_e32 v50, 0
	v_mov_b32_e32 v51, 0
	v_mov_b32_e32 v52, 0
	v_mov_b32_e32 v53, 0
	v_mov_b32_e32 v54, 0
	v_mov_b32_e32 v55, 0
	v_mov_b32_e32 v56, 0
	v_mov_b32_e32 v57, 0
	v_mov_b32_e32 v58, 0
	v_mov_b32_e32 v59, 0
	v_mov_b32_e32 v60, 0
	v_mov_b32_e32 v61, 0
	v_mov_b32_e32 v62, 0
	v_mov_b32_e32 v63, 0
	s_add_u32 s44, s44, 1
	s_cmp_lt_u32 s44, 8
	s_cbranch_scc1 .Lmlp1_tile
	s_waitcnt vmcnt(0) lgkmcnt(0)
	s_barrier
	ds_write_b128 v145, v[252:255] offset:40960
	s_waitcnt lgkmcnt(0)
	s_barrier

; template <int NI> ...
;     ...
;   G_LOAD(a0, b0, 0);
;   G_LOAD(a1, b1, 32);
;   __syncthreads();
;   G_WRITE(a0, b0, 0);
;   __syncthreads();
;   for (int kt = 0; kt < nk; kt += 2) {
;     G_LOAD(a0, b0, min((kt + 2) * 32, klast));
;     G_COMPUTE(0);
;     G_WRITE(a1, b1, 1);
;     __syncthreads();
;     G_LOAD(a1, b1, min((kt + 3) * 32, klast));
;     G_COMPUTE(1);
;     G_WRITE(a0, b0, 0);
;     __syncthreads();
;   }
.Lmlp2_pair:
	s_waitcnt lgkmcnt(0)
	s_cmp_eq_u32 s54, 62
	s_cselect_b64 s[16:17], s[22:23], s[16:17]
	s_add_u32 s55, s4, s98
	s_add_u32 m0, s55, 0x0
	s_nop 0
	global_load_lds_dwordx4 v236, s[16:17]
	s_add_u32 m0, s55, 0x400
	s_nop 0
	global_load_lds_dwordx4 v237, s[16:17]
	s_add_u32 m0, s55, 0x800
	s_nop 0
	global_load_lds_dwordx4 v238, s[16:17]
	s_add_u32 m0, s55, 0xc00
	s_nop 0
	global_load_lds_dwordx4 v239, s[16:17]
	s_add_u32 s16, s16, 128
	s_addc_u32 s17, s17, 0
	v_add_u32_e32 v129, s62, v249
	v_add_u32_e32 v131, s63, v251
	v_mfma_f32_16x16x32_bf16 v[0:3], v[184:187], v[168:171], v[0:3]
	ds_read_b128 v[200:203], v129 offset:0
	v_mfma_f32_16x16x32_bf16 v[4:7], v[188:191], v[168:171], v[4:7]
	ds_read_b128 v[216:219], v131 offset:0
	v_mfma_f32_16x16x32_bf16 v[8:11], v[192:195], v[168:171], v[8:11]
	ds_read_b128 v[204:207], v129 offset:2048
	v_mfma_f32_16x16x32_bf16 v[12:15], v[196:199], v[168:171], v[12:15]
	ds_read_b128 v[220:223], v131 offset:2048
	v_mfma_f32_16x16x32_bf16 v[16:19], v[184:187], v[172:175], v[16:19]
	ds_read_b128 v[208:211], v129 offset:4096
	v_mfma_f32_16x16x32_bf16 v[20:23], v[188:191], v[172:175], v[20:23]
	ds_read_b128 v[228:231], v131 offset:4096
	v_mfma_f32_16x16x32_bf16 v[24:27], v[192:195], v[172:175], v[24:27]
	ds_read_b128 v[212:215], v129 offset:6144
	v_mfma_f32_16x16x32_bf16 v[28:31], v[196:199], v[172:175], v[28:31]
	ds_read_b128 v[232:235], v131 offset:6144
	v_mfma_f32_16x16x32_bf16 v[32:35], v[184:187], v[176:179], v[32:35]
	v_mfma_f32_16x16x32_bf16 v[36:39], v[188:191], v[176:179], v[36:39]
	v_mfma_f32_16x16x32_bf16 v[40:43], v[192:195], v[176:179], v[40:43]
	v_mfma_f32_16x16x32_bf16 v[44:47], v[196:199], v[176:179], v[44:47]
	v_mfma_f32_16x16x32_bf16 v[48:51], v[184:187], v[180:183], v[48:51]
	v_mfma_f32_16x16x32_bf16 v[52:55], v[188:191], v[180:183], v[52:55]
	v_mfma_f32_16x16x32_bf16 v[56:59], v[192:195], v[180:183], v[56:59]
	v_mfma_f32_16x16x32_bf16 v[60:63], v[196:199], v[180:183], v[60:63]
	s_waitcnt vmcnt(4) lgkmcnt(0)
	s_barrier
	s_cmp_eq_u32 s54, 62
	s_cselect_b64 s[18:19], s[26:27], s[18:19]
	s_add_u32 s55, s4, s62
	s_add_u32 m0, s55, 0x0
	s_nop 0
	global_load_lds_dwordx4 v240, s[18:19]
	s_add_u32 m0, s55, 0x400
	s_nop 0
	global_load_lds_dwordx4 v241, s[18:19]
	s_add_u32 m0, s55, 0x800
	s_nop 0
	global_load_lds_dwordx4 v242, s[18:19]
	s_add_u32 m0, s55, 0xc00
	s_nop 0
	global_load_lds_dwordx4 v243, s[18:19]
	s_add_u32 s18, s18, 128
	s_addc_u32 s19, s19, 0
	v_add_u32_e32 v128, s92, v248
	v_add_u32_e32 v130, s93, v250
	v_mfma_f32_16x16x32_bf16 v[0:3], v[216:219], v[200:203], v[0:3]
	ds_read_b128 v[168:171], v128 offset:0
	v_mfma_f32_16x16x32_bf16 v[4:7], v[220:223], v[200:203], v[4:7]
	ds_read_b128 v[184:187], v130 offset:0
	v_mfma_f32_16x16x32_bf16 v[8:11], v[228:231], v[200:203], v[8:11]
	ds_read_b128 v[172:175], v128 offset:2048
	v_mfma_f32_16x16x32_bf16 v[12:15], v[232:235], v[200:203], v[12:15]
	ds_read_b128 v[188:191], v130 offset:2048
	v_mfma_f32_16x16x32_bf16 v[16:19], v[216:219], v[204:207], v[16:19]
	ds_read_b128 v[176:179], v128 offset:4096
	v_mfma_f32_16x16x32_bf16 v[20:23], v[220:223], v[204:207], v[20:23]
	ds_read_b128 v[192:195], v130 offset:4096
	v_mfma_f32_16x16x32_bf16 v[24:27], v[228:231], v[204:207], v[24:27]
	ds_read_b128 v[180:183], v128 offset:6144
	v_mfma_f32_16x16x32_bf16 v[28:31], v[232:235], v[204:207], v[28:31]
	ds_read_b128 v[196:199], v130 offset:6144
	v_mfma_f32_16x16x32_bf16 v[32:35], v[216:219], v[208:211], v[32:35]
	v_mfma_f32_16x16x32_bf16 v[36:39], v[220:223], v[208:211], v[36:39]
	v_mfma_f32_16x16x32_bf16 v[40:43], v[228:231], v[208:211], v[40:43]
	v_mfma_f32_16x16x32_bf16 v[44:47], v[232:235], v[208:211], v[44:47]
	v_mfma_f32_16x16x32_bf16 v[48:51], v[216:219], v[212:215], v[48:51]
	v_mfma_f32_16x16x32_bf16 v[52:55], v[220:223], v[212:215], v[52:55]
	v_mfma_f32_16x16x32_bf16 v[56:59], v[228:231], v[212:215], v[56:59]
	v_mfma_f32_16x16x32_bf16 v[60:63], v[232:235], v[212:215], v[60:63]
	s_mov_b32 s56, s62
	s_mov_b32 s57, s63
	s_mov_b32 s62, s92
	s_mov_b32 s63, s93
	s_mov_b32 s92, s98
	s_mov_b32 s93, s56
	s_mov_b32 s98, s57
	s_add_u32 s54, s54, 1
	s_cmp_lt_u32 s54, 64
	s_cbranch_scc1 .Lmlp2_pair
; __device__ void phase_proj_res(CParams& p, int l, int tm, int tn, char* smem, const bf16_t* A, int K,
;                                const bf16_t* Bt, int gate_off, float gscale) {
;     ...
;   f32x4 acc[4][4];
;   zero_acc<4>(acc);
;   gemm_mainloop<4>(A + (size_t)row0 * K, K, Bt + (size_t)col0 * K, K, K, sA, sB, acc, tid);
;   const float* md = p.mod + ((size_t)l * 3 + modvec_of_tok(row0)) * 6144 + gate_off;
;   EPI_LOOP({
;     float* xp = xrow(p, row0 + rl) + col0 + cl;
;     *xp = *xp + gscale * md[col0 + cl] * acc[mi][ni][j];
;   })
	s_nop 15
	s_nop 7
	global_load_dwordx4 v[200:203], v132, s[52:53] offset:0
	global_load_dwordx4 v[204:207], v132, s[52:53] offset:64
	global_load_dwordx4 v[208:211], v132, s[52:53] offset:128
	global_load_dwordx4 v[212:215], v132, s[52:53] offset:192
	s_mov_b64 s[52:53], s[40:41]
	global_load_dwordx4 v[64:67], v144, s[52:53] offset:0
	global_load_dwordx4 v[68:71], v144, s[52:53] offset:64
	global_load_dwordx4 v[72:75], v144, s[52:53] offset:128
	global_load_dwordx4 v[76:79], v144, s[52:53] offset:192
	s_add_u32 s52, s52, 0x10000
	s_addc_u32 s53, s53, 0
	global_load_dwordx4 v[80:83], v144, s[52:53] offset:0
	global_load_dwordx4 v[84:87], v144, s[52:53] offset:64
	global_load_dwordx4 v[88:91], v144, s[52:53] offset:128
	global_load_dwordx4 v[92:95], v144, s[52:53] offset:192
	s_add_u32 s52, s52, 0x10000
	s_addc_u32 s53, s53, 0
	global_load_dwordx4 v[96:99], v144, s[52:53] offset:0
	global_load_dwordx4 v[100:103], v144, s[52:53] offset:64
	global_load_dwordx4 v[104:107], v144, s[52:53] offset:128
	global_load_dwordx4 v[108:111], v144, s[52:53] offset:192
	s_add_u32 s52, s52, 0x10000
	s_addc_u32 s53, s53, 0
	global_load_dwordx4 v[112:115], v144, s[52:53] offset:0
	global_load_dwordx4 v[116:119], v144, s[52:53] offset:64
	global_load_dwordx4 v[120:123], v144, s[52:53] offset:128
	global_load_dwordx4 v[124:127], v144, s[52:53] offset:192
	s_waitcnt vmcnt(12)
	v_fmac_f32_e32 v64, v200, v0
	v_fmac_f32_e32 v65, v201, v1
	v_fmac_f32_e32 v66, v202, v2
	v_fmac_f32_e32 v67, v203, v3
	v_fmac_f32_e32 v68, v204, v4
	v_fmac_f32_e32 v69, v205, v5
	v_fmac_f32_e32 v70, v206, v6
	v_fmac_f32_e32 v71, v207, v7
	v_fmac_f32_e32 v72, v208, v8
	v_fmac_f32_e32 v73, v209, v9
	v_fmac_f32_e32 v74, v210, v10
	v_fmac_f32_e32 v75, v211, v11
	v_fmac_f32_e32 v76, v212, v12
	v_fmac_f32_e32 v77, v213, v13
	v_fmac_f32_e32 v78, v214, v14
	v_fmac_f32_e32 v79, v215, v15
	s_waitcnt vmcnt(8)
	v_fmac_f32_e32 v80, v200, v16
	v_fmac_f32_e32 v81, v201, v17
	v_fmac_f32_e32 v82, v202, v18
	v_fmac_f32_e32 v83, v203, v19
	v_fmac_f32_e32 v84, v204, v20
	v_fmac_f32_e32 v85, v205, v21
	v_fmac_f32_e32 v86, v206, v22
	v_fmac_f32_e32 v87, v207, v23
	v_fmac_f32_e32 v88, v208, v24
	v_fmac_f32_e32 v89, v209, v25
	v_fmac_f32_e32 v90, v210, v26
	v_fmac_f32_e32 v91, v211, v27
	v_fmac_f32_e32 v92, v212, v28
	v_fmac_f32_e32 v93, v213, v29
	v_fmac_f32_e32 v94, v214, v30
	v_fmac_f32_e32 v95, v215, v31
	s_waitcnt vmcnt(4)
	v_fmac_f32_e32 v96, v200, v32
	v_fmac_f32_e32 v97, v201, v33
	v_fmac_f32_e32 v98, v202, v34
	v_fmac_f32_e32 v99, v203, v35
	v_fmac_f32_e32 v100, v204, v36
	v_fmac_f32_e32 v101, v205, v37
	v_fmac_f32_e32 v102, v206, v38
	v_fmac_f32_e32 v103, v207, v39
	v_fmac_f32_e32 v104, v208, v40
	v_fmac_f32_e32 v105, v209, v41
	v_fmac_f32_e32 v106, v210, v42
	v_fmac_f32_e32 v107, v211, v43
	v_fmac_f32_e32 v108, v212, v44
	v_fmac_f32_e32 v109, v213, v45
	v_fmac_f32_e32 v110, v214, v46
	v_fmac_f32_e32 v111, v215, v47
	s_waitcnt vmcnt(0)
	v_fmac_f32_e32 v112, v200, v48
	v_fmac_f32_e32 v113, v201, v49
	v_fmac_f32_e32 v114, v202, v50
	v_fmac_f32_e32 v115, v203, v51
	v_fmac_f32_e32 v116, v204, v52
	v_fmac_f32_e32 v117, v205, v53
	v_fmac_f32_e32 v118, v206, v54
	v_fmac_f32_e32 v119, v207, v55
	v_fmac_f32_e32 v120, v208, v56
	v_fmac_f32_e32 v121, v209, v57
	v_fmac_f32_e32 v122, v210, v58
	v_fmac_f32_e32 v123, v211, v59
	v_fmac_f32_e32 v124, v212, v60
	v_fmac_f32_e32 v125, v213, v61
	v_fmac_f32_e32 v126, v214, v62
	v_fmac_f32_e32 v127, v215, v63
	global_store_dwordx4 v144, v[64:67], s[40:41] offset:0
	global_store_dwordx4 v144, v[68:71], s[40:41] offset:64
	global_store_dwordx4 v144, v[72:75], s[40:41] offset:128
	global_store_dwordx4 v144, v[76:79], s[40:41] offset:192
	s_add_u32 s40, s40, 0x10000
	s_addc_u32 s41, s41, 0
	global_store_dwordx4 v144, v[80:83], s[40:41] offset:0
	global_store_dwordx4 v144, v[84:87], s[40:41] offset:64
	global_store_dwordx4 v144, v[88:91], s[40:41] offset:128
	global_store_dwordx4 v144, v[92:95], s[40:41] offset:192
	s_add_u32 s40, s40, 0x10000
	s_addc_u32 s41, s41, 0
	global_store_dwordx4 v144, v[96:99], s[40:41] offset:0
	global_store_dwordx4 v144, v[100:103], s[40:41] offset:64
	global_store_dwordx4 v144, v[104:107], s[40:41] offset:128
	global_store_dwordx4 v144, v[108:111], s[40:41] offset:192
	s_add_u32 s40, s40, 0x10000
	s_addc_u32 s41, s41, 0
	global_store_dwordx4 v144, v[112:115], s[40:41] offset:0
	global_store_dwordx4 v144, v[116:119], s[40:41] offset:64
	global_store_dwordx4 v144, v[120:123], s[40:41] offset:128
	global_store_dwordx4 v144, v[124:127], s[40:41] offset:192
	v_mov_b32_e32 v0, 0
	v_mov_b32_e32 v1, 0
	v_mov_b32_e32 v2, 0
	v_mov_b32_e32 v3, 0
	v_mov_b32_e32 v4, 0
	v_mov_b32_e32 v5, 0
	v_mov_b32_e32 v6, 0
	v_mov_b32_e32 v7, 0
	v_mov_b32_e32 v8, 0
	v_mov_b32_e32 v9, 0
	v_mov_b32_e32 v10, 0
	v_mov_b32_e32 v11, 0
	v_mov_b32_e32 v12, 0
	v_mov_b32_e32 v13, 0
	v_mov_b32_e32 v14, 0
	v_mov_b32_e32 v15, 0
	v_mov_b32_e32 v16, 0
	v_mov_b32_e32 v17, 0
	v_mov_b32_e32 v18, 0
	v_mov_b32_e32 v19, 0
	v_mov_b32_e32 v20, 0
	v_mov_b32_e32 v21, 0
	v_mov_b32_e32 v22, 0
	v_mov_b32_e32 v23, 0
	v_mov_b32_e32 v24, 0
	v_mov_b32_e32 v25, 0
	v_mov_b32_e32 v26, 0
	v_mov_b32_e32 v27, 0
	v_mov_b32_e32 v28, 0
	v_mov_b32_e32 v29, 0
	v_mov_b32_e32 v30, 0
	v_mov_b32_e32 v31, 0
	v_mov_b32_e32 v32, 0
	v_mov_b32_e32 v33, 0
	v_mov_b32_e32 v34, 0
	v_mov_b32_e32 v35, 0
	v_mov_b32_e32 v36, 0
	v_mov_b32_e32 v37, 0
	v_mov_b32_e32 v38, 0
	v_mov_b32_e32 v39, 0
	v_mov_b32_e32 v40, 0
	v_mov_b32_e32 v41, 0
	v_mov_b32_e32 v42, 0
	v_mov_b32_e32 v43, 0
	v_mov_b32_e32 v44, 0
	v_mov_b32_e32 v45, 0
	v_mov_b32_e32 v46, 0
	v_mov_b32_e32 v47, 0
	v_mov_b32_e32 v48, 0
	v_mov_b32_e32 v49, 0
	v_mov_b32_e32 v50, 0
	v_mov_b32_e32 v51, 0
	v_mov_b32_e32 v52, 0
	v_mov_b32_e32 v53, 0
	v_mov_b32_e32 v54, 0
	v_mov_b32_e32 v55, 0
	v_mov_b32_e32 v56, 0
	v_mov_b32_e32 v57, 0
	v_mov_b32_e32 v58, 0
	v_mov_b32_e32 v59, 0
	v_mov_b32_e32 v60, 0
	v_mov_b32_e32 v61, 0
	v_mov_b32_e32 v62, 0
	v_mov_b32_e32 v63, 0
	s_add_u32 s32, s32, 1
	s_cmp_lt_u32 s32, 2
	s_cbranch_scc1 .Lmlp2_tile
	s_waitcnt vmcnt(0) lgkmcnt(0)
	s_barrier
	ds_write_b128 v145, v[252:255] offset:40960
	s_waitcnt lgkmcnt(0)
	s_barrier
	s_mov_b64 s[50:51], 0
